# NOPRIO: the 112 per-phase s_setprio flips of the seven GEMM main loops removed (A/B of hipcc's priority toggling); on top of DPP+CONV5
# speedup vs baseline: 1.0058x; 1.0058x over previous
; #define PG8_STAGE(bufoff, gbase, voff) do { _Pragma("unroll") for (int _i = 0; _i < 2; ++_i) \
;         __builtin_amdgcn_global_load_lds((const unsigned*)((const char*)(gbase) + (voff)[_i]), (PG8_LAS unsigned*)(lds + (bufoff) + ldsw + _i * 8192), 16, 0, 0); } while (0)
; #define PG8_LDA(dst, b, h) do { _Pragma("unroll") for (int m = 0; m < 4; ++m) _Pragma("unroll") for (int k = 0; k < 2; ++k) dst[m][k] = *(const PG8_LAS bf16x8*)(lds + PG8_SA(b, h) + aoff + m * 2048 + k * 1024); } while (0)
; #define PG8_LDB(dst, b, h) do { _Pragma("unroll") for (int n = 0; n < 2; ++n) _Pragma("unroll") for (int k = 0; k < 2; ++k) dst[n][k] = *(const PG8_LAS bf16x8*)(lds + PG8_SB(b, h) + boff + n * 2048 + k * 1024); } while (0)
; #define PG8_MMA(ai, bj, At, Bt) do { __builtin_amdgcn_s_setprio(1); _Pragma("unroll") for (int m = 0; m < 4; ++m) _Pragma("unroll") for (int n = 0; n < 2; ++n) _Pragma("unroll") for (int k = 0; k < 2; ++k) \
;         acc[ai][bj][m][n] = __builtin_amdgcn_mfma_f32_16x16x32_bf16(Bt[n][k], At[m][k], acc[ai][bj][m][n], 0, 0, 0); __builtin_amdgcn_s_setprio(0); } while (0)
; #define PG8_WAIT_L(n) asm volatile("s_waitcnt lgkmcnt(" #n ")" ::: "memory")
; #define PG8_BAR __builtin_amdgcn_s_barrier()
; #define PG8_SCHED __builtin_amdgcn_sched_barrier(0)
; template <class Epi, class Sched>
; __device__ __forceinline__ void gemm_phase(PG8_LAS unsigned char* lds, const Gemm g, const Sched& S, const Epi& E, int tid_in) {
;     ...
;             PG8_LDB(B0, 0, 0); PG8_SCHED; PG8_LDA(At, 0, 0); PG8_STAGE(PG8_SA(1, 1), a1 + hstep, voffA);
;             PG8_WAIT_L(8); PG8_BAR; PG8_WAIT_L(0); PG8_MMA(0, 0, At, B0); PG8_BAR; PG8_SCHED;
;             PG8_LDB(B1, 0, 1); PG8_STAGE(PG8_SB(0, 0), b2, voffB);
;             PG8_BAR; PG8_WAIT_L(0); PG8_MMA(0, 1, At, B1); PG8_BAR;
;             PG8_LDA(At, 0, 1); PG8_STAGE(PG8_SA(0, 0), a2, voffA);
;             PG8_BAR; PG8_WAIT_L(0); PG8_MMA(1, 0, At, B0); PG8_BAR; PG8_SCHED;
.LBB0_266:
	s_add_u32 s28, s4, 0x100
	s_addc_u32 s29, s5, 0
	s_add_i32 s58, 0, 0x10000
	v_add_u32_e32 v136, s58, v151
	ds_read_b128 v[128:131], v136
	ds_read_b128 v[132:135], v136 offset:1024
	ds_read_b128 v[144:147], v136 offset:2048
	ds_read_b128 v[154:157], v136 offset:3072
	s_cmp_eq_u32 s56, 60
	s_cselect_b32 s79, s15, s29
	s_cselect_b32 s78, s52, s28
	s_cselect_b32 s31, s13, s55
	s_cselect_b32 s30, s53, s54
	v_lshl_add_u64 v[136:137], s[4:5], 0, v[140:141]
	s_add_i32 m0, s27, 0xc000
	ds_read_b128 v[158:161], v153
	ds_read_b128 v[162:165], v153 offset:1024
	ds_read_b128 v[166:169], v153 offset:2048
	ds_read_b128 v[170:173], v153 offset:3072
	ds_read_b128 v[174:177], v153 offset:4096
	ds_read_b128 v[178:181], v153 offset:5120
	ds_read_b128 v[182:185], v153 offset:6144
	ds_read_b128 v[186:189], v153 offset:7168
	global_load_lds_dwordx4 v[136:137], off
	v_lshl_add_u64 v[136:137], s[4:5], 0, v[142:143]
	s_add_i32 m0, s27, 0xe000
	s_nop 0
	global_load_lds_dwordx4 v[136:137], off
	s_waitcnt lgkmcnt(8)
	s_barrier
	s_waitcnt lgkmcnt(0)
	s_waitcnt lgkmcnt(0)
	v_mfma_f32_16x16x32_bf16 v[124:127], v[128:131], v[158:161], v[124:127]
	v_mfma_f32_16x16x32_bf16 v[96:99], v[144:147], v[158:161], v[96:99]
	v_mfma_f32_16x16x32_bf16 v[120:123], v[128:131], v[166:169], v[120:123]
	v_mfma_f32_16x16x32_bf16 v[88:91], v[144:147], v[166:169], v[88:91]
	v_mfma_f32_16x16x32_bf16 v[116:119], v[128:131], v[174:177], v[116:119]
	v_mfma_f32_16x16x32_bf16 v[84:87], v[144:147], v[174:177], v[84:87]
	v_mfma_f32_16x16x32_bf16 v[112:115], v[128:131], v[182:185], v[112:115]
	v_mfma_f32_16x16x32_bf16 v[80:83], v[144:147], v[182:185], v[80:83]
	v_mfma_f32_16x16x32_bf16 v[124:127], v[132:135], v[162:165], v[124:127]
	v_mfma_f32_16x16x32_bf16 v[96:99], v[154:157], v[162:165], v[96:99]
	v_mfma_f32_16x16x32_bf16 v[120:123], v[132:135], v[170:173], v[120:123]
	v_mfma_f32_16x16x32_bf16 v[88:91], v[154:157], v[170:173], v[88:91]
	v_mfma_f32_16x16x32_bf16 v[116:119], v[132:135], v[178:181], v[116:119]
	v_mfma_f32_16x16x32_bf16 v[84:87], v[154:157], v[178:181], v[84:87]
	v_mfma_f32_16x16x32_bf16 v[112:115], v[132:135], v[186:189], v[112:115]
	v_mfma_f32_16x16x32_bf16 v[80:83], v[154:157], v[186:189], v[80:83]
	s_barrier
	s_add_i32 s59, 0, 0x14000
	v_add_u32_e32 v136, s59, v151
	s_add_i32 s4, s58, s33
	ds_read_b128 v[194:197], v136
	ds_read_b128 v[200:203], v136 offset:1024
	ds_read_b128 v[204:207], v136 offset:2048
	ds_read_b128 v[208:211], v136 offset:3072
	v_lshl_add_u64 v[136:137], s[30:31], 0, v[192:193]
	s_mov_b32 m0, s4
	v_lshl_add_u64 v[148:149], s[30:31], 0, v[138:139]
	global_load_lds_dwordx4 v[136:137], off
	s_add_i32 m0, s4, 0x2000
	s_nop 0
	global_load_lds_dwordx4 v[148:149], off
	s_barrier
	s_waitcnt lgkmcnt(0)
	s_waitcnt lgkmcnt(0)
	v_mfma_f32_16x16x32_bf16 v[64:67], v[194:197], v[158:161], v[64:67]
	v_mfma_f32_16x16x32_bf16 v[36:39], v[204:207], v[158:161], v[36:39]
	v_mfma_f32_16x16x32_bf16 v[56:59], v[194:197], v[166:169], v[56:59]
	v_mfma_f32_16x16x32_bf16 v[28:31], v[204:207], v[166:169], v[28:31]
	v_mfma_f32_16x16x32_bf16 v[52:55], v[194:197], v[174:177], v[52:55]
	v_mfma_f32_16x16x32_bf16 v[20:23], v[204:207], v[174:177], v[20:23]
	v_mfma_f32_16x16x32_bf16 v[48:51], v[194:197], v[182:185], v[48:51]
	v_mfma_f32_16x16x32_bf16 v[16:19], v[204:207], v[182:185], v[16:19]
	v_mfma_f32_16x16x32_bf16 v[64:67], v[200:203], v[162:165], v[64:67]
	v_mfma_f32_16x16x32_bf16 v[36:39], v[208:211], v[162:165], v[36:39]
	v_mfma_f32_16x16x32_bf16 v[56:59], v[200:203], v[170:173], v[56:59]
	v_mfma_f32_16x16x32_bf16 v[28:31], v[208:211], v[170:173], v[28:31]
	v_mfma_f32_16x16x32_bf16 v[52:55], v[200:203], v[178:181], v[52:55]
	v_mfma_f32_16x16x32_bf16 v[20:23], v[208:211], v[178:181], v[20:23]
	v_mfma_f32_16x16x32_bf16 v[48:51], v[200:203], v[186:189], v[48:51]
	v_mfma_f32_16x16x32_bf16 v[16:19], v[208:211], v[186:189], v[16:19]
	s_mov_b32 m0, s27
	v_lshl_add_u64 v[190:191], s[78:79], 0, v[192:193]
	s_barrier
	ds_read_b128 v[158:161], v153 offset:16384
	ds_read_b128 v[162:165], v153 offset:17408
	ds_read_b128 v[166:169], v153 offset:18432
	ds_read_b128 v[170:173], v153 offset:19456
	ds_read_b128 v[174:177], v153 offset:20480
	ds_read_b128 v[178:181], v153 offset:21504
	ds_read_b128 v[182:185], v153 offset:22528
	ds_read_b128 v[186:189], v153 offset:23552
	global_load_lds_dwordx4 v[190:191], off
	v_lshl_add_u64 v[212:213], s[78:79], 0, v[138:139]
	s_mov_b32 m0, s42
	s_nop 0
	global_load_lds_dwordx4 v[212:213], off
	s_barrier
	s_waitcnt lgkmcnt(0)
	s_waitcnt lgkmcnt(0)
	v_mfma_f32_16x16x32_bf16 v[108:111], v[128:131], v[158:161], v[108:111]
	v_mfma_f32_16x16x32_bf16 v[76:79], v[144:147], v[158:161], v[76:79]
	v_mfma_f32_16x16x32_bf16 v[104:107], v[128:131], v[166:169], v[104:107]
	v_mfma_f32_16x16x32_bf16 v[72:75], v[144:147], v[166:169], v[72:75]
	v_mfma_f32_16x16x32_bf16 v[100:103], v[128:131], v[174:177], v[100:103]
	v_mfma_f32_16x16x32_bf16 v[68:71], v[144:147], v[174:177], v[68:71]
	v_mfma_f32_16x16x32_bf16 v[92:95], v[128:131], v[182:185], v[92:95]
	v_mfma_f32_16x16x32_bf16 v[60:63], v[144:147], v[182:185], v[60:63]
	v_mfma_f32_16x16x32_bf16 v[108:111], v[132:135], v[162:165], v[108:111]
	v_mfma_f32_16x16x32_bf16 v[76:79], v[154:157], v[162:165], v[76:79]
	v_mfma_f32_16x16x32_bf16 v[104:107], v[132:135], v[170:173], v[104:107]
	v_mfma_f32_16x16x32_bf16 v[72:75], v[154:157], v[170:173], v[72:75]
	v_mfma_f32_16x16x32_bf16 v[100:103], v[132:135], v[178:181], v[100:103]
	v_mfma_f32_16x16x32_bf16 v[68:71], v[154:157], v[178:181], v[68:71]
	v_mfma_f32_16x16x32_bf16 v[92:95], v[132:135], v[186:189], v[92:95]
	v_mfma_f32_16x16x32_bf16 v[60:63], v[154:157], v[186:189], v[60:63]
	s_barrier
; #define PG8_STAGE(bufoff, gbase, voff) do { _Pragma("unroll") for (int _i = 0; _i < 2; ++_i) \
;         __builtin_amdgcn_global_load_lds((const unsigned*)((const char*)(gbase) + (voff)[_i]), (PG8_LAS unsigned*)(lds + (bufoff) + ldsw + _i * 8192), 16, 0, 0); } while (0)
; #define PG8_LDA(dst, b, h) do { _Pragma("unroll") for (int m = 0; m < 4; ++m) _Pragma("unroll") for (int k = 0; k < 2; ++k) dst[m][k] = *(const PG8_LAS bf16x8*)(lds + PG8_SA(b, h) + aoff + m * 2048 + k * 1024); } while (0)
; #define PG8_LDB(dst, b, h) do { _Pragma("unroll") for (int n = 0; n < 2; ++n) _Pragma("unroll") for (int k = 0; k < 2; ++k) dst[n][k] = *(const PG8_LAS bf16x8*)(lds + PG8_SB(b, h) + boff + n * 2048 + k * 1024); } while (0)
; #define PG8_MMA(ai, bj, At, Bt) do { __builtin_amdgcn_s_setprio(1); _Pragma("unroll") for (int m = 0; m < 4; ++m) _Pragma("unroll") for (int n = 0; n < 2; ++n) _Pragma("unroll") for (int k = 0; k < 2; ++k) \
;         acc[ai][bj][m][n] = __builtin_amdgcn_mfma_f32_16x16x32_bf16(Bt[n][k], At[m][k], acc[ai][bj][m][n], 0, 0, 0); __builtin_amdgcn_s_setprio(0); } while (0)
; #define PG8_WAIT_V(n) asm volatile("s_waitcnt vmcnt(" #n ")" ::: "memory")
; #define PG8_WAIT_L(n) asm volatile("s_waitcnt lgkmcnt(" #n ")" ::: "memory")
; #define PG8_BAR __builtin_amdgcn_s_barrier()
; #define PG8_SCHED __builtin_amdgcn_sched_barrier(0)
; template <class Epi, class Sched>
; __device__ __forceinline__ void gemm_phase(PG8_LAS unsigned char* lds, const Gemm g, const Sched& S, const Epi& E, int tid_in) {
;     ...
;             PG8_STAGE(PG8_SB(0, 1), b2 + hstep, voffB);
;             PG8_WAIT_V(6); PG8_BAR; PG8_MMA(1, 1, At, B1); PG8_BAR;
;             PG8_LDB(B0, 1, 0); PG8_SCHED; PG8_LDA(At, 1, 0); PG8_STAGE(PG8_SA(0, 1), a2 + hstep, voffA);
;             PG8_WAIT_L(8); PG8_BAR; PG8_WAIT_L(0); PG8_MMA(0, 0, At, B0); PG8_BAR; PG8_SCHED;
;             PG8_LDB(B1, 1, 1); PG8_STAGE(PG8_SB(1, 0), b3, voffB);
;             PG8_BAR; PG8_WAIT_L(0); PG8_MMA(0, 1, At, B1); PG8_BAR;
	s_add_u32 s4, s30, 0x100000
	s_addc_u32 s5, s31, 0
	s_add_i32 s58, s59, s33
	v_lshl_add_u64 v[128:129], s[4:5], 0, v[192:193]
	s_mov_b32 m0, s58
	s_nop 0
	global_load_lds_dwordx4 v[128:129], off
	v_lshl_add_u64 v[128:129], s[4:5], 0, v[138:139]
	s_add_i32 m0, s58, 0x2000
	s_nop 0
	global_load_lds_dwordx4 v[128:129], off
	s_waitcnt vmcnt(6)
	s_barrier
	v_mfma_f32_16x16x32_bf16 v[44:47], v[194:197], v[158:161], v[44:47]
	v_mfma_f32_16x16x32_bf16 v[12:15], v[204:207], v[158:161], v[12:15]
	v_mfma_f32_16x16x32_bf16 v[40:43], v[194:197], v[166:169], v[40:43]
	v_mfma_f32_16x16x32_bf16 v[8:11], v[204:207], v[166:169], v[8:11]
	v_mfma_f32_16x16x32_bf16 v[32:35], v[194:197], v[174:177], v[32:35]
	v_mfma_f32_16x16x32_bf16 v[4:7], v[204:207], v[174:177], v[4:7]
	v_mfma_f32_16x16x32_bf16 v[24:27], v[194:197], v[182:185], v[24:27]
	v_mfma_f32_16x16x32_bf16 v[0:3], v[204:207], v[182:185], v[0:3]
	v_mfma_f32_16x16x32_bf16 v[44:47], v[200:203], v[162:165], v[44:47]
	v_mfma_f32_16x16x32_bf16 v[12:15], v[208:211], v[162:165], v[12:15]
	v_mfma_f32_16x16x32_bf16 v[40:43], v[200:203], v[170:173], v[40:43]
	v_mfma_f32_16x16x32_bf16 v[8:11], v[208:211], v[170:173], v[8:11]
	v_mfma_f32_16x16x32_bf16 v[32:35], v[200:203], v[178:181], v[32:35]
	v_mfma_f32_16x16x32_bf16 v[4:7], v[208:211], v[178:181], v[4:7]
	v_mfma_f32_16x16x32_bf16 v[24:27], v[200:203], v[186:189], v[24:27]
	v_mfma_f32_16x16x32_bf16 v[0:3], v[208:211], v[186:189], v[0:3]
	s_add_i32 s58, 0, 0x18000
	v_add_u32_e32 v154, s58, v151
	s_barrier
	ds_read_b128 v[128:131], v154
	ds_read_b128 v[132:135], v154 offset:1024
	ds_read_b128 v[144:147], v154 offset:2048
	ds_read_b128 v[154:157], v154 offset:3072
	s_add_u32 s4, s78, 0x100000
	s_addc_u32 s5, s79, 0
	s_mov_b32 m0, s43
	v_lshl_add_u64 v[194:195], s[4:5], 0, v[192:193]
	ds_read_b128 v[158:161], v153 offset:32768
	ds_read_b128 v[162:165], v153 offset:33792
	ds_read_b128 v[166:169], v153 offset:34816
	ds_read_b128 v[170:173], v153 offset:35840
	ds_read_b128 v[174:177], v153 offset:36864
	ds_read_b128 v[178:181], v153 offset:37888
	ds_read_b128 v[182:185], v153 offset:38912
	ds_read_b128 v[186:189], v153 offset:39936
	global_load_lds_dwordx4 v[194:195], off
	v_lshl_add_u64 v[194:195], s[4:5], 0, v[138:139]
	s_mov_b32 m0, s44
	s_nop 0
	global_load_lds_dwordx4 v[194:195], off
	s_waitcnt lgkmcnt(8)
	s_barrier
	s_waitcnt lgkmcnt(0)
	s_waitcnt lgkmcnt(0)
	v_mfma_f32_16x16x32_bf16 v[124:127], v[128:131], v[158:161], v[124:127]
	v_mfma_f32_16x16x32_bf16 v[96:99], v[144:147], v[158:161], v[96:99]
	v_mfma_f32_16x16x32_bf16 v[120:123], v[128:131], v[166:169], v[120:123]
	v_mfma_f32_16x16x32_bf16 v[88:91], v[144:147], v[166:169], v[88:91]
	v_mfma_f32_16x16x32_bf16 v[116:119], v[128:131], v[174:177], v[116:119]
	v_mfma_f32_16x16x32_bf16 v[84:87], v[144:147], v[174:177], v[84:87]
	v_mfma_f32_16x16x32_bf16 v[112:115], v[128:131], v[182:185], v[112:115]
	v_mfma_f32_16x16x32_bf16 v[80:83], v[144:147], v[182:185], v[80:83]
	v_mfma_f32_16x16x32_bf16 v[124:127], v[132:135], v[162:165], v[124:127]
	v_mfma_f32_16x16x32_bf16 v[96:99], v[154:157], v[162:165], v[96:99]
	v_mfma_f32_16x16x32_bf16 v[120:123], v[132:135], v[170:173], v[120:123]
	v_mfma_f32_16x16x32_bf16 v[88:91], v[154:157], v[170:173], v[88:91]
	v_mfma_f32_16x16x32_bf16 v[116:119], v[132:135], v[178:181], v[116:119]
	v_mfma_f32_16x16x32_bf16 v[84:87], v[154:157], v[178:181], v[84:87]
	v_mfma_f32_16x16x32_bf16 v[112:115], v[132:135], v[186:189], v[112:115]
	v_mfma_f32_16x16x32_bf16 v[80:83], v[154:157], v[186:189], v[80:83]
	s_barrier
	s_add_i32 s59, 0, 0x1c000
	s_add_i32 s4, s58, s33
	v_add_u32_e32 v199, s59, v151
	v_lshl_add_u64 v[136:137], v[136:137], 0, s[74:75]
	s_mov_b32 m0, s4
	ds_read_b128 v[194:197], v199
	ds_read_b128 v[200:203], v199 offset:1024
	ds_read_b128 v[204:207], v199 offset:2048
	ds_read_b128 v[208:211], v199 offset:3072
	global_load_lds_dwordx4 v[136:137], off
	v_lshl_add_u64 v[136:137], v[148:149], 0, s[74:75]
	s_add_i32 m0, s4, 0x2000
	s_nop 0
	global_load_lds_dwordx4 v[136:137], off
	s_barrier
	s_waitcnt lgkmcnt(0)
	s_waitcnt lgkmcnt(0)
	v_mfma_f32_16x16x32_bf16 v[64:67], v[194:197], v[158:161], v[64:67]
	v_mfma_f32_16x16x32_bf16 v[36:39], v[204:207], v[158:161], v[36:39]
	v_mfma_f32_16x16x32_bf16 v[56:59], v[194:197], v[166:169], v[56:59]
	v_mfma_f32_16x16x32_bf16 v[28:31], v[204:207], v[166:169], v[28:31]
	v_mfma_f32_16x16x32_bf16 v[52:55], v[194:197], v[174:177], v[52:55]
	v_mfma_f32_16x16x32_bf16 v[20:23], v[204:207], v[174:177], v[20:23]
	v_mfma_f32_16x16x32_bf16 v[48:51], v[194:197], v[182:185], v[48:51]
	v_mfma_f32_16x16x32_bf16 v[16:19], v[204:207], v[182:185], v[16:19]
	v_mfma_f32_16x16x32_bf16 v[64:67], v[200:203], v[162:165], v[64:67]
	v_mfma_f32_16x16x32_bf16 v[36:39], v[208:211], v[162:165], v[36:39]
	v_mfma_f32_16x16x32_bf16 v[56:59], v[200:203], v[170:173], v[56:59]
	v_mfma_f32_16x16x32_bf16 v[28:31], v[208:211], v[170:173], v[28:31]
	v_mfma_f32_16x16x32_bf16 v[52:55], v[200:203], v[178:181], v[52:55]
	v_mfma_f32_16x16x32_bf16 v[20:23], v[208:211], v[178:181], v[20:23]
	v_mfma_f32_16x16x32_bf16 v[48:51], v[200:203], v[186:189], v[48:51]
	v_mfma_f32_16x16x32_bf16 v[16:19], v[208:211], v[186:189], v[16:19]
	s_mov_b32 m0, s48
	v_lshl_add_u64 v[136:137], v[190:191], 0, s[74:75]
	s_barrier
; #define PG8_STAGE(bufoff, gbase, voff) do { _Pragma("unroll") for (int _i = 0; _i < 2; ++_i) \
;         __builtin_amdgcn_global_load_lds((const unsigned*)((const char*)(gbase) + (voff)[_i]), (PG8_LAS unsigned*)(lds + (bufoff) + ldsw + _i * 8192), 16, 0, 0); } while (0)
; #define PG8_LDA(dst, b, h) do { _Pragma("unroll") for (int m = 0; m < 4; ++m) _Pragma("unroll") for (int k = 0; k < 2; ++k) dst[m][k] = *(const PG8_LAS bf16x8*)(lds + PG8_SA(b, h) + aoff + m * 2048 + k * 1024); } while (0)
; #define PG8_MMA(ai, bj, At, Bt) do { __builtin_amdgcn_s_setprio(1); _Pragma("unroll") for (int m = 0; m < 4; ++m) _Pragma("unroll") for (int n = 0; n < 2; ++n) _Pragma("unroll") for (int k = 0; k < 2; ++k) \
;         acc[ai][bj][m][n] = __builtin_amdgcn_mfma_f32_16x16x32_bf16(Bt[n][k], At[m][k], acc[ai][bj][m][n], 0, 0, 0); __builtin_amdgcn_s_setprio(0); } while (0)
; #define PG8_WAIT_V(n) asm volatile("s_waitcnt vmcnt(" #n ")" ::: "memory")
; #define PG8_WAIT_L(n) asm volatile("s_waitcnt lgkmcnt(" #n ")" ::: "memory")
; #define PG8_BAR __builtin_amdgcn_s_barrier()
; #define PG8_SCHED __builtin_amdgcn_sched_barrier(0)
; template <class Epi, class Sched>
; __device__ __forceinline__ void gemm_phase(PG8_LAS unsigned char* lds, const Gemm g, const Sched& S, const Epi& E, int tid_in) {
;     ...
;             PG8_LDA(At, 1, 1); PG8_STAGE(PG8_SA(1, 0), a3, voffA);
;             PG8_BAR; PG8_WAIT_L(0); PG8_MMA(1, 0, At, B0); PG8_BAR; PG8_SCHED;
;             PG8_STAGE(PG8_SB(1, 1), b3 + hstep, voffB);
;             PG8_WAIT_V(6); PG8_BAR; PG8_MMA(1, 1, At, B1); PG8_BAR;
;         }
;     __device__ __forceinline__ void operator()(f32x4 (&acc)[2][2][4][2], const Unit& u, int wr, int wc, int fr, int fq) const {
;         const int row0 = u.pm * 256 + wr * 64 + fr, col0 = u.pn * 256 + wc * 32 + 4 * fq;
;         const float* gr = gate + (size_t)(bbase + (u.pm * 256) / SEQ) * MODW;
; #pragma unroll
;         for (int bj = 0; bj < 2; ++bj)
; #pragma unroll
;             for (int n = 0; n < 2; ++n) { const int col = col0 + bj * 128 + n * 16; const f32x4 gv = *(const f32x4*)(gr + col);
;                 f32x4 bv = (f32x4){0.f, 0.f, 0.f, 0.f}; if (bias) bv = *(const f32x4*)(bias + col);
	ds_read_b128 v[158:161], v153 offset:49152
	ds_read_b128 v[162:165], v153 offset:50176
	ds_read_b128 v[166:169], v153 offset:51200
	ds_read_b128 v[170:173], v153 offset:52224
	ds_read_b128 v[174:177], v153 offset:53248
	ds_read_b128 v[178:181], v153 offset:54272
	ds_read_b128 v[182:185], v153 offset:55296
	ds_read_b128 v[186:189], v153 offset:56320
	global_load_lds_dwordx4 v[136:137], off
	v_lshl_add_u64 v[136:137], v[212:213], 0, s[74:75]
	s_mov_b32 m0, s49
	s_nop 0
	global_load_lds_dwordx4 v[136:137], off
	s_barrier
	s_waitcnt lgkmcnt(0)
	s_waitcnt lgkmcnt(0)
	v_mfma_f32_16x16x32_bf16 v[108:111], v[128:131], v[158:161], v[108:111]
	v_mfma_f32_16x16x32_bf16 v[76:79], v[144:147], v[158:161], v[76:79]
	v_mfma_f32_16x16x32_bf16 v[104:107], v[128:131], v[166:169], v[104:107]
	v_mfma_f32_16x16x32_bf16 v[72:75], v[144:147], v[166:169], v[72:75]
	v_mfma_f32_16x16x32_bf16 v[100:103], v[128:131], v[174:177], v[100:103]
	v_mfma_f32_16x16x32_bf16 v[68:71], v[144:147], v[174:177], v[68:71]
	v_mfma_f32_16x16x32_bf16 v[92:95], v[128:131], v[182:185], v[92:95]
	v_mfma_f32_16x16x32_bf16 v[60:63], v[144:147], v[182:185], v[60:63]
	v_mfma_f32_16x16x32_bf16 v[108:111], v[132:135], v[162:165], v[108:111]
	v_mfma_f32_16x16x32_bf16 v[76:79], v[154:157], v[162:165], v[76:79]
	v_mfma_f32_16x16x32_bf16 v[104:107], v[132:135], v[170:173], v[104:107]
	v_mfma_f32_16x16x32_bf16 v[72:75], v[154:157], v[170:173], v[72:75]
	v_mfma_f32_16x16x32_bf16 v[100:103], v[132:135], v[178:181], v[100:103]
	v_mfma_f32_16x16x32_bf16 v[68:71], v[154:157], v[178:181], v[68:71]
	v_mfma_f32_16x16x32_bf16 v[92:95], v[132:135], v[186:189], v[92:95]
	v_mfma_f32_16x16x32_bf16 v[60:63], v[154:157], v[186:189], v[60:63]
	s_barrier
	s_add_u32 s4, s30, 0x100080
	s_addc_u32 s5, s31, 0
	s_add_i32 s30, s59, s33
	v_lshl_add_u64 v[128:129], s[4:5], 0, v[192:193]
	s_mov_b32 m0, s30
	s_nop 0
	global_load_lds_dwordx4 v[128:129], off
	v_lshl_add_u64 v[128:129], s[4:5], 0, v[138:139]
	s_add_i32 m0, s30, 0x2000
	s_nop 0
	global_load_lds_dwordx4 v[128:129], off
	s_waitcnt vmcnt(6)
	s_barrier
	v_mfma_f32_16x16x32_bf16 v[44:47], v[194:197], v[158:161], v[44:47]
	v_mfma_f32_16x16x32_bf16 v[12:15], v[204:207], v[158:161], v[12:15]
	v_mfma_f32_16x16x32_bf16 v[40:43], v[194:197], v[166:169], v[40:43]
	v_mfma_f32_16x16x32_bf16 v[8:11], v[204:207], v[166:169], v[8:11]
	v_mfma_f32_16x16x32_bf16 v[32:35], v[194:197], v[174:177], v[32:35]
	v_mfma_f32_16x16x32_bf16 v[4:7], v[204:207], v[174:177], v[4:7]
	v_mfma_f32_16x16x32_bf16 v[24:27], v[194:197], v[182:185], v[24:27]
	v_mfma_f32_16x16x32_bf16 v[0:3], v[204:207], v[182:185], v[0:3]
	v_mfma_f32_16x16x32_bf16 v[44:47], v[200:203], v[162:165], v[44:47]
	v_mfma_f32_16x16x32_bf16 v[12:15], v[208:211], v[162:165], v[12:15]
	v_mfma_f32_16x16x32_bf16 v[40:43], v[200:203], v[170:173], v[40:43]
	v_mfma_f32_16x16x32_bf16 v[8:11], v[208:211], v[170:173], v[8:11]
	v_mfma_f32_16x16x32_bf16 v[32:35], v[200:203], v[178:181], v[32:35]
	v_mfma_f32_16x16x32_bf16 v[4:7], v[208:211], v[178:181], v[4:7]
	v_mfma_f32_16x16x32_bf16 v[24:27], v[200:203], v[186:189], v[24:27]
	v_mfma_f32_16x16x32_bf16 v[0:3], v[208:211], v[186:189], v[0:3]
	s_add_i32 s56, s56, 2
	s_add_u32 s54, s54, 0x100
	s_addc_u32 s55, s55, 0
	s_cmp_gt_u32 s56, 61
	s_mov_b64 s[4:5], s[28:29]
	s_barrier
	s_cbranch_scc0 .LBB0_266
	s_ashr_i32 s4, s26, 31
	s_lshr_b32 s4, s4, 29
	s_add_i32 s4, s26, s4
	s_ashr_i32 s4, s4, 3
	s_add_i32 s4, s4, s76
	s_mul_hi_i32 s5, s4, 0x6000
	s_mulk_i32 s4, 0x6000
	v_lshl_or_b32 v148, s51, 8, v152
	s_add_u32 s4, s45, s4
	s_addc_u32 s5, s46, s5
	v_ashrrev_i32_e32 v149, 31, v148
	v_lshl_add_u64 v[146:147], v[148:149], 2, s[4:5]
	global_load_dwordx4 v[130:133], v[146:147], off
	global_load_dwordx4 v[158:161], v[146:147], off offset:64
	global_load_dwordx4 v[162:165], v[146:147], off offset:512
	global_load_dwordx4 v[166:169], v[146:147], off offset:576
	v_cndmask_b32_e64 v129, 0, 1, s[10:11]
	v_mov_b32_e32 v128, 0
	v_cmp_ne_u32_e64 s[4:5], 1, v129
	s_andn2_b64 vcc, exec, s[10:11]
	v_lshl_add_u64 v[144:145], v[148:149], 2, s[8:9]
	v_mov_b32_e32 v134, 0
	v_mov_b32_e32 v135, 0
	v_mov_b32_e32 v136, 0
	v_mov_b32_e32 v137, 0
	s_cbranch_vccnz .LBB0_269
	global_load_dwordx4 v[134:137], v[144:145], off
	global_load_dwordx4 v[170:173], v[144:145], off offset:64
	global_load_dwordx4 v[174:177], v[144:145], off offset:512
	global_load_dwordx4 v[178:181], v[144:145], off offset:576

; #define PG8_STAGE(bufoff, gbase, voff) do { _Pragma("unroll") for (int _i = 0; _i < 2; ++_i) \
;         __builtin_amdgcn_global_load_lds((const unsigned*)((const char*)(gbase) + (voff)[_i]), (PG8_LAS unsigned*)(lds + (bufoff) + ldsw + _i * 8192), 16, 0, 0); } while (0)
; #define PG8_LDA(dst, b, h) do { _Pragma("unroll") for (int m = 0; m < 4; ++m) _Pragma("unroll") for (int k = 0; k < 2; ++k) dst[m][k] = *(const PG8_LAS bf16x8*)(lds + PG8_SA(b, h) + aoff + m * 2048 + k * 1024); } while (0)
; #define PG8_LDB(dst, b, h) do { _Pragma("unroll") for (int n = 0; n < 2; ++n) _Pragma("unroll") for (int k = 0; k < 2; ++k) dst[n][k] = *(const PG8_LAS bf16x8*)(lds + PG8_SB(b, h) + boff + n * 2048 + k * 1024); } while (0)
; #define PG8_MMA(ai, bj, At, Bt) do { __builtin_amdgcn_s_setprio(1); _Pragma("unroll") for (int m = 0; m < 4; ++m) _Pragma("unroll") for (int n = 0; n < 2; ++n) _Pragma("unroll") for (int k = 0; k < 2; ++k) \
;         acc[ai][bj][m][n] = __builtin_amdgcn_mfma_f32_16x16x32_bf16(Bt[n][k], At[m][k], acc[ai][bj][m][n], 0, 0, 0); __builtin_amdgcn_s_setprio(0); } while (0)
; #define PG8_WAIT_L(n) asm volatile("s_waitcnt lgkmcnt(" #n ")" ::: "memory")
; #define PG8_BAR __builtin_amdgcn_s_barrier()
; #define PG8_SCHED __builtin_amdgcn_sched_barrier(0)
; template <class Epi, class Sched>
; __device__ __forceinline__ void gemm_phase(PG8_LAS unsigned char* lds, const Gemm g, const Sched& S, const Epi& E, int tid_in) {
;     ...
;             PG8_LDB(B0, 0, 0); PG8_SCHED; PG8_LDA(At, 0, 0); PG8_STAGE(PG8_SA(1, 1), a1 + hstep, voffA);
;             PG8_WAIT_L(8); PG8_BAR; PG8_WAIT_L(0); PG8_MMA(0, 0, At, B0); PG8_BAR; PG8_SCHED;
;             PG8_LDB(B1, 0, 1); PG8_STAGE(PG8_SB(0, 0), b2, voffB);
;             PG8_BAR; PG8_WAIT_L(0); PG8_MMA(0, 1, At, B1); PG8_BAR;
;             PG8_LDA(At, 0, 1); PG8_STAGE(PG8_SA(0, 0), a2, voffA);
;             PG8_BAR; PG8_WAIT_L(0); PG8_MMA(1, 0, At, B0); PG8_BAR; PG8_SCHED;
.LBB0_295:
	s_add_u32 s24, s22, 0xfffc0080
	s_addc_u32 s25, s23, -1
	s_add_i32 s51, 0, 0x10000
	v_add_u32_e32 v154, s51, v151
	ds_read_b128 v[120:123], v154
	ds_read_b128 v[124:127], v154 offset:1024
	ds_read_b128 v[146:149], v154 offset:2048
	ds_read_b128 v[154:157], v154 offset:3072
	s_cmp_eq_u32 s50, 12
	s_cselect_b32 s27, s9, s25
	s_cselect_b32 s26, s45, s24
	s_cselect_b32 s25, s5, s49
	s_cselect_b32 s24, s46, s48
	v_lshl_add_u64 v[190:191], s[22:23], 0, v[142:143]
	s_add_i32 m0, s15, 0xc000
	ds_read_b128 v[158:161], v153
	ds_read_b128 v[162:165], v153 offset:1024
	ds_read_b128 v[166:169], v153 offset:2048
	ds_read_b128 v[170:173], v153 offset:3072
	ds_read_b128 v[174:177], v153 offset:4096
	ds_read_b128 v[178:181], v153 offset:5120
	ds_read_b128 v[182:185], v153 offset:6144
	ds_read_b128 v[186:189], v153 offset:7168
	global_load_lds_dwordx4 v[190:191], off
	v_lshl_add_u64 v[190:191], s[22:23], 0, v[144:145]
	s_add_i32 m0, s15, 0xe000
	s_nop 0
	global_load_lds_dwordx4 v[190:191], off
	s_waitcnt lgkmcnt(8)
	s_barrier
	s_waitcnt lgkmcnt(0)
	s_waitcnt lgkmcnt(0)
	v_mfma_f32_16x16x32_bf16 v[132:135], v[120:123], v[158:161], v[132:135]
	v_mfma_f32_16x16x32_bf16 v[128:131], v[146:149], v[158:161], v[128:131]
	v_mfma_f32_16x16x32_bf16 v[116:119], v[120:123], v[166:169], v[116:119]
	v_mfma_f32_16x16x32_bf16 v[112:115], v[146:149], v[166:169], v[112:115]
	v_mfma_f32_16x16x32_bf16 v[108:111], v[120:123], v[174:177], v[108:111]
	v_mfma_f32_16x16x32_bf16 v[104:107], v[146:149], v[174:177], v[104:107]
	v_mfma_f32_16x16x32_bf16 v[100:103], v[120:123], v[182:185], v[100:103]
	v_mfma_f32_16x16x32_bf16 v[96:99], v[146:149], v[182:185], v[96:99]
	v_mfma_f32_16x16x32_bf16 v[132:135], v[124:127], v[162:165], v[132:135]
	v_mfma_f32_16x16x32_bf16 v[128:131], v[154:157], v[162:165], v[128:131]
	v_mfma_f32_16x16x32_bf16 v[116:119], v[124:127], v[170:173], v[116:119]
	v_mfma_f32_16x16x32_bf16 v[112:115], v[154:157], v[170:173], v[112:115]
	v_mfma_f32_16x16x32_bf16 v[108:111], v[124:127], v[178:181], v[108:111]
	v_mfma_f32_16x16x32_bf16 v[104:107], v[154:157], v[178:181], v[104:107]
	v_mfma_f32_16x16x32_bf16 v[100:103], v[124:127], v[186:189], v[100:103]
	v_mfma_f32_16x16x32_bf16 v[96:99], v[154:157], v[186:189], v[96:99]
	s_barrier
	s_add_i32 s54, 0, 0x14000
	v_add_u32_e32 v190, s54, v151
	s_add_i32 s51, s51, s38
	ds_read_b128 v[194:197], v190
	ds_read_b128 v[200:203], v190 offset:1024
	ds_read_b128 v[204:207], v190 offset:2048
	ds_read_b128 v[208:211], v190 offset:3072
	v_lshl_add_u64 v[190:191], s[24:25], 0, v[192:193]
	s_mov_b32 m0, s51
	v_lshl_add_u64 v[212:213], s[24:25], 0, v[140:141]
	global_load_lds_dwordx4 v[190:191], off
	s_add_i32 m0, s51, 0x2000
	s_nop 0
	global_load_lds_dwordx4 v[212:213], off
	s_barrier
	s_waitcnt lgkmcnt(0)
	s_waitcnt lgkmcnt(0)
	v_mfma_f32_16x16x32_bf16 v[60:63], v[194:197], v[158:161], v[60:63]
	v_mfma_f32_16x16x32_bf16 v[56:59], v[204:207], v[158:161], v[56:59]
	v_mfma_f32_16x16x32_bf16 v[52:55], v[194:197], v[166:169], v[52:55]
	v_mfma_f32_16x16x32_bf16 v[48:51], v[204:207], v[166:169], v[48:51]
	v_mfma_f32_16x16x32_bf16 v[44:47], v[194:197], v[174:177], v[44:47]
	v_mfma_f32_16x16x32_bf16 v[40:43], v[204:207], v[174:177], v[40:43]
	v_mfma_f32_16x16x32_bf16 v[36:39], v[194:197], v[182:185], v[36:39]
	v_mfma_f32_16x16x32_bf16 v[32:35], v[204:207], v[182:185], v[32:35]
	v_mfma_f32_16x16x32_bf16 v[60:63], v[200:203], v[162:165], v[60:63]
	v_mfma_f32_16x16x32_bf16 v[56:59], v[208:211], v[162:165], v[56:59]
	v_mfma_f32_16x16x32_bf16 v[52:55], v[200:203], v[170:173], v[52:55]
	v_mfma_f32_16x16x32_bf16 v[48:51], v[208:211], v[170:173], v[48:51]
	v_mfma_f32_16x16x32_bf16 v[44:47], v[200:203], v[178:181], v[44:47]
	v_mfma_f32_16x16x32_bf16 v[40:43], v[208:211], v[178:181], v[40:43]
	v_mfma_f32_16x16x32_bf16 v[36:39], v[200:203], v[186:189], v[36:39]
	v_mfma_f32_16x16x32_bf16 v[32:35], v[208:211], v[186:189], v[32:35]
	s_mov_b32 m0, s15
	v_lshl_add_u64 v[214:215], s[26:27], 0, v[136:137]
	s_barrier
	ds_read_b128 v[158:161], v153 offset:16384
	ds_read_b128 v[162:165], v153 offset:17408
	ds_read_b128 v[166:169], v153 offset:18432
	ds_read_b128 v[170:173], v153 offset:19456
	ds_read_b128 v[174:177], v153 offset:20480
	ds_read_b128 v[178:181], v153 offset:21504
	ds_read_b128 v[182:185], v153 offset:22528
	ds_read_b128 v[186:189], v153 offset:23552
	global_load_lds_dwordx4 v[214:215], off
	v_lshl_add_u64 v[216:217], s[26:27], 0, v[138:139]
	s_mov_b32 m0, s39
	s_nop 0
	global_load_lds_dwordx4 v[216:217], off
	s_barrier
	s_waitcnt lgkmcnt(0)
	s_waitcnt lgkmcnt(0)
	v_mfma_f32_16x16x32_bf16 v[92:95], v[120:123], v[158:161], v[92:95]
	v_mfma_f32_16x16x32_bf16 v[88:91], v[146:149], v[158:161], v[88:91]
	v_mfma_f32_16x16x32_bf16 v[84:87], v[120:123], v[166:169], v[84:87]
	v_mfma_f32_16x16x32_bf16 v[80:83], v[146:149], v[166:169], v[80:83]
	v_mfma_f32_16x16x32_bf16 v[76:79], v[120:123], v[174:177], v[76:79]
	v_mfma_f32_16x16x32_bf16 v[72:75], v[146:149], v[174:177], v[72:75]
	v_mfma_f32_16x16x32_bf16 v[68:71], v[120:123], v[182:185], v[68:71]
	v_mfma_f32_16x16x32_bf16 v[64:67], v[146:149], v[182:185], v[64:67]
	v_mfma_f32_16x16x32_bf16 v[92:95], v[124:127], v[162:165], v[92:95]
	v_mfma_f32_16x16x32_bf16 v[88:91], v[154:157], v[162:165], v[88:91]
	v_mfma_f32_16x16x32_bf16 v[84:87], v[124:127], v[170:173], v[84:87]
	v_mfma_f32_16x16x32_bf16 v[80:83], v[154:157], v[170:173], v[80:83]
	v_mfma_f32_16x16x32_bf16 v[76:79], v[124:127], v[178:181], v[76:79]
	v_mfma_f32_16x16x32_bf16 v[72:75], v[154:157], v[178:181], v[72:75]
	v_mfma_f32_16x16x32_bf16 v[68:71], v[124:127], v[186:189], v[68:71]
	v_mfma_f32_16x16x32_bf16 v[64:67], v[154:157], v[186:189], v[64:67]
	s_barrier
; #define PG8_STAGE(bufoff, gbase, voff) do { _Pragma("unroll") for (int _i = 0; _i < 2; ++_i) \
;         __builtin_amdgcn_global_load_lds((const unsigned*)((const char*)(gbase) + (voff)[_i]), (PG8_LAS unsigned*)(lds + (bufoff) + ldsw + _i * 8192), 16, 0, 0); } while (0)
; #define PG8_LDA(dst, b, h) do { _Pragma("unroll") for (int m = 0; m < 4; ++m) _Pragma("unroll") for (int k = 0; k < 2; ++k) dst[m][k] = *(const PG8_LAS bf16x8*)(lds + PG8_SA(b, h) + aoff + m * 2048 + k * 1024); } while (0)
; #define PG8_LDB(dst, b, h) do { _Pragma("unroll") for (int n = 0; n < 2; ++n) _Pragma("unroll") for (int k = 0; k < 2; ++k) dst[n][k] = *(const PG8_LAS bf16x8*)(lds + PG8_SB(b, h) + boff + n * 2048 + k * 1024); } while (0)
; #define PG8_MMA(ai, bj, At, Bt) do { __builtin_amdgcn_s_setprio(1); _Pragma("unroll") for (int m = 0; m < 4; ++m) _Pragma("unroll") for (int n = 0; n < 2; ++n) _Pragma("unroll") for (int k = 0; k < 2; ++k) \
;         acc[ai][bj][m][n] = __builtin_amdgcn_mfma_f32_16x16x32_bf16(Bt[n][k], At[m][k], acc[ai][bj][m][n], 0, 0, 0); __builtin_amdgcn_s_setprio(0); } while (0)
; #define PG8_WAIT_V(n) asm volatile("s_waitcnt vmcnt(" #n ")" ::: "memory")
; #define PG8_WAIT_L(n) asm volatile("s_waitcnt lgkmcnt(" #n ")" ::: "memory")
; #define PG8_BAR __builtin_amdgcn_s_barrier()
; #define PG8_SCHED __builtin_amdgcn_sched_barrier(0)
; template <class Epi, class Sched>
; __device__ __forceinline__ void gemm_phase(PG8_LAS unsigned char* lds, const Gemm g, const Sched& S, const Epi& E, int tid_in) {
;     ...
;             PG8_STAGE(PG8_SB(0, 1), b2 + hstep, voffB);
;             PG8_WAIT_V(6); PG8_BAR; PG8_MMA(1, 1, At, B1); PG8_BAR;
;             PG8_LDB(B0, 1, 0); PG8_SCHED; PG8_LDA(At, 1, 0); PG8_STAGE(PG8_SA(0, 1), a2 + hstep, voffA);
;             PG8_WAIT_L(8); PG8_BAR; PG8_WAIT_L(0); PG8_MMA(0, 0, At, B0); PG8_BAR; PG8_SCHED;
;             PG8_LDB(B1, 1, 1); PG8_STAGE(PG8_SB(1, 0), b3, voffB);
;             PG8_BAR; PG8_WAIT_L(0); PG8_MMA(0, 1, At, B1); PG8_BAR;
;             PG8_LDA(At, 1, 1); PG8_STAGE(PG8_SA(1, 0), a3, voffA);
;             PG8_BAR; PG8_WAIT_L(0); PG8_MMA(1, 0, At, B0); PG8_BAR; PG8_SCHED;
	s_add_u32 s52, s24, 0x40000
	s_addc_u32 s53, s25, 0
	s_add_i32 s51, s54, s38
	v_lshl_add_u64 v[120:121], s[52:53], 0, v[192:193]
	s_mov_b32 m0, s51
	s_nop 0
	global_load_lds_dwordx4 v[120:121], off
	v_lshl_add_u64 v[120:121], s[52:53], 0, v[140:141]
	s_add_i32 m0, s51, 0x2000
	s_nop 0
	global_load_lds_dwordx4 v[120:121], off
	s_waitcnt vmcnt(6)
	s_barrier
	v_mfma_f32_16x16x32_bf16 v[28:31], v[194:197], v[158:161], v[28:31]
	v_mfma_f32_16x16x32_bf16 v[24:27], v[204:207], v[158:161], v[24:27]
	v_mfma_f32_16x16x32_bf16 v[20:23], v[194:197], v[166:169], v[20:23]
	v_mfma_f32_16x16x32_bf16 v[16:19], v[204:207], v[166:169], v[16:19]
	v_mfma_f32_16x16x32_bf16 v[12:15], v[194:197], v[174:177], v[12:15]
	v_mfma_f32_16x16x32_bf16 v[8:11], v[204:207], v[174:177], v[8:11]
	v_mfma_f32_16x16x32_bf16 v[4:7], v[194:197], v[182:185], v[4:7]
	v_mfma_f32_16x16x32_bf16 v[0:3], v[204:207], v[182:185], v[0:3]
	v_mfma_f32_16x16x32_bf16 v[28:31], v[200:203], v[162:165], v[28:31]
	v_mfma_f32_16x16x32_bf16 v[24:27], v[208:211], v[162:165], v[24:27]
	v_mfma_f32_16x16x32_bf16 v[20:23], v[200:203], v[170:173], v[20:23]
	v_mfma_f32_16x16x32_bf16 v[16:19], v[208:211], v[170:173], v[16:19]
	v_mfma_f32_16x16x32_bf16 v[12:15], v[200:203], v[178:181], v[12:15]
	v_mfma_f32_16x16x32_bf16 v[8:11], v[208:211], v[178:181], v[8:11]
	v_mfma_f32_16x16x32_bf16 v[4:7], v[200:203], v[186:189], v[4:7]
	v_mfma_f32_16x16x32_bf16 v[0:3], v[208:211], v[186:189], v[0:3]
	s_add_i32 s51, 0, 0x18000
	v_add_u32_e32 v154, s51, v151
	s_barrier
	ds_read_b128 v[120:123], v154
	ds_read_b128 v[124:127], v154 offset:1024
	ds_read_b128 v[146:149], v154 offset:2048
	ds_read_b128 v[154:157], v154 offset:3072
	s_add_u32 s26, s26, 0x40000
	s_addc_u32 s27, s27, 0
	s_mov_b32 m0, s40
	v_lshl_add_u64 v[194:195], s[26:27], 0, v[136:137]
	ds_read_b128 v[158:161], v153 offset:32768
	ds_read_b128 v[162:165], v153 offset:33792
	ds_read_b128 v[166:169], v153 offset:34816
	ds_read_b128 v[170:173], v153 offset:35840
	ds_read_b128 v[174:177], v153 offset:36864
	ds_read_b128 v[178:181], v153 offset:37888
	ds_read_b128 v[182:185], v153 offset:38912
	ds_read_b128 v[186:189], v153 offset:39936
	global_load_lds_dwordx4 v[194:195], off
	v_lshl_add_u64 v[194:195], s[26:27], 0, v[138:139]
	s_mov_b32 m0, s41
	s_nop 0
	global_load_lds_dwordx4 v[194:195], off
	s_waitcnt lgkmcnt(8)
	s_barrier
	s_waitcnt lgkmcnt(0)
	s_waitcnt lgkmcnt(0)
	v_mfma_f32_16x16x32_bf16 v[132:135], v[120:123], v[158:161], v[132:135]
	v_mfma_f32_16x16x32_bf16 v[128:131], v[146:149], v[158:161], v[128:131]
	v_mfma_f32_16x16x32_bf16 v[116:119], v[120:123], v[166:169], v[116:119]
	v_mfma_f32_16x16x32_bf16 v[112:115], v[146:149], v[166:169], v[112:115]
	v_mfma_f32_16x16x32_bf16 v[108:111], v[120:123], v[174:177], v[108:111]
	v_mfma_f32_16x16x32_bf16 v[104:107], v[146:149], v[174:177], v[104:107]
	v_mfma_f32_16x16x32_bf16 v[100:103], v[120:123], v[182:185], v[100:103]
	v_mfma_f32_16x16x32_bf16 v[96:99], v[146:149], v[182:185], v[96:99]
	v_mfma_f32_16x16x32_bf16 v[132:135], v[124:127], v[162:165], v[132:135]
	v_mfma_f32_16x16x32_bf16 v[128:131], v[154:157], v[162:165], v[128:131]
	v_mfma_f32_16x16x32_bf16 v[116:119], v[124:127], v[170:173], v[116:119]
	v_mfma_f32_16x16x32_bf16 v[112:115], v[154:157], v[170:173], v[112:115]
	v_mfma_f32_16x16x32_bf16 v[108:111], v[124:127], v[178:181], v[108:111]
	v_mfma_f32_16x16x32_bf16 v[104:107], v[154:157], v[178:181], v[104:107]
	v_mfma_f32_16x16x32_bf16 v[100:103], v[124:127], v[186:189], v[100:103]
	v_mfma_f32_16x16x32_bf16 v[96:99], v[154:157], v[186:189], v[96:99]
	s_barrier
	s_add_i32 s26, 0, 0x1c000
	s_add_i32 s27, s51, s38
	v_add_u32_e32 v199, s26, v151
	v_lshl_add_u64 v[190:191], v[190:191], 0, s[74:75]
	s_mov_b32 m0, s27
	ds_read_b128 v[194:197], v199
	ds_read_b128 v[200:203], v199 offset:1024
	ds_read_b128 v[204:207], v199 offset:2048
	ds_read_b128 v[208:211], v199 offset:3072
	global_load_lds_dwordx4 v[190:191], off
	v_lshl_add_u64 v[190:191], v[212:213], 0, s[74:75]
	s_add_i32 m0, s27, 0x2000
	s_nop 0
	global_load_lds_dwordx4 v[190:191], off
	s_barrier
	s_waitcnt lgkmcnt(0)
	s_waitcnt lgkmcnt(0)
	v_mfma_f32_16x16x32_bf16 v[60:63], v[194:197], v[158:161], v[60:63]
	v_mfma_f32_16x16x32_bf16 v[56:59], v[204:207], v[158:161], v[56:59]
	v_mfma_f32_16x16x32_bf16 v[52:55], v[194:197], v[166:169], v[52:55]
	v_mfma_f32_16x16x32_bf16 v[48:51], v[204:207], v[166:169], v[48:51]
	v_mfma_f32_16x16x32_bf16 v[44:47], v[194:197], v[174:177], v[44:47]
	v_mfma_f32_16x16x32_bf16 v[40:43], v[204:207], v[174:177], v[40:43]
	v_mfma_f32_16x16x32_bf16 v[36:39], v[194:197], v[182:185], v[36:39]
	v_mfma_f32_16x16x32_bf16 v[32:35], v[204:207], v[182:185], v[32:35]
	v_mfma_f32_16x16x32_bf16 v[60:63], v[200:203], v[162:165], v[60:63]
	v_mfma_f32_16x16x32_bf16 v[56:59], v[208:211], v[162:165], v[56:59]
	v_mfma_f32_16x16x32_bf16 v[52:55], v[200:203], v[170:173], v[52:55]
	v_mfma_f32_16x16x32_bf16 v[48:51], v[208:211], v[170:173], v[48:51]
	v_mfma_f32_16x16x32_bf16 v[44:47], v[200:203], v[178:181], v[44:47]
	v_mfma_f32_16x16x32_bf16 v[40:43], v[208:211], v[178:181], v[40:43]
	v_mfma_f32_16x16x32_bf16 v[36:39], v[200:203], v[186:189], v[36:39]
	v_mfma_f32_16x16x32_bf16 v[32:35], v[208:211], v[186:189], v[32:35]
	s_mov_b32 m0, s42
	v_lshl_add_u64 v[190:191], v[214:215], 0, s[74:75]
	s_barrier
	ds_read_b128 v[158:161], v153 offset:49152
	ds_read_b128 v[162:165], v153 offset:50176
	ds_read_b128 v[166:169], v153 offset:51200
	ds_read_b128 v[170:173], v153 offset:52224
	ds_read_b128 v[174:177], v153 offset:53248
	ds_read_b128 v[178:181], v153 offset:54272
	ds_read_b128 v[182:185], v153 offset:55296
	ds_read_b128 v[186:189], v153 offset:56320
	global_load_lds_dwordx4 v[190:191], off
	v_lshl_add_u64 v[190:191], v[216:217], 0, s[74:75]
	s_mov_b32 m0, s43
	s_nop 0
	global_load_lds_dwordx4 v[190:191], off
	s_barrier
; __device__ __forceinline__ unsigned cvt_pk_bf16(float lo, float hi) { unsigned r; asm volatile("s_nop 0\n\tv_cvt_pk_bf16_f32 %0, %1, %2\n\ts_nop 1" : "=v"(r) : "v"(lo), "v"(hi)); return r; }
; #define PG8_STAGE(bufoff, gbase, voff) do { _Pragma("unroll") for (int _i = 0; _i < 2; ++_i) \
;         __builtin_amdgcn_global_load_lds((const unsigned*)((const char*)(gbase) + (voff)[_i]), (PG8_LAS unsigned*)(lds + (bufoff) + ldsw + _i * 8192), 16, 0, 0); } while (0)
; #define PG8_MMA(ai, bj, At, Bt) do { __builtin_amdgcn_s_setprio(1); _Pragma("unroll") for (int m = 0; m < 4; ++m) _Pragma("unroll") for (int n = 0; n < 2; ++n) _Pragma("unroll") for (int k = 0; k < 2; ++k) \
;         acc[ai][bj][m][n] = __builtin_amdgcn_mfma_f32_16x16x32_bf16(Bt[n][k], At[m][k], acc[ai][bj][m][n], 0, 0, 0); __builtin_amdgcn_s_setprio(0); } while (0)
; #define PG8_WAIT_V(n) asm volatile("s_waitcnt vmcnt(" #n ")" ::: "memory")
; #define PG8_WAIT_L(n) asm volatile("s_waitcnt lgkmcnt(" #n ")" ::: "memory")
; template <class Epi, class Sched>
; __device__ __forceinline__ void gemm_phase(PG8_LAS unsigned char* lds, const Gemm g, const Sched& S, const Epi& E, int tid_in) {
;     ...
;             PG8_BAR; PG8_WAIT_L(0); PG8_MMA(1, 0, At, B0); PG8_BAR; PG8_SCHED;
;             PG8_STAGE(PG8_SB(1, 1), b3 + hstep, voffB);
;             PG8_WAIT_V(6); PG8_BAR; PG8_MMA(1, 1, At, B1); PG8_BAR;
;     __device__ __forceinline__ void operator()(f32x4 (&acc)[2][2][4][2], const Unit& u, int wr, int wc, int fr, int fq) const {
;         const int row0 = u.pm * 256 + wr * 64 + fr, col0 = u.pn * 256 + wc * 32 + 8 * fq;
; #pragma unroll
;         for (int bj = 0; bj < 2; ++bj) { const f32x4 b0 = *(const f32x4*)(bias + col0 + bj * 128), b1 = *(const f32x4*)(bias + col0 + bj * 128 + 4);
; #pragma unroll
;             for (int ai = 0; ai < 2; ++ai)
; #pragma unroll
;                 for (int m = 0; m < 4; ++m) { f32x4 v0 = acc[ai][bj][m][0] + b0, v1 = acc[ai][bj][m][1] + b1;
; #pragma unroll
;                     for (int j = 0; j < 4; ++j) { v0[j] = fmaxf(v0[j], 0.f); v0[j] *= v0[j]; v1[j] = fmaxf(v1[j], 0.f); v1[j] *= v1[j]; }
;                     u32x4 w; w.x = cvt_pk_bf16(v0[0], v0[1]); w.y = cvt_pk_bf16(v0[2], v0[3]); w.z = cvt_pk_bf16(v1[0], v1[1]); w.w = cvt_pk_bf16(v1[2], v1[3]);
;                     *(u32x4*)(O + (size_t)(row0 + ai * 128 + m * 16) * 4096 + col0 + bj * 128) = w; } }
	s_waitcnt lgkmcnt(0)
	s_waitcnt lgkmcnt(0)
	v_mfma_f32_16x16x32_bf16 v[92:95], v[120:123], v[158:161], v[92:95]
	v_mfma_f32_16x16x32_bf16 v[88:91], v[146:149], v[158:161], v[88:91]
	v_mfma_f32_16x16x32_bf16 v[84:87], v[120:123], v[166:169], v[84:87]
	v_mfma_f32_16x16x32_bf16 v[80:83], v[146:149], v[166:169], v[80:83]
	v_mfma_f32_16x16x32_bf16 v[76:79], v[120:123], v[174:177], v[76:79]
	v_mfma_f32_16x16x32_bf16 v[72:75], v[146:149], v[174:177], v[72:75]
	v_mfma_f32_16x16x32_bf16 v[68:71], v[120:123], v[182:185], v[68:71]
	v_mfma_f32_16x16x32_bf16 v[64:67], v[146:149], v[182:185], v[64:67]
	v_mfma_f32_16x16x32_bf16 v[92:95], v[124:127], v[162:165], v[92:95]
	v_mfma_f32_16x16x32_bf16 v[88:91], v[154:157], v[162:165], v[88:91]
	v_mfma_f32_16x16x32_bf16 v[84:87], v[124:127], v[170:173], v[84:87]
	v_mfma_f32_16x16x32_bf16 v[80:83], v[154:157], v[170:173], v[80:83]
	v_mfma_f32_16x16x32_bf16 v[76:79], v[124:127], v[178:181], v[76:79]
	v_mfma_f32_16x16x32_bf16 v[72:75], v[154:157], v[178:181], v[72:75]
	v_mfma_f32_16x16x32_bf16 v[68:71], v[124:127], v[186:189], v[68:71]
	v_mfma_f32_16x16x32_bf16 v[64:67], v[154:157], v[186:189], v[64:67]
	s_barrier
	s_add_u32 s24, s24, 0x40080
	s_addc_u32 s25, s25, 0
	s_add_i32 s26, s26, s38
	v_lshl_add_u64 v[120:121], s[24:25], 0, v[192:193]
	s_mov_b32 m0, s26
	s_nop 0
	global_load_lds_dwordx4 v[120:121], off
	v_lshl_add_u64 v[120:121], s[24:25], 0, v[140:141]
	s_add_i32 m0, s26, 0x2000
	s_nop 0
	global_load_lds_dwordx4 v[120:121], off
	s_waitcnt vmcnt(6)
	s_barrier
	v_mfma_f32_16x16x32_bf16 v[28:31], v[194:197], v[158:161], v[28:31]
	v_mfma_f32_16x16x32_bf16 v[24:27], v[204:207], v[158:161], v[24:27]
	v_mfma_f32_16x16x32_bf16 v[20:23], v[194:197], v[166:169], v[20:23]
	v_mfma_f32_16x16x32_bf16 v[16:19], v[204:207], v[166:169], v[16:19]
	v_mfma_f32_16x16x32_bf16 v[12:15], v[194:197], v[174:177], v[12:15]
	v_mfma_f32_16x16x32_bf16 v[8:11], v[204:207], v[174:177], v[8:11]
	v_mfma_f32_16x16x32_bf16 v[4:7], v[194:197], v[182:185], v[4:7]
	v_mfma_f32_16x16x32_bf16 v[0:3], v[204:207], v[182:185], v[0:3]
	v_mfma_f32_16x16x32_bf16 v[28:31], v[200:203], v[162:165], v[28:31]
	v_mfma_f32_16x16x32_bf16 v[24:27], v[208:211], v[162:165], v[24:27]
	v_mfma_f32_16x16x32_bf16 v[20:23], v[200:203], v[170:173], v[20:23]
	v_mfma_f32_16x16x32_bf16 v[16:19], v[208:211], v[170:173], v[16:19]
	v_mfma_f32_16x16x32_bf16 v[12:15], v[200:203], v[178:181], v[12:15]
	v_mfma_f32_16x16x32_bf16 v[8:11], v[208:211], v[178:181], v[8:11]
	v_mfma_f32_16x16x32_bf16 v[4:7], v[200:203], v[186:189], v[4:7]
	v_mfma_f32_16x16x32_bf16 v[0:3], v[208:211], v[186:189], v[0:3]
	s_add_i32 s50, s50, 2
	s_add_u32 s22, s22, 0x100
	s_addc_u32 s23, s23, 0
	s_add_u32 s48, s48, 0x100
	s_addc_u32 s49, s49, 0
	s_cmp_gt_u32 s50, 13
	s_barrier
	s_cbranch_scc0 .LBB0_295
	v_lshl_or_b32 v154, s33, 8, v152
	v_ashrrev_i32_e32 v155, 31, v154
	v_lshl_add_u64 v[146:147], v[154:155], 2, s[6:7]
	global_load_dwordx4 v[120:123], v[146:147], off offset:16
	global_load_dwordx4 v[124:127], v[146:147], off
	global_load_dwordx4 v[200:203], v[146:147], off offset:528
	global_load_dwordx4 v[204:207], v[146:147], off offset:512
	v_lshl_add_u32 v148, s14, 8, v150
	v_ashrrev_i32_e32 v149, 31, v148
	s_mov_b32 s5, 0x100000
	s_mov_b64 s[22:23], 0x100000
	s_mov_b32 s33, s4
	s_mov_b32 s14, s8
	s_mov_b64 s[24:25], s[12:13]
	s_waitcnt vmcnt(0)
	v_pk_add_f32 v[128:129], v[128:129], v[120:121]
	v_pk_add_f32 v[134:135], v[134:135], v[126:127]
	v_pk_add_f32 v[132:133], v[132:133], v[124:125]
	v_pk_add_f32 v[130:131], v[130:131], v[122:123]
	v_max_f32_e32 v132, 0, v132
	v_max_f32_e32 v128, 0, v128
	v_max_f32_e32 v133, 0, v133
	v_max_f32_e32 v129, 0, v129
	v_max_f32_e32 v134, 0, v134
	v_mul_f32_e32 v132, v132, v132
	v_mul_f32_e32 v128, v128, v128
	v_mul_f32_e32 v133, v133, v133
	v_mul_f32_e32 v129, v129, v129
	v_mul_f32_e32 v134, v134, v134
	v_max_f32_e32 v130, 0, v130
	v_max_f32_e32 v135, 0, v135
	v_max_f32_e32 v131, 0, v131
	v_mul_f32_e32 v130, v130, v130
	v_mul_f32_e32 v135, v135, v135
	v_mul_f32_e32 v131, v131, v131
	v_cvt_pk_bf16_f32 v132, v132, v133
	v_cvt_pk_bf16_f32 v133, v134, v135
	v_cvt_pk_bf16_f32 v134, v128, v129
	v_lshlrev_b64 v[128:129], 13, v[148:149]
	v_cvt_pk_bf16_f32 v135, v130, v131
	v_lshl_add_u64 v[128:129], s[0:1], 0, v[128:129]
	v_lshlrev_b64 v[130:131], 1, v[154:155]
	v_pk_add_f32 v[114:115], v[114:115], v[122:123]
	v_lshl_add_u64 v[128:129], v[128:129], 0, v[130:131]
	v_pk_add_f32 v[118:119], v[118:119], v[126:127]
	v_pk_add_f32 v[116:117], v[116:117], v[124:125]
	v_pk_add_f32 v[112:113], v[112:113], v[120:121]
	v_max_f32_e32 v114, 0, v114
	global_store_dwordx4 v[128:129], v[132:135], off
	v_max_f32_e32 v116, 0, v116
	v_max_f32_e32 v112, 0, v112
	v_mul_f32_e32 v132, v114, v114
	v_max_f32_e32 v114, 0, v119
	v_mul_f32_e32 v116, v116, v116
	v_mul_f32_e32 v112, v112, v112
	v_max_f32_e32 v117, 0, v117
	v_max_f32_e32 v113, 0, v113
	v_max_f32_e32 v118, 0, v118
	v_mul_f32_e32 v119, v114, v114
	v_max_f32_e32 v114, 0, v115
	v_mul_f32_e32 v117, v117, v117
	v_mul_f32_e32 v113, v113, v113
	v_mul_f32_e32 v118, v118, v118
	v_mul_f32_e32 v133, v114, v114
	v_cvt_pk_bf16_f32 v114, v116, v117
	v_cvt_pk_bf16_f32 v115, v118, v119
	v_cvt_pk_bf16_f32 v116, v112, v113
	v_or_b32_e32 v112, 16, v148
	v_ashrrev_i32_e32 v113, 31, v112
	v_lshlrev_b64 v[112:113], 13, v[112:113]
	v_lshl_add_u64 v[112:113], s[0:1], 0, v[112:113]
	v_pk_add_f32 v[106:107], v[106:107], v[122:123]
	v_lshl_add_u64 v[112:113], v[112:113], 0, v[130:131]
	v_pk_add_f32 v[110:111], v[110:111], v[126:127]
	v_pk_add_f32 v[108:109], v[108:109], v[124:125]
	v_pk_add_f32 v[104:105], v[104:105], v[120:121]
	v_max_f32_e32 v106, 0, v106
; __device__ __forceinline__ unsigned cvt_pk_bf16(float lo, float hi) { unsigned r; asm volatile("s_nop 0\n\tv_cvt_pk_bf16_f32 %0, %1, %2\n\ts_nop 1" : "=v"(r) : "v"(lo), "v"(hi)); return r; }
;     __device__ __forceinline__ void operator()(f32x4 (&acc)[2][2][4][2], const Unit& u, int wr, int wc, int fr, int fq) const {
;     ...
;         for (int bj = 0; bj < 2; ++bj) { const f32x4 b0 = *(const f32x4*)(bias + col0 + bj * 128), b1 = *(const f32x4*)(bias + col0 + bj * 128 + 4);
; #pragma unroll
;             for (int ai = 0; ai < 2; ++ai)
; #pragma unroll
;                 for (int m = 0; m < 4; ++m) { f32x4 v0 = acc[ai][bj][m][0] + b0, v1 = acc[ai][bj][m][1] + b1;
; #pragma unroll
;                     for (int j = 0; j < 4; ++j) { v0[j] = fmaxf(v0[j], 0.f); v0[j] *= v0[j]; v1[j] = fmaxf(v1[j], 0.f); v1[j] *= v1[j]; }
;                     u32x4 w; w.x = cvt_pk_bf16(v0[0], v0[1]); w.y = cvt_pk_bf16(v0[2], v0[3]); w.z = cvt_pk_bf16(v1[0], v1[1]); w.w = cvt_pk_bf16(v1[2], v1[3]);
;                     *(u32x4*)(O + (size_t)(row0 + ai * 128 + m * 16) * 4096 + col0 + bj * 128) = w; } }
	v_cvt_pk_bf16_f32 v117, v132, v133
	global_store_dwordx4 v[112:113], v[114:117], off
	v_max_f32_e32 v108, 0, v108
	v_max_f32_e32 v104, 0, v104
	v_mul_f32_e32 v114, v106, v106
	v_max_f32_e32 v106, 0, v111
	v_mul_f32_e32 v108, v108, v108
	v_mul_f32_e32 v104, v104, v104
	v_max_f32_e32 v109, 0, v109
	v_max_f32_e32 v105, 0, v105
	v_max_f32_e32 v110, 0, v110
	v_mul_f32_e32 v111, v106, v106
	v_max_f32_e32 v106, 0, v107
	v_mul_f32_e32 v109, v109, v109
	v_mul_f32_e32 v105, v105, v105
	v_mul_f32_e32 v110, v110, v110
	v_mul_f32_e32 v115, v106, v106
	v_cvt_pk_bf16_f32 v106, v108, v109
	v_cvt_pk_bf16_f32 v107, v110, v111
	v_cvt_pk_bf16_f32 v108, v104, v105
	v_or_b32_e32 v104, 32, v148
	v_ashrrev_i32_e32 v105, 31, v104
	v_lshlrev_b64 v[104:105], 13, v[104:105]
	v_lshl_add_u64 v[104:105], s[0:1], 0, v[104:105]
	v_pk_add_f32 v[98:99], v[98:99], v[122:123]
	v_lshl_add_u64 v[104:105], v[104:105], 0, v[130:131]
	v_pk_add_f32 v[102:103], v[102:103], v[126:127]
	v_pk_add_f32 v[100:101], v[100:101], v[124:125]
	v_pk_add_f32 v[96:97], v[96:97], v[120:121]
	v_max_f32_e32 v98, 0, v98
	v_cvt_pk_bf16_f32 v109, v114, v115
	global_store_dwordx4 v[104:105], v[106:109], off
	v_max_f32_e32 v100, 0, v100
	v_max_f32_e32 v96, 0, v96
	v_mul_f32_e32 v106, v98, v98
	v_max_f32_e32 v98, 0, v103
	v_mul_f32_e32 v100, v100, v100
	v_mul_f32_e32 v96, v96, v96
	v_max_f32_e32 v101, 0, v101
	v_max_f32_e32 v97, 0, v97
	v_max_f32_e32 v102, 0, v102
	v_mul_f32_e32 v103, v98, v98
	v_max_f32_e32 v98, 0, v99
	v_mul_f32_e32 v101, v101, v101
	v_mul_f32_e32 v97, v97, v97
	v_mul_f32_e32 v102, v102, v102
	v_mul_f32_e32 v107, v98, v98
	v_cvt_pk_bf16_f32 v98, v100, v101
	v_cvt_pk_bf16_f32 v99, v102, v103
	v_cvt_pk_bf16_f32 v100, v96, v97
	v_or_b32_e32 v96, 48, v148
	v_ashrrev_i32_e32 v97, 31, v96
	v_lshlrev_b64 v[96:97], 13, v[96:97]
	v_lshl_add_u64 v[96:97], s[0:1], 0, v[96:97]
	v_pk_add_f32 v[90:91], v[90:91], v[122:123]
	v_lshl_add_u64 v[96:97], v[96:97], 0, v[130:131]
	v_pk_add_f32 v[94:95], v[94:95], v[126:127]
	v_max_f32_e32 v90, 0, v90
	v_cvt_pk_bf16_f32 v101, v106, v107
	global_store_dwordx4 v[96:97], v[98:101], off
	v_pk_add_f32 v[92:93], v[92:93], v[124:125]
	v_max_f32_e32 v94, 0, v94
	v_mul_f32_e32 v98, v90, v90
	v_max_f32_e32 v90, 0, v95
	v_max_f32_e32 v92, 0, v92
	v_max_f32_e32 v93, 0, v93
	v_mul_f32_e32 v94, v94, v94
	v_mul_f32_e32 v95, v90, v90
	v_max_f32_e32 v90, 0, v91
	v_pk_add_f32 v[88:89], v[88:89], v[120:121]
	v_mul_f32_e32 v92, v92, v92
	v_mul_f32_e32 v93, v93, v93
	v_mul_f32_e32 v99, v90, v90
	v_cvt_pk_bf16_f32 v90, v92, v93
	v_cvt_pk_bf16_f32 v91, v94, v95
	v_add_co_u32_e32 v94, vcc, s5, v128
	v_pk_add_f32 v[82:83], v[82:83], v[122:123]
	v_max_f32_e32 v88, 0, v88
	v_max_f32_e32 v89, 0, v89
	v_addc_co_u32_e32 v95, vcc, 0, v129, vcc
	v_pk_add_f32 v[86:87], v[86:87], v[126:127]
	v_max_f32_e32 v82, 0, v82
	v_mul_f32_e32 v88, v88, v88
	v_mul_f32_e32 v89, v89, v89
	v_cvt_pk_bf16_f32 v92, v88, v89
	v_cvt_pk_bf16_f32 v93, v98, v99
	global_store_dwordx4 v[94:95], v[90:93], off
	v_pk_add_f32 v[84:85], v[84:85], v[124:125]
	v_max_f32_e32 v86, 0, v86
	v_mul_f32_e32 v90, v82, v82
	v_max_f32_e32 v82, 0, v87
	v_max_f32_e32 v84, 0, v84
	v_max_f32_e32 v85, 0, v85
	v_mul_f32_e32 v86, v86, v86
	v_mul_f32_e32 v87, v82, v82
	v_max_f32_e32 v82, 0, v83
	s_mov_b32 s5, 0x120000
	v_pk_add_f32 v[80:81], v[80:81], v[120:121]
	v_mul_f32_e32 v84, v84, v84
	v_mul_f32_e32 v85, v85, v85
	v_mul_f32_e32 v91, v82, v82
	v_cvt_pk_bf16_f32 v82, v84, v85
	v_cvt_pk_bf16_f32 v83, v86, v87
	v_add_co_u32_e32 v86, vcc, s5, v128
	v_pk_add_f32 v[74:75], v[74:75], v[122:123]
	v_max_f32_e32 v80, 0, v80
	v_max_f32_e32 v81, 0, v81
	v_addc_co_u32_e32 v87, vcc, 0, v129, vcc
	v_pk_add_f32 v[78:79], v[78:79], v[126:127]
	v_max_f32_e32 v74, 0, v74
	v_mul_f32_e32 v80, v80, v80
	v_mul_f32_e32 v81, v81, v81
	v_cvt_pk_bf16_f32 v84, v80, v81
	v_cvt_pk_bf16_f32 v85, v90, v91
	global_store_dwordx4 v[86:87], v[82:85], off
	v_pk_add_f32 v[76:77], v[76:77], v[124:125]
	v_max_f32_e32 v78, 0, v78
	v_mul_f32_e32 v82, v74, v74
	v_max_f32_e32 v74, 0, v79
	v_max_f32_e32 v76, 0, v76
	v_max_f32_e32 v77, 0, v77
	v_mul_f32_e32 v78, v78, v78
	v_mul_f32_e32 v79, v74, v74
	v_max_f32_e32 v74, 0, v75
	s_mov_b32 s5, 0x140000
	v_pk_add_f32 v[72:73], v[72:73], v[120:121]
	v_mul_f32_e32 v76, v76, v76
	v_mul_f32_e32 v77, v77, v77
	v_mul_f32_e32 v83, v74, v74
	v_cvt_pk_bf16_f32 v74, v76, v77
	v_cvt_pk_bf16_f32 v75, v78, v79
	v_add_co_u32_e32 v78, vcc, s5, v128
	v_pk_add_f32 v[64:65], v[64:65], v[120:121]
	v_max_f32_e32 v72, 0, v72
	v_max_f32_e32 v73, 0, v73
	v_addc_co_u32_e32 v79, vcc, 0, v129, vcc
	v_pk_add_f32 v[68:69], v[68:69], v[124:125]
	v_pk_add_f32 v[66:67], v[66:67], v[122:123]
	v_max_f32_e32 v64, 0, v64
	v_mul_f32_e32 v72, v72, v72
	v_mul_f32_e32 v73, v73, v73
	v_cvt_pk_bf16_f32 v76, v72, v73
	v_cvt_pk_bf16_f32 v77, v82, v83
	global_store_dwordx4 v[78:79], v[74:77], off
	v_pk_add_f32 v[70:71], v[70:71], v[126:127]
	v_max_f32_e32 v68, 0, v68
	v_mul_f32_e32 v74, v64, v64
	v_max_f32_e32 v64, 0, v69
	v_max_f32_e32 v65, 0, v65
	v_max_f32_e32 v66, 0, v66
	v_mul_f32_e32 v68, v68, v68
	v_mul_f32_e32 v64, v64, v64
	v_mul_f32_e32 v69, v65, v65
	v_max_f32_e32 v65, 0, v70
	v_mul_f32_e32 v70, v66, v66
	v_max_f32_e32 v66, 0, v71
	s_mov_b32 s5, 0x160000
	v_mul_f32_e32 v65, v65, v65
	v_mul_f32_e32 v66, v66, v66
	v_max_f32_e32 v67, 0, v67
	v_cvt_pk_bf16_f32 v64, v68, v64
	v_add_co_u32_e32 v68, vcc, s5, v128
	v_mul_f32_e32 v67, v67, v67
	v_cvt_pk_bf16_f32 v65, v65, v66
	v_cvt_pk_bf16_f32 v66, v74, v69
	s_nop 0
	v_addc_co_u32_e32 v69, vcc, 0, v129, vcc
	v_cvt_pk_bf16_f32 v67, v70, v67
	global_store_dwordx4 v[68:69], v[64:67], off
	s_nop 1
	v_mov_b32_e32 v64, v200
; __device__ __forceinline__ unsigned cvt_pk_bf16(float lo, float hi) { unsigned r; asm volatile("s_nop 0\n\tv_cvt_pk_bf16_f32 %0, %1, %2\n\ts_nop 1" : "=v"(r) : "v"(lo), "v"(hi)); return r; }
; #define PG8_WAIT_V(n) asm volatile("s_waitcnt vmcnt(" #n ")" ::: "memory")
; #define PG8_BAR __builtin_amdgcn_s_barrier()
; template <class Epi, class Sched>
; __device__ __forceinline__ void gemm_phase(PG8_LAS unsigned char* lds, const Gemm g, const Sched& S, const Epi& E, int tid_in) {
;     ...
;     PG8_WAIT_V(0);
;     if (wr == 0) PG8_BAR;
;     __device__ __forceinline__ void operator()(f32x4 (&acc)[2][2][4][2], const Unit& u, int wr, int wc, int fr, int fq) const {
;     ...
;         for (int bj = 0; bj < 2; ++bj) { const f32x4 b0 = *(const f32x4*)(bias + col0 + bj * 128), b1 = *(const f32x4*)(bias + col0 + bj * 128 + 4);
; #pragma unroll
;             for (int ai = 0; ai < 2; ++ai)
; #pragma unroll
;                 for (int m = 0; m < 4; ++m) { f32x4 v0 = acc[ai][bj][m][0] + b0, v1 = acc[ai][bj][m][1] + b1;
; #pragma unroll
;                     for (int j = 0; j < 4; ++j) { v0[j] = fmaxf(v0[j], 0.f); v0[j] *= v0[j]; v1[j] = fmaxf(v1[j], 0.f); v1[j] *= v1[j]; }
;                     u32x4 w; w.x = cvt_pk_bf16(v0[0], v0[1]); w.y = cvt_pk_bf16(v0[2], v0[3]); w.z = cvt_pk_bf16(v1[0], v1[1]); w.w = cvt_pk_bf16(v1[2], v1[3]);
;                     *(u32x4*)(O + (size_t)(row0 + ai * 128 + m * 16) * 4096 + col0 + bj * 128) = w; } }
	v_mov_b32_e32 v65, v201
	v_mov_b32_e32 v66, v202
	v_mov_b32_e32 v67, v203
	v_mov_b32_e32 v68, v204
	v_mov_b32_e32 v69, v205
	v_mov_b32_e32 v70, v206
	v_mov_b32_e32 v71, v207
	v_lshl_add_u64 v[88:89], v[128:129], 0, s[22:23]
	s_mov_b64 s[22:23], 0x120000
	v_lshl_add_u64 v[80:81], v[128:129], 0, s[22:23]
	s_mov_b64 s[22:23], 0x140000
	v_lshl_add_u64 v[72:73], v[128:129], 0, s[22:23]
	s_mov_b64 s[22:23], 0x160000
	v_lshl_add_u64 v[74:75], v[128:129], 0, s[22:23]
	s_and_b64 vcc, exec, s[2:3]
	s_mov_b64 s[22:23], s[10:11]
	v_pk_add_f32 v[56:57], v[56:57], v[64:65]
	v_pk_add_f32 v[60:61], v[60:61], v[68:69]
	v_pk_add_f32 v[58:59], v[58:59], v[66:67]
	v_max_f32_e32 v56, 0, v56
	v_pk_add_f32 v[62:63], v[62:63], v[70:71]
	v_mul_f32_e32 v76, v56, v56
	v_max_f32_e32 v56, 0, v61
	v_max_f32_e32 v57, 0, v57
	v_max_f32_e32 v58, 0, v58
	v_max_f32_e32 v60, 0, v60
	v_mul_f32_e32 v56, v56, v56
	v_mul_f32_e32 v61, v57, v57
	v_max_f32_e32 v57, 0, v62
	v_mul_f32_e32 v62, v58, v58
	v_max_f32_e32 v58, 0, v63
	v_max_f32_e32 v59, 0, v59
	v_pk_add_f32 v[48:49], v[48:49], v[64:65]
	v_mul_f32_e32 v60, v60, v60
	v_mul_f32_e32 v57, v57, v57
	v_mul_f32_e32 v58, v58, v58
	v_mul_f32_e32 v59, v59, v59
	v_cvt_pk_bf16_f32 v56, v60, v56
	v_pk_add_f32 v[52:53], v[52:53], v[68:69]
	v_pk_add_f32 v[50:51], v[50:51], v[66:67]
	v_max_f32_e32 v48, 0, v48
	v_cvt_pk_bf16_f32 v57, v57, v58
	v_cvt_pk_bf16_f32 v58, v76, v61
	v_cvt_pk_bf16_f32 v59, v62, v59
	global_store_dwordx4 v[128:129], v[56:59], off offset:256
	v_pk_add_f32 v[54:55], v[54:55], v[70:71]
	v_max_f32_e32 v49, 0, v49
	v_mul_f32_e32 v56, v48, v48
	v_max_f32_e32 v48, 0, v53
	v_max_f32_e32 v50, 0, v50
	v_max_f32_e32 v52, 0, v52
	v_mul_f32_e32 v48, v48, v48
	v_mul_f32_e32 v53, v49, v49
	v_max_f32_e32 v49, 0, v54
	v_mul_f32_e32 v54, v50, v50
	v_max_f32_e32 v50, 0, v55
	v_max_f32_e32 v51, 0, v51
	v_pk_add_f32 v[40:41], v[40:41], v[64:65]
	v_mul_f32_e32 v52, v52, v52
	v_mul_f32_e32 v49, v49, v49
	v_mul_f32_e32 v50, v50, v50
	v_mul_f32_e32 v51, v51, v51
	v_cvt_pk_bf16_f32 v48, v52, v48
	v_pk_add_f32 v[44:45], v[44:45], v[68:69]
	v_pk_add_f32 v[42:43], v[42:43], v[66:67]
	v_max_f32_e32 v40, 0, v40
	v_cvt_pk_bf16_f32 v49, v49, v50
	v_cvt_pk_bf16_f32 v50, v56, v53
	v_cvt_pk_bf16_f32 v51, v54, v51
	global_store_dwordx4 v[112:113], v[48:51], off offset:256
	v_pk_add_f32 v[46:47], v[46:47], v[70:71]
	v_max_f32_e32 v41, 0, v41
	v_mul_f32_e32 v48, v40, v40
	v_max_f32_e32 v40, 0, v45
	v_max_f32_e32 v42, 0, v42
	v_max_f32_e32 v44, 0, v44
	v_mul_f32_e32 v40, v40, v40
	v_mul_f32_e32 v45, v41, v41
	v_max_f32_e32 v41, 0, v46
	v_mul_f32_e32 v46, v42, v42
	v_max_f32_e32 v42, 0, v47
	v_max_f32_e32 v43, 0, v43
	v_pk_add_f32 v[32:33], v[32:33], v[64:65]
	v_mul_f32_e32 v44, v44, v44
	v_mul_f32_e32 v41, v41, v41
	v_mul_f32_e32 v42, v42, v42
	v_mul_f32_e32 v43, v43, v43
	v_cvt_pk_bf16_f32 v40, v44, v40
	v_pk_add_f32 v[36:37], v[36:37], v[68:69]
	v_pk_add_f32 v[34:35], v[34:35], v[66:67]
	v_max_f32_e32 v32, 0, v32
	v_cvt_pk_bf16_f32 v41, v41, v42
	v_cvt_pk_bf16_f32 v42, v48, v45
	v_cvt_pk_bf16_f32 v43, v46, v43
	global_store_dwordx4 v[104:105], v[40:43], off offset:256
	v_pk_add_f32 v[38:39], v[38:39], v[70:71]
	v_max_f32_e32 v33, 0, v33
	v_mul_f32_e32 v40, v32, v32
	v_max_f32_e32 v32, 0, v37
	v_max_f32_e32 v34, 0, v34
	v_max_f32_e32 v36, 0, v36
	v_mul_f32_e32 v32, v32, v32
	v_mul_f32_e32 v37, v33, v33
	v_max_f32_e32 v33, 0, v38
	v_mul_f32_e32 v38, v34, v34
	v_max_f32_e32 v34, 0, v39
	v_max_f32_e32 v35, 0, v35
	v_pk_add_f32 v[24:25], v[24:25], v[64:65]
	v_mul_f32_e32 v36, v36, v36
	v_mul_f32_e32 v33, v33, v33
	v_mul_f32_e32 v34, v34, v34
	v_mul_f32_e32 v35, v35, v35
	v_cvt_pk_bf16_f32 v32, v36, v32
	v_pk_add_f32 v[28:29], v[28:29], v[68:69]
	v_pk_add_f32 v[26:27], v[26:27], v[66:67]
	v_max_f32_e32 v24, 0, v24
	v_cvt_pk_bf16_f32 v33, v33, v34
	v_cvt_pk_bf16_f32 v34, v40, v37
	v_cvt_pk_bf16_f32 v35, v38, v35
	global_store_dwordx4 v[96:97], v[32:35], off offset:256
	v_pk_add_f32 v[30:31], v[30:31], v[70:71]
	v_max_f32_e32 v25, 0, v25
	v_mul_f32_e32 v32, v24, v24
	v_max_f32_e32 v24, 0, v29
	v_max_f32_e32 v26, 0, v26
	v_max_f32_e32 v28, 0, v28
	v_mul_f32_e32 v24, v24, v24
	v_mul_f32_e32 v29, v25, v25
	v_max_f32_e32 v25, 0, v30
	v_mul_f32_e32 v30, v26, v26
	v_max_f32_e32 v26, 0, v31
	v_max_f32_e32 v27, 0, v27
	v_pk_add_f32 v[16:17], v[16:17], v[64:65]
	v_mul_f32_e32 v28, v28, v28
	v_mul_f32_e32 v25, v25, v25
	v_mul_f32_e32 v26, v26, v26
	v_mul_f32_e32 v27, v27, v27
	v_cvt_pk_bf16_f32 v24, v28, v24
	v_pk_add_f32 v[20:21], v[20:21], v[68:69]
	v_pk_add_f32 v[18:19], v[18:19], v[66:67]
	v_max_f32_e32 v16, 0, v16
	v_cvt_pk_bf16_f32 v25, v25, v26
	v_cvt_pk_bf16_f32 v26, v32, v29
	v_cvt_pk_bf16_f32 v27, v30, v27
	global_store_dwordx4 v[88:89], v[24:27], off offset:256
	v_pk_add_f32 v[22:23], v[22:23], v[70:71]
	v_max_f32_e32 v17, 0, v17
	v_mul_f32_e32 v24, v16, v16
	v_max_f32_e32 v16, 0, v21
	v_max_f32_e32 v18, 0, v18
	v_max_f32_e32 v20, 0, v20
	v_mul_f32_e32 v16, v16, v16
	v_mul_f32_e32 v21, v17, v17
	v_max_f32_e32 v17, 0, v22
	v_mul_f32_e32 v22, v18, v18
	v_max_f32_e32 v18, 0, v23
	v_max_f32_e32 v19, 0, v19
	v_pk_add_f32 v[8:9], v[8:9], v[64:65]
	v_mul_f32_e32 v20, v20, v20
	v_mul_f32_e32 v17, v17, v17
	v_mul_f32_e32 v18, v18, v18
	v_mul_f32_e32 v19, v19, v19
	v_cvt_pk_bf16_f32 v16, v20, v16
	v_pk_add_f32 v[12:13], v[12:13], v[68:69]
	v_pk_add_f32 v[10:11], v[10:11], v[66:67]
	v_max_f32_e32 v8, 0, v8
	v_cvt_pk_bf16_f32 v17, v17, v18
	v_cvt_pk_bf16_f32 v18, v24, v21
	v_cvt_pk_bf16_f32 v19, v22, v19
	global_store_dwordx4 v[80:81], v[16:19], off offset:256
	v_pk_add_f32 v[14:15], v[14:15], v[70:71]
	v_max_f32_e32 v9, 0, v9
	v_mul_f32_e32 v16, v8, v8
	v_max_f32_e32 v8, 0, v13
	v_max_f32_e32 v10, 0, v10
	v_max_f32_e32 v12, 0, v12
	v_mul_f32_e32 v8, v8, v8
	v_mul_f32_e32 v13, v9, v9
	v_max_f32_e32 v9, 0, v14
	v_mul_f32_e32 v14, v10, v10
	v_max_f32_e32 v10, 0, v15
	v_max_f32_e32 v11, 0, v11
	v_pk_add_f32 v[2:3], v[2:3], v[66:67]
	v_pk_add_f32 v[0:1], v[0:1], v[64:65]
	v_mul_f32_e32 v12, v12, v12
	v_mul_f32_e32 v9, v9, v9
	v_mul_f32_e32 v10, v10, v10
	v_mul_f32_e32 v11, v11, v11
	v_cvt_pk_bf16_f32 v8, v12, v8
	v_pk_add_f32 v[6:7], v[6:7], v[70:71]
	v_pk_add_f32 v[4:5], v[4:5], v[68:69]
	v_max_f32_e32 v0, 0, v0
	v_max_f32_e32 v1, 0, v1
	v_max_f32_e32 v2, 0, v2
	v_cvt_pk_bf16_f32 v9, v9, v10
	v_cvt_pk_bf16_f32 v10, v16, v13
	v_cvt_pk_bf16_f32 v11, v14, v11
	global_store_dwordx4 v[72:73], v[8:11], off offset:256
	v_max_f32_e32 v3, 0, v3
	v_max_f32_e32 v4, 0, v4
	v_mul_f32_e32 v8, v0, v0
	v_max_f32_e32 v0, 0, v5
	v_mul_f32_e32 v5, v1, v1
	v_max_f32_e32 v1, 0, v6
	v_mul_f32_e32 v6, v2, v2
	v_max_f32_e32 v2, 0, v7
	v_mul_f32_e32 v0, v0, v0
	v_mul_f32_e32 v1, v1, v1
	v_mul_f32_e32 v2, v2, v2
	v_mul_f32_e32 v3, v3, v3
	v_mul_f32_e32 v4, v4, v4
	v_cvt_pk_bf16_f32 v0, v4, v0
	v_cvt_pk_bf16_f32 v1, v1, v2
	v_cvt_pk_bf16_f32 v2, v8, v5
	v_cvt_pk_bf16_f32 v3, v6, v3
	s_nop 1
	global_store_dwordx4 v[74:75], v[0:3], off offset:256
	s_cbranch_vccz .LBB0_288
	s_waitcnt vmcnt(0)
	s_cmpk_gt_u32 s28, 0xff
	s_cbranch_scc1 .LBB0_299
	s_barrier

; #define PG8_STAGE(bufoff, gbase, voff) do { _Pragma("unroll") for (int _i = 0; _i < 2; ++_i) \
;         __builtin_amdgcn_global_load_lds((const unsigned*)((const char*)(gbase) + (voff)[_i]), (PG8_LAS unsigned*)(lds + (bufoff) + ldsw + _i * 8192), 16, 0, 0); } while (0)
; #define PG8_LDA(dst, b, h) do { _Pragma("unroll") for (int m = 0; m < 4; ++m) _Pragma("unroll") for (int k = 0; k < 2; ++k) dst[m][k] = *(const PG8_LAS bf16x8*)(lds + PG8_SA(b, h) + aoff + m * 2048 + k * 1024); } while (0)
; #define PG8_LDB(dst, b, h) do { _Pragma("unroll") for (int n = 0; n < 2; ++n) _Pragma("unroll") for (int k = 0; k < 2; ++k) dst[n][k] = *(const PG8_LAS bf16x8*)(lds + PG8_SB(b, h) + boff + n * 2048 + k * 1024); } while (0)
; #define PG8_MMA(ai, bj, At, Bt) do { __builtin_amdgcn_s_setprio(1); _Pragma("unroll") for (int m = 0; m < 4; ++m) _Pragma("unroll") for (int n = 0; n < 2; ++n) _Pragma("unroll") for (int k = 0; k < 2; ++k) \
;         acc[ai][bj][m][n] = __builtin_amdgcn_mfma_f32_16x16x32_bf16(Bt[n][k], At[m][k], acc[ai][bj][m][n], 0, 0, 0); __builtin_amdgcn_s_setprio(0); } while (0)
; #define PG8_WAIT_L(n) asm volatile("s_waitcnt lgkmcnt(" #n ")" ::: "memory")
; #define PG8_BAR __builtin_amdgcn_s_barrier()
; #define PG8_SCHED __builtin_amdgcn_sched_barrier(0)
; template <class Epi, class Sched>
; __device__ __forceinline__ void gemm_phase(PG8_LAS unsigned char* lds, const Gemm g, const Sched& S, const Epi& E, int tid_in) {
;     ...
;             const bool last = (t == nt - 2);
;             const char* a1 = cA + (size_t)(t + 1) * kstep;
;             const char* a2 = last ? nA : cA + (size_t)(t + 2) * kstep; const char* b2 = last ? nB : cB + (size_t)(t + 2) * kstep;
;             const char* a3 = a2 + kstep; const char* b3 = b2 + kstep;
;             if (last && has_next) S.a_ready(nxt);
;             PG8_LDB(B0, 0, 0); PG8_SCHED; PG8_LDA(At, 0, 0); PG8_STAGE(PG8_SA(1, 1), a1 + hstep, voffA);
;             PG8_WAIT_L(8); PG8_BAR; PG8_WAIT_L(0); PG8_MMA(0, 0, At, B0); PG8_BAR; PG8_SCHED;
;             PG8_LDB(B1, 0, 1); PG8_STAGE(PG8_SB(0, 0), b2, voffB);
;             PG8_BAR; PG8_WAIT_L(0); PG8_MMA(0, 1, At, B1); PG8_BAR;
;             PG8_LDA(At, 0, 1); PG8_STAGE(PG8_SA(0, 0), a2, voffA);
;             PG8_BAR; PG8_WAIT_L(0); PG8_MMA(1, 0, At, B0); PG8_BAR; PG8_SCHED;
.LBB0_325:
	s_add_u32 s16, s14, 0x100
	s_addc_u32 s17, s15, 0
	s_add_i32 s46, 0, 0x10000
	v_add_u32_e32 v138, s46, v141
	ds_read_b128 v[128:131], v138
	ds_read_b128 v[144:147], v138 offset:1024
	ds_read_b128 v[148:151], v138 offset:2048
	ds_read_b128 v[152:155], v138 offset:3072
	s_cmp_eq_u32 s45, 12
	s_cselect_b32 s21, s7, s17
	s_cselect_b32 s20, s41, s16
	s_cselect_b32 s19, s5, s44
	s_cselect_b32 s18, s42, s43
	v_lshl_add_u64 v[138:139], s[14:15], 0, v[134:135]
	s_add_i32 m0, s13, 0xc000
	ds_read_b128 v[156:159], v143
	ds_read_b128 v[160:163], v143 offset:1024
	ds_read_b128 v[164:167], v143 offset:2048
	ds_read_b128 v[168:171], v143 offset:3072
	ds_read_b128 v[172:175], v143 offset:4096
	ds_read_b128 v[176:179], v143 offset:5120
	ds_read_b128 v[180:183], v143 offset:6144
	ds_read_b128 v[184:187], v143 offset:7168
	global_load_lds_dwordx4 v[138:139], off
	v_lshl_add_u64 v[138:139], s[14:15], 0, v[136:137]
	s_add_i32 m0, s13, 0xe000
	s_nop 0
	global_load_lds_dwordx4 v[138:139], off
	s_waitcnt lgkmcnt(8)
	s_barrier
	s_waitcnt lgkmcnt(0)
	s_waitcnt lgkmcnt(0)
	v_mfma_f32_16x16x32_bf16 v[124:127], v[128:131], v[156:159], v[124:127]
	v_mfma_f32_16x16x32_bf16 v[92:95], v[148:151], v[156:159], v[92:95]
	v_mfma_f32_16x16x32_bf16 v[120:123], v[128:131], v[164:167], v[120:123]
	v_mfma_f32_16x16x32_bf16 v[88:91], v[148:151], v[164:167], v[88:91]
	v_mfma_f32_16x16x32_bf16 v[116:119], v[128:131], v[172:175], v[116:119]
	v_mfma_f32_16x16x32_bf16 v[84:87], v[148:151], v[172:175], v[84:87]
	v_mfma_f32_16x16x32_bf16 v[112:115], v[128:131], v[180:183], v[112:115]
	v_mfma_f32_16x16x32_bf16 v[80:83], v[148:151], v[180:183], v[80:83]
	v_mfma_f32_16x16x32_bf16 v[124:127], v[144:147], v[160:163], v[124:127]
	v_mfma_f32_16x16x32_bf16 v[92:95], v[152:155], v[160:163], v[92:95]
	v_mfma_f32_16x16x32_bf16 v[120:123], v[144:147], v[168:171], v[120:123]
	v_mfma_f32_16x16x32_bf16 v[88:91], v[152:155], v[168:171], v[88:91]
	v_mfma_f32_16x16x32_bf16 v[116:119], v[144:147], v[176:179], v[116:119]
	v_mfma_f32_16x16x32_bf16 v[84:87], v[152:155], v[176:179], v[84:87]
	v_mfma_f32_16x16x32_bf16 v[112:115], v[144:147], v[184:187], v[112:115]
	v_mfma_f32_16x16x32_bf16 v[80:83], v[152:155], v[184:187], v[80:83]
	s_barrier
	s_add_i32 s48, 0, 0x14000
	v_add_u32_e32 v138, s48, v141
	s_add_i32 s14, s46, s28
	ds_read_b128 v[188:191], v138
	ds_read_b128 v[194:197], v138 offset:1024
	ds_read_b128 v[200:203], v138 offset:2048
	ds_read_b128 v[204:207], v138 offset:3072
	v_lshl_add_u64 v[138:139], s[18:19], 0, v[192:193]
	s_mov_b32 m0, s14
	v_lshl_add_u64 v[208:209], s[18:19], 0, v[132:133]
	global_load_lds_dwordx4 v[138:139], off
	s_add_i32 m0, s14, 0x2000
	s_nop 0
	global_load_lds_dwordx4 v[208:209], off
	s_barrier
	s_waitcnt lgkmcnt(0)
	s_waitcnt lgkmcnt(0)
	v_mfma_f32_16x16x32_bf16 v[60:63], v[188:191], v[156:159], v[60:63]
	v_mfma_f32_16x16x32_bf16 v[28:31], v[200:203], v[156:159], v[28:31]
	v_mfma_f32_16x16x32_bf16 v[56:59], v[188:191], v[164:167], v[56:59]
	v_mfma_f32_16x16x32_bf16 v[24:27], v[200:203], v[164:167], v[24:27]
	v_mfma_f32_16x16x32_bf16 v[52:55], v[188:191], v[172:175], v[52:55]
	v_mfma_f32_16x16x32_bf16 v[20:23], v[200:203], v[172:175], v[20:23]
	v_mfma_f32_16x16x32_bf16 v[48:51], v[188:191], v[180:183], v[48:51]
	v_mfma_f32_16x16x32_bf16 v[16:19], v[200:203], v[180:183], v[16:19]
	v_mfma_f32_16x16x32_bf16 v[60:63], v[194:197], v[160:163], v[60:63]
	v_mfma_f32_16x16x32_bf16 v[28:31], v[204:207], v[160:163], v[28:31]
	v_mfma_f32_16x16x32_bf16 v[56:59], v[194:197], v[168:171], v[56:59]
	v_mfma_f32_16x16x32_bf16 v[24:27], v[204:207], v[168:171], v[24:27]
	v_mfma_f32_16x16x32_bf16 v[52:55], v[194:197], v[176:179], v[52:55]
	v_mfma_f32_16x16x32_bf16 v[20:23], v[204:207], v[176:179], v[20:23]
	v_mfma_f32_16x16x32_bf16 v[48:51], v[194:197], v[184:187], v[48:51]
	v_mfma_f32_16x16x32_bf16 v[16:19], v[204:207], v[184:187], v[16:19]
	s_mov_b32 m0, s13
	v_lshl_add_u64 v[210:211], s[20:21], 0, v[192:193]
	s_barrier
	ds_read_b128 v[156:159], v143 offset:16384
	ds_read_b128 v[160:163], v143 offset:17408
	ds_read_b128 v[164:167], v143 offset:18432
	ds_read_b128 v[168:171], v143 offset:19456
	ds_read_b128 v[172:175], v143 offset:20480
	ds_read_b128 v[176:179], v143 offset:21504
	ds_read_b128 v[180:183], v143 offset:22528
	ds_read_b128 v[184:187], v143 offset:23552
	global_load_lds_dwordx4 v[210:211], off
	v_lshl_add_u64 v[212:213], s[20:21], 0, v[132:133]
	s_mov_b32 m0, s29
	s_nop 0
	global_load_lds_dwordx4 v[212:213], off
	s_barrier
	s_waitcnt lgkmcnt(0)
	s_waitcnt lgkmcnt(0)
	v_mfma_f32_16x16x32_bf16 v[108:111], v[128:131], v[156:159], v[108:111]
	v_mfma_f32_16x16x32_bf16 v[76:79], v[148:151], v[156:159], v[76:79]
	v_mfma_f32_16x16x32_bf16 v[104:107], v[128:131], v[164:167], v[104:107]
	v_mfma_f32_16x16x32_bf16 v[72:75], v[148:151], v[164:167], v[72:75]
	v_mfma_f32_16x16x32_bf16 v[100:103], v[128:131], v[172:175], v[100:103]
	v_mfma_f32_16x16x32_bf16 v[68:71], v[148:151], v[172:175], v[68:71]
	v_mfma_f32_16x16x32_bf16 v[96:99], v[128:131], v[180:183], v[96:99]
	v_mfma_f32_16x16x32_bf16 v[64:67], v[148:151], v[180:183], v[64:67]
	v_mfma_f32_16x16x32_bf16 v[108:111], v[144:147], v[160:163], v[108:111]
	v_mfma_f32_16x16x32_bf16 v[76:79], v[152:155], v[160:163], v[76:79]
	v_mfma_f32_16x16x32_bf16 v[104:107], v[144:147], v[168:171], v[104:107]
	v_mfma_f32_16x16x32_bf16 v[72:75], v[152:155], v[168:171], v[72:75]
	v_mfma_f32_16x16x32_bf16 v[100:103], v[144:147], v[176:179], v[100:103]
	v_mfma_f32_16x16x32_bf16 v[68:71], v[152:155], v[176:179], v[68:71]
	v_mfma_f32_16x16x32_bf16 v[96:99], v[144:147], v[184:187], v[96:99]
	v_mfma_f32_16x16x32_bf16 v[64:67], v[152:155], v[184:187], v[64:67]
	s_barrier
; #define PG8_STAGE(bufoff, gbase, voff) do { _Pragma("unroll") for (int _i = 0; _i < 2; ++_i) \
;         __builtin_amdgcn_global_load_lds((const unsigned*)((const char*)(gbase) + (voff)[_i]), (PG8_LAS unsigned*)(lds + (bufoff) + ldsw + _i * 8192), 16, 0, 0); } while (0)
; #define PG8_LDA(dst, b, h) do { _Pragma("unroll") for (int m = 0; m < 4; ++m) _Pragma("unroll") for (int k = 0; k < 2; ++k) dst[m][k] = *(const PG8_LAS bf16x8*)(lds + PG8_SA(b, h) + aoff + m * 2048 + k * 1024); } while (0)
; #define PG8_LDB(dst, b, h) do { _Pragma("unroll") for (int n = 0; n < 2; ++n) _Pragma("unroll") for (int k = 0; k < 2; ++k) dst[n][k] = *(const PG8_LAS bf16x8*)(lds + PG8_SB(b, h) + boff + n * 2048 + k * 1024); } while (0)
; #define PG8_MMA(ai, bj, At, Bt) do { __builtin_amdgcn_s_setprio(1); _Pragma("unroll") for (int m = 0; m < 4; ++m) _Pragma("unroll") for (int n = 0; n < 2; ++n) _Pragma("unroll") for (int k = 0; k < 2; ++k) \
;         acc[ai][bj][m][n] = __builtin_amdgcn_mfma_f32_16x16x32_bf16(Bt[n][k], At[m][k], acc[ai][bj][m][n], 0, 0, 0); __builtin_amdgcn_s_setprio(0); } while (0)
; #define PG8_WAIT_V(n) asm volatile("s_waitcnt vmcnt(" #n ")" ::: "memory")
; #define PG8_WAIT_L(n) asm volatile("s_waitcnt lgkmcnt(" #n ")" ::: "memory")
; #define PG8_BAR __builtin_amdgcn_s_barrier()
; #define PG8_SCHED __builtin_amdgcn_sched_barrier(0)
; template <class Epi, class Sched>
; __device__ __forceinline__ void gemm_phase(PG8_LAS unsigned char* lds, const Gemm g, const Sched& S, const Epi& E, int tid_in) {
;     ...
;             PG8_STAGE(PG8_SB(0, 1), b2 + hstep, voffB);
;             PG8_WAIT_V(6); PG8_BAR; PG8_MMA(1, 1, At, B1); PG8_BAR;
;             PG8_LDB(B0, 1, 0); PG8_SCHED; PG8_LDA(At, 1, 0); PG8_STAGE(PG8_SA(0, 1), a2 + hstep, voffA);
;             PG8_WAIT_L(8); PG8_BAR; PG8_WAIT_L(0); PG8_MMA(0, 0, At, B0); PG8_BAR; PG8_SCHED;
;             PG8_LDB(B1, 1, 1); PG8_STAGE(PG8_SB(1, 0), b3, voffB);
;             PG8_BAR; PG8_WAIT_L(0); PG8_MMA(0, 1, At, B1); PG8_BAR;
;             PG8_LDA(At, 1, 1); PG8_STAGE(PG8_SA(1, 0), a3, voffA);
;             PG8_BAR; PG8_WAIT_L(0); PG8_MMA(1, 0, At, B0); PG8_BAR; PG8_SCHED;
	s_add_u32 s14, s18, 0x40000
	s_addc_u32 s15, s19, 0
	s_add_i32 s46, s48, s28
	v_lshl_add_u64 v[128:129], s[14:15], 0, v[192:193]
	s_mov_b32 m0, s46
	s_nop 0
	global_load_lds_dwordx4 v[128:129], off
	v_lshl_add_u64 v[128:129], s[14:15], 0, v[132:133]
	s_add_i32 m0, s46, 0x2000
	s_nop 0
	global_load_lds_dwordx4 v[128:129], off
	s_waitcnt vmcnt(6)
	s_barrier
	v_mfma_f32_16x16x32_bf16 v[44:47], v[188:191], v[156:159], v[44:47]
	v_mfma_f32_16x16x32_bf16 v[12:15], v[200:203], v[156:159], v[12:15]
	v_mfma_f32_16x16x32_bf16 v[40:43], v[188:191], v[164:167], v[40:43]
	v_mfma_f32_16x16x32_bf16 v[8:11], v[200:203], v[164:167], v[8:11]
	v_mfma_f32_16x16x32_bf16 v[36:39], v[188:191], v[172:175], v[36:39]
	v_mfma_f32_16x16x32_bf16 v[4:7], v[200:203], v[172:175], v[4:7]
	v_mfma_f32_16x16x32_bf16 v[32:35], v[188:191], v[180:183], v[32:35]
	v_mfma_f32_16x16x32_bf16 v[0:3], v[200:203], v[180:183], v[0:3]
	v_mfma_f32_16x16x32_bf16 v[44:47], v[194:197], v[160:163], v[44:47]
	v_mfma_f32_16x16x32_bf16 v[12:15], v[204:207], v[160:163], v[12:15]
	v_mfma_f32_16x16x32_bf16 v[40:43], v[194:197], v[168:171], v[40:43]
	v_mfma_f32_16x16x32_bf16 v[8:11], v[204:207], v[168:171], v[8:11]
	v_mfma_f32_16x16x32_bf16 v[36:39], v[194:197], v[176:179], v[36:39]
	v_mfma_f32_16x16x32_bf16 v[4:7], v[204:207], v[176:179], v[4:7]
	v_mfma_f32_16x16x32_bf16 v[32:35], v[194:197], v[184:187], v[32:35]
	v_mfma_f32_16x16x32_bf16 v[0:3], v[204:207], v[184:187], v[0:3]
	s_add_i32 s46, 0, 0x18000
	v_add_u32_e32 v152, s46, v141
	s_barrier
	ds_read_b128 v[128:131], v152
	ds_read_b128 v[144:147], v152 offset:1024
	ds_read_b128 v[148:151], v152 offset:2048
	ds_read_b128 v[152:155], v152 offset:3072
	s_add_u32 s14, s20, 0x40000
	s_addc_u32 s15, s21, 0
	s_mov_b32 m0, s30
	v_lshl_add_u64 v[188:189], s[14:15], 0, v[192:193]
	ds_read_b128 v[156:159], v143 offset:32768
	ds_read_b128 v[160:163], v143 offset:33792
	ds_read_b128 v[164:167], v143 offset:34816
	ds_read_b128 v[168:171], v143 offset:35840
	ds_read_b128 v[172:175], v143 offset:36864
	ds_read_b128 v[176:179], v143 offset:37888
	ds_read_b128 v[180:183], v143 offset:38912
	ds_read_b128 v[184:187], v143 offset:39936
	global_load_lds_dwordx4 v[188:189], off
	v_lshl_add_u64 v[188:189], s[14:15], 0, v[132:133]
	s_mov_b32 m0, s31
	s_nop 0
	global_load_lds_dwordx4 v[188:189], off
	s_waitcnt lgkmcnt(8)
	s_barrier
	s_waitcnt lgkmcnt(0)
	s_waitcnt lgkmcnt(0)
	v_mfma_f32_16x16x32_bf16 v[124:127], v[128:131], v[156:159], v[124:127]
	v_mfma_f32_16x16x32_bf16 v[92:95], v[148:151], v[156:159], v[92:95]
	v_mfma_f32_16x16x32_bf16 v[120:123], v[128:131], v[164:167], v[120:123]
	v_mfma_f32_16x16x32_bf16 v[88:91], v[148:151], v[164:167], v[88:91]
	v_mfma_f32_16x16x32_bf16 v[116:119], v[128:131], v[172:175], v[116:119]
	v_mfma_f32_16x16x32_bf16 v[84:87], v[148:151], v[172:175], v[84:87]
	v_mfma_f32_16x16x32_bf16 v[112:115], v[128:131], v[180:183], v[112:115]
	v_mfma_f32_16x16x32_bf16 v[80:83], v[148:151], v[180:183], v[80:83]
	v_mfma_f32_16x16x32_bf16 v[124:127], v[144:147], v[160:163], v[124:127]
	v_mfma_f32_16x16x32_bf16 v[92:95], v[152:155], v[160:163], v[92:95]
	v_mfma_f32_16x16x32_bf16 v[120:123], v[144:147], v[168:171], v[120:123]
	v_mfma_f32_16x16x32_bf16 v[88:91], v[152:155], v[168:171], v[88:91]
	v_mfma_f32_16x16x32_bf16 v[116:119], v[144:147], v[176:179], v[116:119]
	v_mfma_f32_16x16x32_bf16 v[84:87], v[152:155], v[176:179], v[84:87]
	v_mfma_f32_16x16x32_bf16 v[112:115], v[144:147], v[184:187], v[112:115]
	v_mfma_f32_16x16x32_bf16 v[80:83], v[152:155], v[184:187], v[80:83]
	s_barrier
	s_add_i32 s20, 0, 0x1c000
	s_add_i32 s14, s46, s28
	v_add_u32_e32 v199, s20, v141
	v_lshl_add_u64 v[138:139], v[138:139], 0, s[74:75]
	s_mov_b32 m0, s14
	ds_read_b128 v[188:191], v199
	ds_read_b128 v[194:197], v199 offset:1024
	ds_read_b128 v[200:203], v199 offset:2048
	ds_read_b128 v[204:207], v199 offset:3072
	global_load_lds_dwordx4 v[138:139], off
	v_lshl_add_u64 v[138:139], v[208:209], 0, s[74:75]
	s_add_i32 m0, s14, 0x2000
	s_nop 0
	global_load_lds_dwordx4 v[138:139], off
	s_barrier
	s_waitcnt lgkmcnt(0)
	s_waitcnt lgkmcnt(0)
	v_mfma_f32_16x16x32_bf16 v[60:63], v[188:191], v[156:159], v[60:63]
	v_mfma_f32_16x16x32_bf16 v[28:31], v[200:203], v[156:159], v[28:31]
	v_mfma_f32_16x16x32_bf16 v[56:59], v[188:191], v[164:167], v[56:59]
	v_mfma_f32_16x16x32_bf16 v[24:27], v[200:203], v[164:167], v[24:27]
	v_mfma_f32_16x16x32_bf16 v[52:55], v[188:191], v[172:175], v[52:55]
	v_mfma_f32_16x16x32_bf16 v[20:23], v[200:203], v[172:175], v[20:23]
	v_mfma_f32_16x16x32_bf16 v[48:51], v[188:191], v[180:183], v[48:51]
	v_mfma_f32_16x16x32_bf16 v[16:19], v[200:203], v[180:183], v[16:19]
	v_mfma_f32_16x16x32_bf16 v[60:63], v[194:197], v[160:163], v[60:63]
	v_mfma_f32_16x16x32_bf16 v[28:31], v[204:207], v[160:163], v[28:31]
	v_mfma_f32_16x16x32_bf16 v[56:59], v[194:197], v[168:171], v[56:59]
	v_mfma_f32_16x16x32_bf16 v[24:27], v[204:207], v[168:171], v[24:27]
	v_mfma_f32_16x16x32_bf16 v[52:55], v[194:197], v[176:179], v[52:55]
	v_mfma_f32_16x16x32_bf16 v[20:23], v[204:207], v[176:179], v[20:23]
	v_mfma_f32_16x16x32_bf16 v[48:51], v[194:197], v[184:187], v[48:51]
	v_mfma_f32_16x16x32_bf16 v[16:19], v[204:207], v[184:187], v[16:19]
	s_mov_b32 m0, s38
	v_lshl_add_u64 v[138:139], v[210:211], 0, s[74:75]
	s_barrier
	ds_read_b128 v[156:159], v143 offset:49152
	ds_read_b128 v[160:163], v143 offset:50176
	ds_read_b128 v[164:167], v143 offset:51200
	ds_read_b128 v[168:171], v143 offset:52224
	ds_read_b128 v[172:175], v143 offset:53248
	ds_read_b128 v[176:179], v143 offset:54272
	ds_read_b128 v[180:183], v143 offset:55296
	ds_read_b128 v[184:187], v143 offset:56320
	global_load_lds_dwordx4 v[138:139], off
	v_lshl_add_u64 v[138:139], v[212:213], 0, s[74:75]
	s_mov_b32 m0, s39
	s_nop 0
	global_load_lds_dwordx4 v[138:139], off
	s_barrier
; __device__ __forceinline__ unsigned cvt_pk_bf16(float lo, float hi) { unsigned r; asm volatile("s_nop 0\n\tv_cvt_pk_bf16_f32 %0, %1, %2\n\ts_nop 1" : "=v"(r) : "v"(lo), "v"(hi)); return r; }
; #define PG8_STAGE(bufoff, gbase, voff) do { _Pragma("unroll") for (int _i = 0; _i < 2; ++_i) \
;         __builtin_amdgcn_global_load_lds((const unsigned*)((const char*)(gbase) + (voff)[_i]), (PG8_LAS unsigned*)(lds + (bufoff) + ldsw + _i * 8192), 16, 0, 0); } while (0)
; #define PG8_MMA(ai, bj, At, Bt) do { __builtin_amdgcn_s_setprio(1); _Pragma("unroll") for (int m = 0; m < 4; ++m) _Pragma("unroll") for (int n = 0; n < 2; ++n) _Pragma("unroll") for (int k = 0; k < 2; ++k) \
;         acc[ai][bj][m][n] = __builtin_amdgcn_mfma_f32_16x16x32_bf16(Bt[n][k], At[m][k], acc[ai][bj][m][n], 0, 0, 0); __builtin_amdgcn_s_setprio(0); } while (0)
; #define PG8_WAIT_V(n) asm volatile("s_waitcnt vmcnt(" #n ")" ::: "memory")
; #define PG8_WAIT_L(n) asm volatile("s_waitcnt lgkmcnt(" #n ")" ::: "memory")
; #define PG8_BAR __builtin_amdgcn_s_barrier()
; template <class Epi, class Sched>
; __device__ __forceinline__ void gemm_phase(PG8_LAS unsigned char* lds, const Gemm g, const Sched& S, const Epi& E, int tid_in) {
;     ...
;             PG8_BAR; PG8_WAIT_L(0); PG8_MMA(1, 0, At, B0); PG8_BAR; PG8_SCHED;
;             PG8_STAGE(PG8_SB(1, 1), b3 + hstep, voffB);
;             PG8_WAIT_V(6); PG8_BAR; PG8_MMA(1, 1, At, B1); PG8_BAR;
;     __device__ __forceinline__ void operator()(f32x4 (&acc)[2][2][4][2], const Unit& u, int wr, int wc, int fr, int fq) const {
;         const int row0 = u.pm * 256 + wr * 64 + fr, col0 = u.pn * 256 + wc * 32 + 4 * fq;
;         const float* gr = gate + (size_t)(bbase + (u.pm * 256) / SEQ) * MODW;
; #pragma unroll
;         for (int bj = 0; bj < 2; ++bj)
; #pragma unroll
;             for (int n = 0; n < 2; ++n) { const int col = col0 + bj * 128 + n * 16; const f32x4 gv = *(const f32x4*)(gr + col);
;                 f32x4 bv = (f32x4){0.f, 0.f, 0.f, 0.f}; if (bias) bv = *(const f32x4*)(bias + col);
; #pragma unroll
;                 for (int ai = 0; ai < 2; ++ai)
; #pragma unroll
;                     for (int m = 0; m < 4; ++m) { const size_t row = row0 + ai * 128 + m * 16;
;                         const f32x4 o = gv * (acc[ai][bj][m][n] + bv); u32x2 w; w.x = cvt_pk_bf16(o[0], o[1]); w.y = cvt_pk_bf16(o[2], o[3]);
	s_waitcnt lgkmcnt(0)
	s_waitcnt lgkmcnt(0)
	v_mfma_f32_16x16x32_bf16 v[108:111], v[128:131], v[156:159], v[108:111]
	v_mfma_f32_16x16x32_bf16 v[76:79], v[148:151], v[156:159], v[76:79]
	v_mfma_f32_16x16x32_bf16 v[104:107], v[128:131], v[164:167], v[104:107]
	v_mfma_f32_16x16x32_bf16 v[72:75], v[148:151], v[164:167], v[72:75]
	v_mfma_f32_16x16x32_bf16 v[100:103], v[128:131], v[172:175], v[100:103]
	v_mfma_f32_16x16x32_bf16 v[68:71], v[148:151], v[172:175], v[68:71]
	v_mfma_f32_16x16x32_bf16 v[96:99], v[128:131], v[180:183], v[96:99]
	v_mfma_f32_16x16x32_bf16 v[64:67], v[148:151], v[180:183], v[64:67]
	v_mfma_f32_16x16x32_bf16 v[108:111], v[144:147], v[160:163], v[108:111]
	v_mfma_f32_16x16x32_bf16 v[76:79], v[152:155], v[160:163], v[76:79]
	v_mfma_f32_16x16x32_bf16 v[104:107], v[144:147], v[168:171], v[104:107]
	v_mfma_f32_16x16x32_bf16 v[72:75], v[152:155], v[168:171], v[72:75]
	v_mfma_f32_16x16x32_bf16 v[100:103], v[144:147], v[176:179], v[100:103]
	v_mfma_f32_16x16x32_bf16 v[68:71], v[152:155], v[176:179], v[68:71]
	v_mfma_f32_16x16x32_bf16 v[96:99], v[144:147], v[184:187], v[96:99]
	v_mfma_f32_16x16x32_bf16 v[64:67], v[152:155], v[184:187], v[64:67]
	s_barrier
	s_add_u32 s14, s18, 0x40080
	s_addc_u32 s15, s19, 0
	s_add_i32 s18, s20, s28
	v_lshl_add_u64 v[128:129], s[14:15], 0, v[192:193]
	s_mov_b32 m0, s18
	s_nop 0
	global_load_lds_dwordx4 v[128:129], off
	v_lshl_add_u64 v[128:129], s[14:15], 0, v[132:133]
	s_add_i32 m0, s18, 0x2000
	s_nop 0
	global_load_lds_dwordx4 v[128:129], off
	s_waitcnt vmcnt(6)
	s_barrier
	v_mfma_f32_16x16x32_bf16 v[44:47], v[188:191], v[156:159], v[44:47]
	v_mfma_f32_16x16x32_bf16 v[12:15], v[200:203], v[156:159], v[12:15]
	v_mfma_f32_16x16x32_bf16 v[40:43], v[188:191], v[164:167], v[40:43]
	v_mfma_f32_16x16x32_bf16 v[8:11], v[200:203], v[164:167], v[8:11]
	v_mfma_f32_16x16x32_bf16 v[36:39], v[188:191], v[172:175], v[36:39]
	v_mfma_f32_16x16x32_bf16 v[4:7], v[200:203], v[172:175], v[4:7]
	v_mfma_f32_16x16x32_bf16 v[32:35], v[188:191], v[180:183], v[32:35]
	v_mfma_f32_16x16x32_bf16 v[0:3], v[200:203], v[180:183], v[0:3]
	v_mfma_f32_16x16x32_bf16 v[44:47], v[194:197], v[160:163], v[44:47]
	v_mfma_f32_16x16x32_bf16 v[12:15], v[204:207], v[160:163], v[12:15]
	v_mfma_f32_16x16x32_bf16 v[40:43], v[194:197], v[168:171], v[40:43]
	v_mfma_f32_16x16x32_bf16 v[8:11], v[204:207], v[168:171], v[8:11]
	v_mfma_f32_16x16x32_bf16 v[36:39], v[194:197], v[176:179], v[36:39]
	v_mfma_f32_16x16x32_bf16 v[4:7], v[204:207], v[176:179], v[4:7]
	v_mfma_f32_16x16x32_bf16 v[32:35], v[194:197], v[184:187], v[32:35]
	v_mfma_f32_16x16x32_bf16 v[0:3], v[204:207], v[184:187], v[0:3]
	s_add_i32 s45, s45, 2
	s_add_u32 s43, s43, 0x100
	s_addc_u32 s44, s44, 0
	s_cmp_gt_u32 s45, 13
	s_mov_b64 s[14:15], s[16:17]
	s_barrier
	s_cbranch_scc0 .LBB0_325
	s_ashr_i32 s5, s12, 31
	s_lshr_b32 s5, s5, 29
	s_add_i32 s5, s12, s5
	s_ashr_i32 s5, s5, 3
	s_add_i32 s5, s5, s76
	s_mul_hi_i32 s7, s5, 0x6000
	s_mulk_i32 s5, 0x6000
	v_lshl_or_b32 v146, s33, 8, v142
	s_add_u32 s14, s36, s5
	s_addc_u32 s15, s37, s7
	v_ashrrev_i32_e32 v147, 31, v146
	v_lshl_add_u64 v[138:139], v[146:147], 2, s[14:15]
	global_load_dwordx4 v[128:131], v[138:139], off
	global_load_dwordx4 v[152:155], v[138:139], off offset:64
	global_load_dwordx4 v[156:159], v[138:139], off offset:512
	global_load_dwordx4 v[160:163], v[138:139], off offset:576
	v_lshl_add_u32 v144, s12, 8, v140
	v_pk_add_f32 v[124:125], v[124:125], 0 op_sel_hi:[1,0]
	v_ashrrev_i32_e32 v145, 31, v144
	v_pk_add_f32 v[126:127], v[126:127], 0 op_sel_hi:[1,0]
	v_pk_add_f32 v[120:121], v[120:121], 0 op_sel_hi:[1,0]
	v_pk_add_f32 v[122:123], v[122:123], 0 op_sel_hi:[1,0]
	v_pk_add_f32 v[116:117], v[116:117], 0 op_sel_hi:[1,0]
	v_pk_add_f32 v[118:119], v[118:119], 0 op_sel_hi:[1,0]
	v_pk_add_f32 v[112:113], v[112:113], 0 op_sel_hi:[1,0]
	v_pk_add_f32 v[114:115], v[114:115], 0 op_sel_hi:[1,0]
	v_pk_add_f32 v[110:111], v[110:111], 0 op_sel_hi:[1,0]
	v_pk_add_f32 v[108:109], v[108:109], 0 op_sel_hi:[1,0]
	v_pk_add_f32 v[106:107], v[106:107], 0 op_sel_hi:[1,0]
	v_pk_add_f32 v[104:105], v[104:105], 0 op_sel_hi:[1,0]
	v_pk_add_f32 v[102:103], v[102:103], 0 op_sel_hi:[1,0]
	v_pk_add_f32 v[100:101], v[100:101], 0 op_sel_hi:[1,0]
	v_pk_add_f32 v[98:99], v[98:99], 0 op_sel_hi:[1,0]
	v_pk_add_f32 v[96:97], v[96:97], 0 op_sel_hi:[1,0]
	s_mov_b32 s5, 0x58000
	s_mov_b64 s[14:15], 0x40000
	v_pk_add_f32 v[92:93], v[92:93], 0 op_sel_hi:[1,0]
	v_pk_add_f32 v[88:89], v[88:89], 0 op_sel_hi:[1,0]
	v_pk_add_f32 v[84:85], v[84:85], 0 op_sel_hi:[1,0]
	v_pk_add_f32 v[80:81], v[80:81], 0 op_sel_hi:[1,0]
	v_pk_add_f32 v[76:77], v[76:77], 0 op_sel_hi:[1,0]
	v_pk_add_f32 v[72:73], v[72:73], 0 op_sel_hi:[1,0]
	v_pk_add_f32 v[68:69], v[68:69], 0 op_sel_hi:[1,0]
	v_pk_add_f32 v[64:65], v[64:65], 0 op_sel_hi:[1,0]
	v_pk_add_f32 v[94:95], v[94:95], 0 op_sel_hi:[1,0]
	v_pk_add_f32 v[90:91], v[90:91], 0 op_sel_hi:[1,0]
	v_pk_add_f32 v[86:87], v[86:87], 0 op_sel_hi:[1,0]
	v_pk_add_f32 v[82:83], v[82:83], 0 op_sel_hi:[1,0]
	v_pk_add_f32 v[78:79], v[78:79], 0 op_sel_hi:[1,0]
	v_pk_add_f32 v[74:75], v[74:75], 0 op_sel_hi:[1,0]
	v_pk_add_f32 v[70:71], v[70:71], 0 op_sel_hi:[1,0]
	v_pk_add_f32 v[66:67], v[66:67], 0 op_sel_hi:[1,0]
	v_pk_add_f32 v[60:61], v[60:61], 0 op_sel_hi:[1,0]
	v_pk_add_f32 v[56:57], v[56:57], 0 op_sel_hi:[1,0]
	v_pk_add_f32 v[52:53], v[52:53], 0 op_sel_hi:[1,0]
	v_pk_add_f32 v[48:49], v[48:49], 0 op_sel_hi:[1,0]
	v_pk_add_f32 v[44:45], v[44:45], 0 op_sel_hi:[1,0]
	v_pk_add_f32 v[40:41], v[40:41], 0 op_sel_hi:[1,0]
	v_pk_add_f32 v[36:37], v[36:37], 0 op_sel_hi:[1,0]
	v_pk_add_f32 v[32:33], v[32:33], 0 op_sel_hi:[1,0]
	v_pk_add_f32 v[62:63], v[62:63], 0 op_sel_hi:[1,0]
	v_pk_add_f32 v[58:59], v[58:59], 0 op_sel_hi:[1,0]
	v_pk_add_f32 v[54:55], v[54:55], 0 op_sel_hi:[1,0]
	v_pk_add_f32 v[50:51], v[50:51], 0 op_sel_hi:[1,0]
	v_pk_add_f32 v[46:47], v[46:47], 0 op_sel_hi:[1,0]
	v_pk_add_f32 v[42:43], v[42:43], 0 op_sel_hi:[1,0]
	v_pk_add_f32 v[38:39], v[38:39], 0 op_sel_hi:[1,0]
	v_pk_add_f32 v[34:35], v[34:35], 0 op_sel_hi:[1,0]
	v_pk_add_f32 v[28:29], v[28:29], 0 op_sel_hi:[1,0]
	v_pk_add_f32 v[24:25], v[24:25], 0 op_sel_hi:[1,0]
	v_pk_add_f32 v[20:21], v[20:21], 0 op_sel_hi:[1,0]
	v_pk_add_f32 v[16:17], v[16:17], 0 op_sel_hi:[1,0]
	v_pk_add_f32 v[12:13], v[12:13], 0 op_sel_hi:[1,0]
	v_pk_add_f32 v[8:9], v[8:9], 0 op_sel_hi:[1,0]
	v_pk_add_f32 v[4:5], v[4:5], 0 op_sel_hi:[1,0]
	v_pk_add_f32 v[0:1], v[0:1], 0 op_sel_hi:[1,0]
	v_pk_add_f32 v[30:31], v[30:31], 0 op_sel_hi:[1,0]
	v_pk_add_f32 v[26:27], v[26:27], 0 op_sel_hi:[1,0]
	v_pk_add_f32 v[22:23], v[22:23], 0 op_sel_hi:[1,0]
	v_pk_add_f32 v[18:19], v[18:19], 0 op_sel_hi:[1,0]
	v_pk_add_f32 v[14:15], v[14:15], 0 op_sel_hi:[1,0]
	v_pk_add_f32 v[10:11], v[10:11], 0 op_sel_hi:[1,0]
	v_pk_add_f32 v[6:7], v[6:7], 0 op_sel_hi:[1,0]
	v_pk_add_f32 v[2:3], v[2:3], 0 op_sel_hi:[1,0]
	s_mov_b32 s33, s4
	s_mov_b32 s12, s6
	s_mov_b64 s[16:17], s[10:11]
	s_waitcnt vmcnt(0)
; __device__ __forceinline__ unsigned cvt_pk_bf16(float lo, float hi) { unsigned r; asm volatile("s_nop 0\n\tv_cvt_pk_bf16_f32 %0, %1, %2\n\ts_nop 1" : "=v"(r) : "v"(lo), "v"(hi)); return r; }
;     __device__ __forceinline__ void operator()(f32x4 (&acc)[2][2][4][2], const Unit& u, int wr, int wc, int fr, int fq) const {
;         const int row0 = u.pm * 256 + wr * 64 + fr, col0 = u.pn * 256 + wc * 32 + 4 * fq;
;         const float* gr = gate + (size_t)(bbase + (u.pm * 256) / SEQ) * MODW;
; #pragma unroll
;         for (int bj = 0; bj < 2; ++bj)
; #pragma unroll
;             for (int n = 0; n < 2; ++n) { const int col = col0 + bj * 128 + n * 16; const f32x4 gv = *(const f32x4*)(gr + col);
;                 f32x4 bv = (f32x4){0.f, 0.f, 0.f, 0.f}; if (bias) bv = *(const f32x4*)(bias + col);
; #pragma unroll
;                 for (int ai = 0; ai < 2; ++ai)
; #pragma unroll
;                     for (int m = 0; m < 4; ++m) { const size_t row = row0 + ai * 128 + m * 16;
;                         const f32x4 o = gv * (acc[ai][bj][m][n] + bv); u32x2 w; w.x = cvt_pk_bf16(o[0], o[1]); w.y = cvt_pk_bf16(o[2], o[3]);
;                         *(u32x2*)(O + row * 1024 + col) = w; } }
	v_pk_mul_f32 v[124:125], v[124:125], v[128:129]
	v_pk_mul_f32 v[126:127], v[126:127], v[130:131]
	v_cvt_pk_bf16_f32 v148, v124, v125
	v_lshlrev_b64 v[124:125], 11, v[144:145]
	v_cvt_pk_bf16_f32 v149, v126, v127
	v_lshl_add_u64 v[124:125], s[0:1], 0, v[124:125]
	v_lshlrev_b64 v[126:127], 1, v[146:147]
	v_or_b32_e32 v146, 16, v144
	v_lshl_add_u64 v[124:125], v[124:125], 0, v[126:127]
	v_ashrrev_i32_e32 v147, 31, v146
	v_pk_mul_f32 v[120:121], v[120:121], v[128:129]
	global_store_dwordx2 v[124:125], v[148:149], off
	v_pk_mul_f32 v[122:123], v[122:123], v[130:131]
	v_cvt_pk_bf16_f32 v148, v120, v121
	v_lshlrev_b64 v[120:121], 11, v[146:147]
	v_cvt_pk_bf16_f32 v149, v122, v123
	v_lshl_add_u64 v[120:121], s[0:1], 0, v[120:121]
	v_or_b32_e32 v122, 32, v144
	v_lshl_add_u64 v[120:121], v[120:121], 0, v[126:127]
	v_ashrrev_i32_e32 v123, 31, v122
	v_pk_mul_f32 v[116:117], v[116:117], v[128:129]
	global_store_dwordx2 v[120:121], v[148:149], off
	v_pk_mul_f32 v[118:119], v[118:119], v[130:131]
	v_cvt_pk_bf16_f32 v146, v116, v117
	v_lshlrev_b64 v[116:117], 11, v[122:123]
	v_cvt_pk_bf16_f32 v147, v118, v119
	v_lshl_add_u64 v[116:117], s[0:1], 0, v[116:117]
	v_or_b32_e32 v118, 48, v144
	v_lshl_add_u64 v[116:117], v[116:117], 0, v[126:127]
	v_ashrrev_i32_e32 v119, 31, v118
	v_pk_mul_f32 v[112:113], v[112:113], v[128:129]
	global_store_dwordx2 v[116:117], v[146:147], off
	v_cvt_pk_bf16_f32 v122, v112, v113
	v_lshlrev_b64 v[112:113], 11, v[118:119]
	v_lshl_add_u64 v[112:113], s[0:1], 0, v[112:113]
	v_pk_mul_f32 v[114:115], v[114:115], v[130:131]
	v_lshl_add_u64 v[112:113], v[112:113], 0, v[126:127]
	v_pk_mul_f32 v[110:111], v[110:111], v[130:131]
	v_cvt_pk_bf16_f32 v123, v114, v115
	global_store_dwordx2 v[112:113], v[122:123], off
	v_pk_mul_f32 v[108:109], v[108:109], v[128:129]
	v_pk_mul_f32 v[106:107], v[106:107], v[130:131]
	v_cvt_pk_bf16_f32 v114, v108, v109
	v_cvt_pk_bf16_f32 v115, v110, v111
	v_add_co_u32_e32 v110, vcc, s63, v124
	v_pk_mul_f32 v[104:105], v[104:105], v[128:129]
	s_nop 0
	v_addc_co_u32_e32 v111, vcc, 0, v125, vcc
	global_store_dwordx2 v[110:111], v[114:115], off
	v_cvt_pk_bf16_f32 v110, v104, v105
	v_cvt_pk_bf16_f32 v111, v106, v107
	v_add_co_u32_e32 v106, vcc, s66, v124
	v_pk_mul_f32 v[102:103], v[102:103], v[130:131]
	s_nop 0
	v_addc_co_u32_e32 v107, vcc, 0, v125, vcc
	global_store_dwordx2 v[106:107], v[110:111], off
	v_pk_mul_f32 v[100:101], v[100:101], v[128:129]
	v_pk_mul_f32 v[98:99], v[98:99], v[130:131]
	v_cvt_pk_bf16_f32 v106, v100, v101
	v_cvt_pk_bf16_f32 v107, v102, v103
	v_add_co_u32_e32 v102, vcc, s55, v124
	v_pk_mul_f32 v[96:97], v[96:97], v[128:129]
	s_nop 0
	v_addc_co_u32_e32 v103, vcc, 0, v125, vcc
	global_store_dwordx2 v[102:103], v[106:107], off
	v_cvt_pk_bf16_f32 v96, v96, v97
	v_cvt_pk_bf16_f32 v97, v98, v99
	v_add_co_u32_e32 v98, vcc, s5, v124
	v_lshl_add_u64 v[108:109], v[124:125], 0, s[14:15]
	s_nop 0
	v_addc_co_u32_e32 v99, vcc, 0, v125, vcc
	global_store_dwordx2 v[98:99], v[96:97], off
	s_nop 0
	v_mov_b32_e32 v96, v152
	v_mov_b32_e32 v97, v153
	v_mov_b32_e32 v98, v154
	v_mov_b32_e32 v99, v155
	s_mov_b64 s[14:15], 0x50000
	v_lshl_add_u64 v[100:101], v[124:125], 0, s[14:15]
	s_mov_b64 s[14:15], 0x58000
	v_lshl_add_u64 v[104:105], v[124:125], 0, s[64:65]
	v_lshl_add_u64 v[102:103], v[124:125], 0, s[14:15]
	s_and_b64 vcc, exec, s[2:3]
	s_mov_b64 s[14:15], s[8:9]
	v_pk_mul_f32 v[92:93], v[92:93], v[96:97]
	v_pk_mul_f32 v[88:89], v[88:89], v[96:97]
	v_pk_mul_f32 v[84:85], v[84:85], v[96:97]
	v_pk_mul_f32 v[80:81], v[80:81], v[96:97]
	v_pk_mul_f32 v[76:77], v[76:77], v[96:97]
	v_pk_mul_f32 v[72:73], v[72:73], v[96:97]
	v_pk_mul_f32 v[68:69], v[68:69], v[96:97]
	v_pk_mul_f32 v[64:65], v[64:65], v[96:97]
	v_pk_mul_f32 v[94:95], v[94:95], v[98:99]
	v_cvt_pk_bf16_f32 v92, v92, v93
	v_pk_mul_f32 v[90:91], v[90:91], v[98:99]
	v_cvt_pk_bf16_f32 v93, v94, v95
	global_store_dwordx2 v[124:125], v[92:93], off offset:32
	v_cvt_pk_bf16_f32 v88, v88, v89
	v_cvt_pk_bf16_f32 v89, v90, v91
	global_store_dwordx2 v[120:121], v[88:89], off offset:32
	v_pk_mul_f32 v[86:87], v[86:87], v[98:99]
	v_cvt_pk_bf16_f32 v84, v84, v85
	v_pk_mul_f32 v[82:83], v[82:83], v[98:99]
	v_cvt_pk_bf16_f32 v85, v86, v87
	global_store_dwordx2 v[116:117], v[84:85], off offset:32
	v_cvt_pk_bf16_f32 v80, v80, v81
	v_cvt_pk_bf16_f32 v81, v82, v83
	global_store_dwordx2 v[112:113], v[80:81], off offset:32
; __device__ __forceinline__ unsigned cvt_pk_bf16(float lo, float hi) { unsigned r; asm volatile("s_nop 0\n\tv_cvt_pk_bf16_f32 %0, %1, %2\n\ts_nop 1" : "=v"(r) : "v"(lo), "v"(hi)); return r; }
; #define PG8_WAIT_V(n) asm volatile("s_waitcnt vmcnt(" #n ")" ::: "memory")
; #define PG8_BAR __builtin_amdgcn_s_barrier()
; template <class Epi, class Sched>
; __device__ __forceinline__ void gemm_phase(PG8_LAS unsigned char* lds, const Gemm g, const Sched& S, const Epi& E, int tid_in) {
;     ...
;     PG8_WAIT_V(0);
;     if (wr == 0) PG8_BAR;
;     __device__ __forceinline__ void operator()(f32x4 (&acc)[2][2][4][2], const Unit& u, int wr, int wc, int fr, int fq) const {
;     ...
;         for (int bj = 0; bj < 2; ++bj)
; #pragma unroll
;             for (int n = 0; n < 2; ++n) { const int col = col0 + bj * 128 + n * 16; const f32x4 gv = *(const f32x4*)(gr + col);
;                 f32x4 bv = (f32x4){0.f, 0.f, 0.f, 0.f}; if (bias) bv = *(const f32x4*)(bias + col);
; #pragma unroll
;                 for (int ai = 0; ai < 2; ++ai)
; #pragma unroll
;                     for (int m = 0; m < 4; ++m) { const size_t row = row0 + ai * 128 + m * 16;
;                         const f32x4 o = gv * (acc[ai][bj][m][n] + bv); u32x2 w; w.x = cvt_pk_bf16(o[0], o[1]); w.y = cvt_pk_bf16(o[2], o[3]);
;                         *(u32x2*)(O + row * 1024 + col) = w; } }
	v_pk_mul_f32 v[78:79], v[78:79], v[98:99]
	v_cvt_pk_bf16_f32 v76, v76, v77
	v_pk_mul_f32 v[74:75], v[74:75], v[98:99]
	v_cvt_pk_bf16_f32 v77, v78, v79
	global_store_dwordx2 v[108:109], v[76:77], off offset:32
	v_cvt_pk_bf16_f32 v72, v72, v73
	v_cvt_pk_bf16_f32 v73, v74, v75
	global_store_dwordx2 v[104:105], v[72:73], off offset:32
	v_pk_mul_f32 v[70:71], v[70:71], v[98:99]
	v_cvt_pk_bf16_f32 v68, v68, v69
	v_pk_mul_f32 v[66:67], v[66:67], v[98:99]
	v_cvt_pk_bf16_f32 v69, v70, v71
	global_store_dwordx2 v[100:101], v[68:69], off offset:32
	v_cvt_pk_bf16_f32 v64, v64, v65
	v_cvt_pk_bf16_f32 v65, v66, v67
	global_store_dwordx2 v[102:103], v[64:65], off offset:32
	s_nop 0
	v_mov_b32_e32 v64, v156
	v_mov_b32_e32 v65, v157
	v_mov_b32_e32 v66, v158
	v_mov_b32_e32 v67, v159
	v_pk_mul_f32 v[60:61], v[60:61], v[64:65]
	v_pk_mul_f32 v[56:57], v[56:57], v[64:65]
	v_pk_mul_f32 v[52:53], v[52:53], v[64:65]
	v_pk_mul_f32 v[48:49], v[48:49], v[64:65]
	v_pk_mul_f32 v[44:45], v[44:45], v[64:65]
	v_pk_mul_f32 v[40:41], v[40:41], v[64:65]
	v_pk_mul_f32 v[36:37], v[36:37], v[64:65]
	v_pk_mul_f32 v[32:33], v[32:33], v[64:65]
	v_pk_mul_f32 v[62:63], v[62:63], v[66:67]
	v_cvt_pk_bf16_f32 v60, v60, v61
	v_pk_mul_f32 v[58:59], v[58:59], v[66:67]
	v_cvt_pk_bf16_f32 v61, v62, v63
	global_store_dwordx2 v[124:125], v[60:61], off offset:256
	v_cvt_pk_bf16_f32 v56, v56, v57
	v_cvt_pk_bf16_f32 v57, v58, v59
	global_store_dwordx2 v[120:121], v[56:57], off offset:256
	v_pk_mul_f32 v[54:55], v[54:55], v[66:67]
	v_cvt_pk_bf16_f32 v52, v52, v53
	v_pk_mul_f32 v[50:51], v[50:51], v[66:67]
	v_cvt_pk_bf16_f32 v53, v54, v55
	global_store_dwordx2 v[116:117], v[52:53], off offset:256
	v_cvt_pk_bf16_f32 v48, v48, v49
	v_cvt_pk_bf16_f32 v49, v50, v51
	global_store_dwordx2 v[112:113], v[48:49], off offset:256
	v_pk_mul_f32 v[46:47], v[46:47], v[66:67]
	v_cvt_pk_bf16_f32 v44, v44, v45
	v_pk_mul_f32 v[42:43], v[42:43], v[66:67]
	v_cvt_pk_bf16_f32 v45, v46, v47
	global_store_dwordx2 v[108:109], v[44:45], off offset:256
	v_cvt_pk_bf16_f32 v40, v40, v41
	v_cvt_pk_bf16_f32 v41, v42, v43
	global_store_dwordx2 v[104:105], v[40:41], off offset:256
	v_pk_mul_f32 v[38:39], v[38:39], v[66:67]
	v_cvt_pk_bf16_f32 v36, v36, v37
	v_pk_mul_f32 v[34:35], v[34:35], v[66:67]
	v_cvt_pk_bf16_f32 v37, v38, v39
	global_store_dwordx2 v[100:101], v[36:37], off offset:256
	v_cvt_pk_bf16_f32 v32, v32, v33
	v_cvt_pk_bf16_f32 v33, v34, v35
	global_store_dwordx2 v[102:103], v[32:33], off offset:256
	s_nop 0
	v_mov_b32_e32 v32, v160
	v_mov_b32_e32 v33, v161
	v_mov_b32_e32 v34, v162
	v_mov_b32_e32 v35, v163
	v_pk_mul_f32 v[28:29], v[28:29], v[32:33]
	v_pk_mul_f32 v[24:25], v[24:25], v[32:33]
	v_pk_mul_f32 v[20:21], v[20:21], v[32:33]
	v_pk_mul_f32 v[16:17], v[16:17], v[32:33]
	v_pk_mul_f32 v[12:13], v[12:13], v[32:33]
	v_pk_mul_f32 v[8:9], v[8:9], v[32:33]
	v_pk_mul_f32 v[4:5], v[4:5], v[32:33]
	v_pk_mul_f32 v[0:1], v[0:1], v[32:33]
	v_pk_mul_f32 v[30:31], v[30:31], v[34:35]
	v_cvt_pk_bf16_f32 v28, v28, v29
	v_pk_mul_f32 v[26:27], v[26:27], v[34:35]
	v_cvt_pk_bf16_f32 v29, v30, v31
	global_store_dwordx2 v[124:125], v[28:29], off offset:288
	v_cvt_pk_bf16_f32 v24, v24, v25
	v_cvt_pk_bf16_f32 v25, v26, v27
	global_store_dwordx2 v[120:121], v[24:25], off offset:288
	v_pk_mul_f32 v[22:23], v[22:23], v[34:35]
	v_cvt_pk_bf16_f32 v20, v20, v21
	v_pk_mul_f32 v[18:19], v[18:19], v[34:35]
	v_cvt_pk_bf16_f32 v21, v22, v23
	global_store_dwordx2 v[116:117], v[20:21], off offset:288
	v_cvt_pk_bf16_f32 v16, v16, v17
	v_cvt_pk_bf16_f32 v17, v18, v19
	global_store_dwordx2 v[112:113], v[16:17], off offset:288
	v_pk_mul_f32 v[14:15], v[14:15], v[34:35]
	v_cvt_pk_bf16_f32 v12, v12, v13
	v_pk_mul_f32 v[10:11], v[10:11], v[34:35]
	v_cvt_pk_bf16_f32 v13, v14, v15
	global_store_dwordx2 v[108:109], v[12:13], off offset:288
	v_cvt_pk_bf16_f32 v8, v8, v9
	v_cvt_pk_bf16_f32 v9, v10, v11
	global_store_dwordx2 v[104:105], v[8:9], off offset:288
	v_pk_mul_f32 v[6:7], v[6:7], v[34:35]
	v_cvt_pk_bf16_f32 v4, v4, v5
	v_pk_mul_f32 v[2:3], v[2:3], v[34:35]
	v_cvt_pk_bf16_f32 v5, v6, v7
	global_store_dwordx2 v[100:101], v[4:5], off offset:288
	v_cvt_pk_bf16_f32 v0, v0, v1
	v_cvt_pk_bf16_f32 v1, v2, v3
	s_nop 1
	global_store_dwordx2 v[102:103], v[0:1], off offset:288
	s_cbranch_vccz .LBB0_318
	s_waitcnt vmcnt(0)
	s_cmpk_gt_u32 s22, 0xff
	s_cbranch_scc1 .LBB0_329
	s_barrier

; #define PG8_STAGE(bufoff, gbase, voff) do { _Pragma("unroll") for (int _i = 0; _i < 2; ++_i) \
;         __builtin_amdgcn_global_load_lds((const unsigned*)((const char*)(gbase) + (voff)[_i]), (PG8_LAS unsigned*)(lds + (bufoff) + ldsw + _i * 8192), 16, 0, 0); } while (0)
; #define PG8_LDA(dst, b, h) do { _Pragma("unroll") for (int m = 0; m < 4; ++m) _Pragma("unroll") for (int k = 0; k < 2; ++k) dst[m][k] = *(const PG8_LAS bf16x8*)(lds + PG8_SA(b, h) + aoff + m * 2048 + k * 1024); } while (0)
; #define PG8_LDB(dst, b, h) do { _Pragma("unroll") for (int n = 0; n < 2; ++n) _Pragma("unroll") for (int k = 0; k < 2; ++k) dst[n][k] = *(const PG8_LAS bf16x8*)(lds + PG8_SB(b, h) + boff + n * 2048 + k * 1024); } while (0)
; #define PG8_MMA(ai, bj, At, Bt) do { __builtin_amdgcn_s_setprio(1); _Pragma("unroll") for (int m = 0; m < 4; ++m) _Pragma("unroll") for (int n = 0; n < 2; ++n) _Pragma("unroll") for (int k = 0; k < 2; ++k) \
;         acc[ai][bj][m][n] = __builtin_amdgcn_mfma_f32_16x16x32_bf16(Bt[n][k], At[m][k], acc[ai][bj][m][n], 0, 0, 0); __builtin_amdgcn_s_setprio(0); } while (0)
; #define PG8_WAIT_L(n) asm volatile("s_waitcnt lgkmcnt(" #n ")" ::: "memory")
; #define PG8_BAR __builtin_amdgcn_s_barrier()
; #define PG8_SCHED __builtin_amdgcn_sched_barrier(0)
; template <class Epi, class Sched>
; __device__ __forceinline__ void gemm_phase(PG8_LAS unsigned char* lds, const Gemm g, const Sched& S, const Epi& E, int tid_in) {
;     ...
;             const bool last = (t == nt - 2);
;             const char* a1 = cA + (size_t)(t + 1) * kstep;
;             const char* a2 = last ? nA : cA + (size_t)(t + 2) * kstep; const char* b2 = last ? nB : cB + (size_t)(t + 2) * kstep;
;             const char* a3 = a2 + kstep; const char* b3 = b2 + kstep;
;             if (last && has_next) S.a_ready(nxt);
;             PG8_LDB(B0, 0, 0); PG8_SCHED; PG8_LDA(At, 0, 0); PG8_STAGE(PG8_SA(1, 1), a1 + hstep, voffA);
;             PG8_WAIT_L(8); PG8_BAR; PG8_WAIT_L(0); PG8_MMA(0, 0, At, B0); PG8_BAR; PG8_SCHED;
;             PG8_LDB(B1, 0, 1); PG8_STAGE(PG8_SB(0, 0), b2, voffB);
;             PG8_BAR; PG8_WAIT_L(0); PG8_MMA(0, 1, At, B1); PG8_BAR;
;             PG8_LDA(At, 0, 1); PG8_STAGE(PG8_SA(0, 0), a2, voffA);
;             PG8_BAR; PG8_WAIT_L(0); PG8_MMA(1, 0, At, B0); PG8_BAR; PG8_SCHED;
.LBB0_350:
	s_add_u32 s20, s18, 0xfff80080
	s_addc_u32 s21, s19, -1
	s_add_i32 s46, 0, 0x10000
	v_add_u32_e32 v146, s46, v171
	ds_read_b128 v[134:137], v146
	ds_read_b128 v[138:141], v146 offset:1024
	ds_read_b128 v[142:145], v146 offset:2048
	ds_read_b128 v[146:149], v146 offset:3072
	s_cmp_eq_u32 s45, 28
	s_cselect_b32 s23, s11, s21
	s_cselect_b32 s22, s41, s20
	s_cselect_b32 s21, s9, s44
	s_cselect_b32 s20, s42, s43
	v_lshl_add_u64 v[186:187], s[18:19], 0, v[130:131]
	s_add_i32 m0, s17, 0xc000
	ds_read_b128 v[150:153], v173
	ds_read_b128 v[154:157], v173 offset:1024
	ds_read_b128 v[158:161], v173 offset:2048
	ds_read_b128 v[162:165], v173 offset:3072
	ds_read_b128 v[166:169], v173 offset:4096
	ds_read_b128 v[174:177], v173 offset:5120
	ds_read_b128 v[178:181], v173 offset:6144
	ds_read_b128 v[182:185], v173 offset:7168
	global_load_lds_dwordx4 v[186:187], off
	v_lshl_add_u64 v[186:187], s[18:19], 0, v[132:133]
	s_add_i32 m0, s17, 0xe000
	s_nop 0
	global_load_lds_dwordx4 v[186:187], off
	s_waitcnt lgkmcnt(8)
	s_barrier
	s_waitcnt lgkmcnt(0)
	s_waitcnt lgkmcnt(0)
	v_mfma_f32_16x16x32_bf16 v[124:127], v[134:137], v[150:153], v[124:127]
	v_mfma_f32_16x16x32_bf16 v[120:123], v[142:145], v[150:153], v[120:123]
	v_mfma_f32_16x16x32_bf16 v[108:111], v[134:137], v[158:161], v[108:111]
	v_mfma_f32_16x16x32_bf16 v[104:107], v[142:145], v[158:161], v[104:107]
	v_mfma_f32_16x16x32_bf16 v[96:99], v[134:137], v[166:169], v[96:99]
	v_mfma_f32_16x16x32_bf16 v[88:91], v[142:145], v[166:169], v[88:91]
	v_mfma_f32_16x16x32_bf16 v[80:83], v[134:137], v[178:181], v[80:83]
	v_mfma_f32_16x16x32_bf16 v[72:75], v[142:145], v[178:181], v[72:75]
	v_mfma_f32_16x16x32_bf16 v[124:127], v[138:141], v[154:157], v[124:127]
	v_mfma_f32_16x16x32_bf16 v[120:123], v[146:149], v[154:157], v[120:123]
	v_mfma_f32_16x16x32_bf16 v[108:111], v[138:141], v[162:165], v[108:111]
	v_mfma_f32_16x16x32_bf16 v[104:107], v[146:149], v[162:165], v[104:107]
	v_mfma_f32_16x16x32_bf16 v[96:99], v[138:141], v[174:177], v[96:99]
	v_mfma_f32_16x16x32_bf16 v[88:91], v[146:149], v[174:177], v[88:91]
	v_mfma_f32_16x16x32_bf16 v[80:83], v[138:141], v[182:185], v[80:83]
	v_mfma_f32_16x16x32_bf16 v[72:75], v[146:149], v[182:185], v[72:75]
	s_barrier
	s_add_i32 s50, 0, 0x14000
	v_add_u32_e32 v190, s50, v171
	s_add_i32 s46, s46, s30
	ds_read_b128 v[186:189], v190
	ds_read_b128 v[194:197], v190 offset:1024
	ds_read_b128 v[200:203], v190 offset:2048
	ds_read_b128 v[204:207], v190 offset:3072
	v_lshl_add_u64 v[190:191], s[20:21], 0, v[192:193]
	s_mov_b32 m0, s46
	v_lshl_add_u64 v[208:209], s[20:21], 0, v[128:129]
	global_load_lds_dwordx4 v[190:191], off
	s_add_i32 m0, s46, 0x2000
	s_nop 0
	global_load_lds_dwordx4 v[208:209], off
	s_barrier
	s_waitcnt lgkmcnt(0)
	s_waitcnt lgkmcnt(0)
	v_mfma_f32_16x16x32_bf16 v[116:119], v[186:189], v[150:153], v[116:119]
	v_mfma_f32_16x16x32_bf16 v[112:115], v[200:203], v[150:153], v[112:115]
	v_mfma_f32_16x16x32_bf16 v[100:103], v[186:189], v[158:161], v[100:103]
	v_mfma_f32_16x16x32_bf16 v[92:95], v[200:203], v[158:161], v[92:95]
	v_mfma_f32_16x16x32_bf16 v[84:87], v[186:189], v[166:169], v[84:87]
	v_mfma_f32_16x16x32_bf16 v[76:79], v[200:203], v[166:169], v[76:79]
	v_mfma_f32_16x16x32_bf16 v[68:71], v[186:189], v[178:181], v[68:71]
	v_mfma_f32_16x16x32_bf16 v[64:67], v[200:203], v[178:181], v[64:67]
	v_mfma_f32_16x16x32_bf16 v[116:119], v[194:197], v[154:157], v[116:119]
	v_mfma_f32_16x16x32_bf16 v[112:115], v[204:207], v[154:157], v[112:115]
	v_mfma_f32_16x16x32_bf16 v[100:103], v[194:197], v[162:165], v[100:103]
	v_mfma_f32_16x16x32_bf16 v[92:95], v[204:207], v[162:165], v[92:95]
	v_mfma_f32_16x16x32_bf16 v[84:87], v[194:197], v[174:177], v[84:87]
	v_mfma_f32_16x16x32_bf16 v[76:79], v[204:207], v[174:177], v[76:79]
	v_mfma_f32_16x16x32_bf16 v[68:71], v[194:197], v[182:185], v[68:71]
	v_mfma_f32_16x16x32_bf16 v[64:67], v[204:207], v[182:185], v[64:67]
	s_mov_b32 m0, s17
	v_lshl_add_u64 v[210:211], s[22:23], 0, v[192:193]
	s_barrier
	ds_read_b128 v[150:153], v173 offset:16384
	ds_read_b128 v[154:157], v173 offset:17408
	ds_read_b128 v[158:161], v173 offset:18432
	ds_read_b128 v[162:165], v173 offset:19456
	ds_read_b128 v[166:169], v173 offset:20480
	ds_read_b128 v[174:177], v173 offset:21504
	ds_read_b128 v[178:181], v173 offset:22528
	ds_read_b128 v[182:185], v173 offset:23552
	global_load_lds_dwordx4 v[210:211], off
	v_lshl_add_u64 v[212:213], s[22:23], 0, v[128:129]
	s_mov_b32 m0, s31
	s_nop 0
	global_load_lds_dwordx4 v[212:213], off
	s_barrier
	s_waitcnt lgkmcnt(0)
	s_waitcnt lgkmcnt(0)
	v_mfma_f32_16x16x32_bf16 v[60:63], v[134:137], v[150:153], v[60:63]
	v_mfma_f32_16x16x32_bf16 v[56:59], v[142:145], v[150:153], v[56:59]
	v_mfma_f32_16x16x32_bf16 v[48:51], v[134:137], v[158:161], v[48:51]
	v_mfma_f32_16x16x32_bf16 v[40:43], v[142:145], v[158:161], v[40:43]
	v_mfma_f32_16x16x32_bf16 v[32:35], v[134:137], v[166:169], v[32:35]
	v_mfma_f32_16x16x32_bf16 v[24:27], v[142:145], v[166:169], v[24:27]
	v_mfma_f32_16x16x32_bf16 v[16:19], v[134:137], v[178:181], v[16:19]
	v_mfma_f32_16x16x32_bf16 v[8:11], v[142:145], v[178:181], v[8:11]
	v_mfma_f32_16x16x32_bf16 v[60:63], v[138:141], v[154:157], v[60:63]
	v_mfma_f32_16x16x32_bf16 v[56:59], v[146:149], v[154:157], v[56:59]
	v_mfma_f32_16x16x32_bf16 v[48:51], v[138:141], v[162:165], v[48:51]
	v_mfma_f32_16x16x32_bf16 v[40:43], v[146:149], v[162:165], v[40:43]
	v_mfma_f32_16x16x32_bf16 v[32:35], v[138:141], v[174:177], v[32:35]
	v_mfma_f32_16x16x32_bf16 v[24:27], v[146:149], v[174:177], v[24:27]
	v_mfma_f32_16x16x32_bf16 v[16:19], v[138:141], v[182:185], v[16:19]
	v_mfma_f32_16x16x32_bf16 v[8:11], v[146:149], v[182:185], v[8:11]
	s_barrier
; #define PG8_STAGE(bufoff, gbase, voff) do { _Pragma("unroll") for (int _i = 0; _i < 2; ++_i) \
;         __builtin_amdgcn_global_load_lds((const unsigned*)((const char*)(gbase) + (voff)[_i]), (PG8_LAS unsigned*)(lds + (bufoff) + ldsw + _i * 8192), 16, 0, 0); } while (0)
; #define PG8_LDA(dst, b, h) do { _Pragma("unroll") for (int m = 0; m < 4; ++m) _Pragma("unroll") for (int k = 0; k < 2; ++k) dst[m][k] = *(const PG8_LAS bf16x8*)(lds + PG8_SA(b, h) + aoff + m * 2048 + k * 1024); } while (0)
; #define PG8_LDB(dst, b, h) do { _Pragma("unroll") for (int n = 0; n < 2; ++n) _Pragma("unroll") for (int k = 0; k < 2; ++k) dst[n][k] = *(const PG8_LAS bf16x8*)(lds + PG8_SB(b, h) + boff + n * 2048 + k * 1024); } while (0)
; #define PG8_MMA(ai, bj, At, Bt) do { __builtin_amdgcn_s_setprio(1); _Pragma("unroll") for (int m = 0; m < 4; ++m) _Pragma("unroll") for (int n = 0; n < 2; ++n) _Pragma("unroll") for (int k = 0; k < 2; ++k) \
;         acc[ai][bj][m][n] = __builtin_amdgcn_mfma_f32_16x16x32_bf16(Bt[n][k], At[m][k], acc[ai][bj][m][n], 0, 0, 0); __builtin_amdgcn_s_setprio(0); } while (0)
; #define PG8_WAIT_V(n) asm volatile("s_waitcnt vmcnt(" #n ")" ::: "memory")
; #define PG8_WAIT_L(n) asm volatile("s_waitcnt lgkmcnt(" #n ")" ::: "memory")
; #define PG8_BAR __builtin_amdgcn_s_barrier()
; #define PG8_SCHED __builtin_amdgcn_sched_barrier(0)
; template <class Epi, class Sched>
; __device__ __forceinline__ void gemm_phase(PG8_LAS unsigned char* lds, const Gemm g, const Sched& S, const Epi& E, int tid_in) {
;     ...
;             PG8_STAGE(PG8_SB(0, 1), b2 + hstep, voffB);
;             PG8_WAIT_V(6); PG8_BAR; PG8_MMA(1, 1, At, B1); PG8_BAR;
;             PG8_LDB(B0, 1, 0); PG8_SCHED; PG8_LDA(At, 1, 0); PG8_STAGE(PG8_SA(0, 1), a2 + hstep, voffA);
;             PG8_WAIT_L(8); PG8_BAR; PG8_WAIT_L(0); PG8_MMA(0, 0, At, B0); PG8_BAR; PG8_SCHED;
;             PG8_LDB(B1, 1, 1); PG8_STAGE(PG8_SB(1, 0), b3, voffB);
;             PG8_BAR; PG8_WAIT_L(0); PG8_MMA(0, 1, At, B1); PG8_BAR;
;             PG8_LDA(At, 1, 1); PG8_STAGE(PG8_SA(1, 0), a3, voffA);
;             PG8_BAR; PG8_WAIT_L(0); PG8_MMA(1, 0, At, B0); PG8_BAR; PG8_SCHED;
	s_add_u32 s48, s20, 0x80000
	s_addc_u32 s49, s21, 0
	s_add_i32 s46, s50, s30
	v_lshl_add_u64 v[134:135], s[48:49], 0, v[192:193]
	s_mov_b32 m0, s46
	s_nop 0
	global_load_lds_dwordx4 v[134:135], off
	v_lshl_add_u64 v[134:135], s[48:49], 0, v[128:129]
	s_add_i32 m0, s46, 0x2000
	s_nop 0
	global_load_lds_dwordx4 v[134:135], off
	s_waitcnt vmcnt(6)
	s_barrier
	v_mfma_f32_16x16x32_bf16 v[52:55], v[186:189], v[150:153], v[52:55]
	v_mfma_f32_16x16x32_bf16 v[44:47], v[200:203], v[150:153], v[44:47]
	v_mfma_f32_16x16x32_bf16 v[36:39], v[186:189], v[158:161], v[36:39]
	v_mfma_f32_16x16x32_bf16 v[28:31], v[200:203], v[158:161], v[28:31]
	v_mfma_f32_16x16x32_bf16 v[20:23], v[186:189], v[166:169], v[20:23]
	v_mfma_f32_16x16x32_bf16 v[12:15], v[200:203], v[166:169], v[12:15]
	v_mfma_f32_16x16x32_bf16 v[4:7], v[186:189], v[178:181], v[4:7]
	v_mfma_f32_16x16x32_bf16 v[0:3], v[200:203], v[178:181], v[0:3]
	v_mfma_f32_16x16x32_bf16 v[52:55], v[194:197], v[154:157], v[52:55]
	v_mfma_f32_16x16x32_bf16 v[44:47], v[204:207], v[154:157], v[44:47]
	v_mfma_f32_16x16x32_bf16 v[36:39], v[194:197], v[162:165], v[36:39]
	v_mfma_f32_16x16x32_bf16 v[28:31], v[204:207], v[162:165], v[28:31]
	v_mfma_f32_16x16x32_bf16 v[20:23], v[194:197], v[174:177], v[20:23]
	v_mfma_f32_16x16x32_bf16 v[12:15], v[204:207], v[174:177], v[12:15]
	v_mfma_f32_16x16x32_bf16 v[4:7], v[194:197], v[182:185], v[4:7]
	v_mfma_f32_16x16x32_bf16 v[0:3], v[204:207], v[182:185], v[0:3]
	s_add_i32 s46, 0, 0x18000
	v_add_u32_e32 v146, s46, v171
	s_barrier
	ds_read_b128 v[134:137], v146
	ds_read_b128 v[138:141], v146 offset:1024
	ds_read_b128 v[142:145], v146 offset:2048
	ds_read_b128 v[146:149], v146 offset:3072
	s_add_u32 s22, s22, 0x80000
	s_addc_u32 s23, s23, 0
	s_mov_b32 m0, s36
	v_lshl_add_u64 v[186:187], s[22:23], 0, v[192:193]
	ds_read_b128 v[150:153], v173 offset:32768
	ds_read_b128 v[154:157], v173 offset:33792
	ds_read_b128 v[158:161], v173 offset:34816
	ds_read_b128 v[162:165], v173 offset:35840
	ds_read_b128 v[166:169], v173 offset:36864
	ds_read_b128 v[174:177], v173 offset:37888
	ds_read_b128 v[178:181], v173 offset:38912
	ds_read_b128 v[182:185], v173 offset:39936
	global_load_lds_dwordx4 v[186:187], off
	v_lshl_add_u64 v[186:187], s[22:23], 0, v[128:129]
	s_mov_b32 m0, s37
	s_nop 0
	global_load_lds_dwordx4 v[186:187], off
	s_waitcnt lgkmcnt(8)
	s_barrier
	s_waitcnt lgkmcnt(0)
	s_waitcnt lgkmcnt(0)
	v_mfma_f32_16x16x32_bf16 v[124:127], v[134:137], v[150:153], v[124:127]
	v_mfma_f32_16x16x32_bf16 v[120:123], v[142:145], v[150:153], v[120:123]
	v_mfma_f32_16x16x32_bf16 v[108:111], v[134:137], v[158:161], v[108:111]
	v_mfma_f32_16x16x32_bf16 v[104:107], v[142:145], v[158:161], v[104:107]
	v_mfma_f32_16x16x32_bf16 v[96:99], v[134:137], v[166:169], v[96:99]
	v_mfma_f32_16x16x32_bf16 v[88:91], v[142:145], v[166:169], v[88:91]
	v_mfma_f32_16x16x32_bf16 v[80:83], v[134:137], v[178:181], v[80:83]
	v_mfma_f32_16x16x32_bf16 v[72:75], v[142:145], v[178:181], v[72:75]
	v_mfma_f32_16x16x32_bf16 v[124:127], v[138:141], v[154:157], v[124:127]
	v_mfma_f32_16x16x32_bf16 v[120:123], v[146:149], v[154:157], v[120:123]
	v_mfma_f32_16x16x32_bf16 v[108:111], v[138:141], v[162:165], v[108:111]
	v_mfma_f32_16x16x32_bf16 v[104:107], v[146:149], v[162:165], v[104:107]
	v_mfma_f32_16x16x32_bf16 v[96:99], v[138:141], v[174:177], v[96:99]
	v_mfma_f32_16x16x32_bf16 v[88:91], v[146:149], v[174:177], v[88:91]
	v_mfma_f32_16x16x32_bf16 v[80:83], v[138:141], v[182:185], v[80:83]
	v_mfma_f32_16x16x32_bf16 v[72:75], v[146:149], v[182:185], v[72:75]
	s_barrier
	s_add_i32 s22, 0, 0x1c000
	s_add_i32 s23, s46, s30
	v_add_u32_e32 v199, s22, v171
	v_lshl_add_u64 v[190:191], v[190:191], 0, s[74:75]
	s_mov_b32 m0, s23
	ds_read_b128 v[186:189], v199
	ds_read_b128 v[194:197], v199 offset:1024
	ds_read_b128 v[200:203], v199 offset:2048
	ds_read_b128 v[204:207], v199 offset:3072
	global_load_lds_dwordx4 v[190:191], off
	v_lshl_add_u64 v[190:191], v[208:209], 0, s[74:75]
	s_add_i32 m0, s23, 0x2000
	s_nop 0
	global_load_lds_dwordx4 v[190:191], off
	s_barrier
	s_waitcnt lgkmcnt(0)
	s_waitcnt lgkmcnt(0)
	v_mfma_f32_16x16x32_bf16 v[116:119], v[186:189], v[150:153], v[116:119]
	v_mfma_f32_16x16x32_bf16 v[112:115], v[200:203], v[150:153], v[112:115]
	v_mfma_f32_16x16x32_bf16 v[100:103], v[186:189], v[158:161], v[100:103]
	v_mfma_f32_16x16x32_bf16 v[92:95], v[200:203], v[158:161], v[92:95]
	v_mfma_f32_16x16x32_bf16 v[84:87], v[186:189], v[166:169], v[84:87]
	v_mfma_f32_16x16x32_bf16 v[76:79], v[200:203], v[166:169], v[76:79]
	v_mfma_f32_16x16x32_bf16 v[68:71], v[186:189], v[178:181], v[68:71]
	v_mfma_f32_16x16x32_bf16 v[64:67], v[200:203], v[178:181], v[64:67]
	v_mfma_f32_16x16x32_bf16 v[116:119], v[194:197], v[154:157], v[116:119]
	v_mfma_f32_16x16x32_bf16 v[112:115], v[204:207], v[154:157], v[112:115]
	v_mfma_f32_16x16x32_bf16 v[100:103], v[194:197], v[162:165], v[100:103]
	v_mfma_f32_16x16x32_bf16 v[92:95], v[204:207], v[162:165], v[92:95]
	v_mfma_f32_16x16x32_bf16 v[84:87], v[194:197], v[174:177], v[84:87]
	v_mfma_f32_16x16x32_bf16 v[76:79], v[204:207], v[174:177], v[76:79]
	v_mfma_f32_16x16x32_bf16 v[68:71], v[194:197], v[182:185], v[68:71]
	v_mfma_f32_16x16x32_bf16 v[64:67], v[204:207], v[182:185], v[64:67]
	s_mov_b32 m0, s38
	v_lshl_add_u64 v[190:191], v[210:211], 0, s[74:75]
	s_barrier
	ds_read_b128 v[150:153], v173 offset:49152
	ds_read_b128 v[154:157], v173 offset:50176
	ds_read_b128 v[158:161], v173 offset:51200
	ds_read_b128 v[162:165], v173 offset:52224
	ds_read_b128 v[166:169], v173 offset:53248
	ds_read_b128 v[174:177], v173 offset:54272
	ds_read_b128 v[178:181], v173 offset:55296
	ds_read_b128 v[182:185], v173 offset:56320
	global_load_lds_dwordx4 v[190:191], off
	v_lshl_add_u64 v[190:191], v[212:213], 0, s[74:75]
	s_mov_b32 m0, s39
	s_nop 0
	global_load_lds_dwordx4 v[190:191], off
	s_barrier
; #define PG8_STAGE(bufoff, gbase, voff) do { _Pragma("unroll") for (int _i = 0; _i < 2; ++_i) \
;         __builtin_amdgcn_global_load_lds((const unsigned*)((const char*)(gbase) + (voff)[_i]), (PG8_LAS unsigned*)(lds + (bufoff) + ldsw + _i * 8192), 16, 0, 0); } while (0)
; #define PG8_MMA(ai, bj, At, Bt) do { __builtin_amdgcn_s_setprio(1); _Pragma("unroll") for (int m = 0; m < 4; ++m) _Pragma("unroll") for (int n = 0; n < 2; ++n) _Pragma("unroll") for (int k = 0; k < 2; ++k) \
;         acc[ai][bj][m][n] = __builtin_amdgcn_mfma_f32_16x16x32_bf16(Bt[n][k], At[m][k], acc[ai][bj][m][n], 0, 0, 0); __builtin_amdgcn_s_setprio(0); } while (0)
; #define PG8_WAIT_V(n) asm volatile("s_waitcnt vmcnt(" #n ")" ::: "memory")
; #define PG8_WAIT_L(n) asm volatile("s_waitcnt lgkmcnt(" #n ")" ::: "memory")
; #define PG8_BAR __builtin_amdgcn_s_barrier()
; #define PG8_SCHED __builtin_amdgcn_sched_barrier(0)
; template <class Epi, class Sched>
; __device__ __forceinline__ void gemm_phase(PG8_LAS unsigned char* lds, const Gemm g, const Sched& S, const Epi& E, int tid_in) {
;     ...
;             PG8_BAR; PG8_WAIT_L(0); PG8_MMA(1, 0, At, B0); PG8_BAR; PG8_SCHED;
;             PG8_STAGE(PG8_SB(1, 1), b3 + hstep, voffB);
;             PG8_WAIT_V(6); PG8_BAR; PG8_MMA(1, 1, At, B1); PG8_BAR;
;     __device__ __forceinline__ void operator()(f32x4 (&acc)[2][2][4][2], const Unit& u, int wr, int wc, int fr, int fq) const {
;         const int row0 = u.pm * 256 + wr * 64 + fr, col0 = u.pn * 256 + wc * 32 + 4 * fq;
; #pragma unroll
;         for (int ai = 0; ai < 2; ++ai) {
;             u32x2 gw[4][2][2];
; #pragma unroll
;             for (int m = 0; m < 4; ++m)
; #pragma unroll
;                 for (int bj = 0; bj < 2; ++bj)
; #pragma unroll
;                     for (int n = 0; n < 2; ++n) gw[m][bj][n] = *(const u32x2*)(gates + (size_t)(row0 + ai * 128 + m * 16) * 2048 + col0 + bj * 128 + n * 16);
	s_waitcnt lgkmcnt(0)
	s_waitcnt lgkmcnt(0)
	v_mfma_f32_16x16x32_bf16 v[60:63], v[134:137], v[150:153], v[60:63]
	v_mfma_f32_16x16x32_bf16 v[56:59], v[142:145], v[150:153], v[56:59]
	v_mfma_f32_16x16x32_bf16 v[48:51], v[134:137], v[158:161], v[48:51]
	v_mfma_f32_16x16x32_bf16 v[40:43], v[142:145], v[158:161], v[40:43]
	v_mfma_f32_16x16x32_bf16 v[32:35], v[134:137], v[166:169], v[32:35]
	v_mfma_f32_16x16x32_bf16 v[24:27], v[142:145], v[166:169], v[24:27]
	v_mfma_f32_16x16x32_bf16 v[16:19], v[134:137], v[178:181], v[16:19]
	v_mfma_f32_16x16x32_bf16 v[8:11], v[142:145], v[178:181], v[8:11]
	v_mfma_f32_16x16x32_bf16 v[60:63], v[138:141], v[154:157], v[60:63]
	v_mfma_f32_16x16x32_bf16 v[56:59], v[146:149], v[154:157], v[56:59]
	v_mfma_f32_16x16x32_bf16 v[48:51], v[138:141], v[162:165], v[48:51]
	v_mfma_f32_16x16x32_bf16 v[40:43], v[146:149], v[162:165], v[40:43]
	v_mfma_f32_16x16x32_bf16 v[32:35], v[138:141], v[174:177], v[32:35]
	v_mfma_f32_16x16x32_bf16 v[24:27], v[146:149], v[174:177], v[24:27]
	v_mfma_f32_16x16x32_bf16 v[16:19], v[138:141], v[182:185], v[16:19]
	v_mfma_f32_16x16x32_bf16 v[8:11], v[146:149], v[182:185], v[8:11]
	s_barrier
	s_add_u32 s20, s20, 0x80080
	s_addc_u32 s21, s21, 0
	s_add_i32 s22, s22, s30
	v_lshl_add_u64 v[134:135], s[20:21], 0, v[192:193]
	s_mov_b32 m0, s22
	s_nop 0
	global_load_lds_dwordx4 v[134:135], off
	v_lshl_add_u64 v[134:135], s[20:21], 0, v[128:129]
	s_add_i32 m0, s22, 0x2000
	s_nop 0
	global_load_lds_dwordx4 v[134:135], off
	s_waitcnt vmcnt(6)
	s_barrier
	v_mfma_f32_16x16x32_bf16 v[52:55], v[186:189], v[150:153], v[52:55]
	v_mfma_f32_16x16x32_bf16 v[44:47], v[200:203], v[150:153], v[44:47]
	v_mfma_f32_16x16x32_bf16 v[36:39], v[186:189], v[158:161], v[36:39]
	v_mfma_f32_16x16x32_bf16 v[28:31], v[200:203], v[158:161], v[28:31]
	v_mfma_f32_16x16x32_bf16 v[20:23], v[186:189], v[166:169], v[20:23]
	v_mfma_f32_16x16x32_bf16 v[12:15], v[200:203], v[166:169], v[12:15]
	v_mfma_f32_16x16x32_bf16 v[4:7], v[186:189], v[178:181], v[4:7]
	v_mfma_f32_16x16x32_bf16 v[0:3], v[200:203], v[178:181], v[0:3]
	v_mfma_f32_16x16x32_bf16 v[52:55], v[194:197], v[154:157], v[52:55]
	v_mfma_f32_16x16x32_bf16 v[44:47], v[204:207], v[154:157], v[44:47]
	v_mfma_f32_16x16x32_bf16 v[36:39], v[194:197], v[162:165], v[36:39]
	v_mfma_f32_16x16x32_bf16 v[28:31], v[204:207], v[162:165], v[28:31]
	v_mfma_f32_16x16x32_bf16 v[20:23], v[194:197], v[174:177], v[20:23]
	v_mfma_f32_16x16x32_bf16 v[12:15], v[204:207], v[174:177], v[12:15]
	v_mfma_f32_16x16x32_bf16 v[4:7], v[194:197], v[182:185], v[4:7]
	v_mfma_f32_16x16x32_bf16 v[0:3], v[204:207], v[182:185], v[0:3]
	s_add_i32 s45, s45, 2
	s_add_u32 s18, s18, 0x100
	s_addc_u32 s19, s19, 0
	s_add_u32 s43, s43, 0x100
	s_addc_u32 s44, s44, 0
	s_cmp_gt_u32 s45, 29
	s_barrier
	s_cbranch_scc0 .LBB0_350
	v_lshl_or_b32 v134, s33, 8, v172
	v_lshl_add_u32 v136, s16, 8, v170
	v_ashrrev_i32_e32 v135, 31, v134
	v_lshlrev_b64 v[134:135], 1, v[134:135]
	v_ashrrev_i32_e32 v137, 31, v136
	v_lshl_add_u64 v[138:139], s[0:1], 0, v[134:135]
	v_lshlrev_b64 v[140:141], 12, v[136:137]
	v_lshl_add_u64 v[140:141], v[138:139], 0, v[140:141]
	global_load_dwordx2 v[174:175], v[140:141], off
	global_load_dwordx2 v[176:177], v[140:141], off offset:32
	global_load_dwordx2 v[178:179], v[140:141], off offset:256
	global_load_dwordx2 v[180:181], v[140:141], off offset:288
	v_or_b32_e32 v166, 16, v136
	v_ashrrev_i32_e32 v167, 31, v166
	v_lshlrev_b64 v[140:141], 12, v[166:167]
	v_lshl_add_u64 v[140:141], v[138:139], 0, v[140:141]
	global_load_dwordx2 v[168:169], v[140:141], off
	global_load_dwordx2 v[164:165], v[140:141], off offset:32
	global_load_dwordx2 v[162:163], v[140:141], off offset:256
	global_load_dwordx2 v[160:161], v[140:141], off offset:288
	v_or_b32_e32 v156, 32, v136
	v_ashrrev_i32_e32 v157, 31, v156
	v_lshlrev_b64 v[140:141], 12, v[156:157]
	v_lshl_add_u64 v[140:141], v[138:139], 0, v[140:141]
	global_load_dwordx2 v[158:159], v[140:141], off
	global_load_dwordx2 v[154:155], v[140:141], off offset:32
	global_load_dwordx2 v[152:153], v[140:141], off offset:256
	global_load_dwordx2 v[146:147], v[140:141], off offset:288
	v_or_b32_e32 v148, 48, v136
	v_ashrrev_i32_e32 v149, 31, v148
	v_lshlrev_b64 v[140:141], 12, v[148:149]
	v_lshl_add_u64 v[140:141], v[138:139], 0, v[140:141]
	global_load_dwordx2 v[150:151], v[140:141], off
	global_load_dwordx2 v[144:145], v[140:141], off offset:32
	global_load_dwordx2 v[142:143], v[140:141], off offset:256
	s_nop 0
	global_load_dwordx2 v[140:141], v[140:141], off offset:288
	v_lshlrev_b64 v[182:183], 11, v[136:137]
	s_and_b64 vcc, exec, s[2:3]
	s_mov_b32 s33, s8
	s_mov_b32 s16, s10
	s_mov_b64 s[20:21], s[14:15]
	s_mov_b64 s[18:19], s[12:13]
	s_waitcnt vmcnt(0)
; __device__ __forceinline__ unsigned cvt_pk_bf16(float lo, float hi) { unsigned r; asm volatile("s_nop 0\n\tv_cvt_pk_bf16_f32 %0, %1, %2\n\ts_nop 1" : "=v"(r) : "v"(lo), "v"(hi)); return r; }
; __device__ __forceinline__ float bflo(unsigned w) { return __uint_as_float(w << 16); }
; __device__ __forceinline__ float bfhi(unsigned w) { return __uint_as_float(w & 0xffff0000u); }
;     __device__ __forceinline__ void operator()(f32x4 (&acc)[2][2][4][2], const Unit& u, int wr, int wc, int fr, int fq) const {
;     ...
;             for (int m = 0; m < 4; ++m) { const size_t row = row0 + ai * 128 + m * 16;
; #pragma unroll
;                 for (int bj = 0; bj < 2; ++bj)
; #pragma unroll
;                     for (int n = 0; n < 2; ++n) { const int col = col0 + bj * 128 + n * 16; const u32x2 g2 = gw[m][bj][n];
;                         const f32x4 gv = (f32x4){bflo(g2.x), bfhi(g2.x), bflo(g2.y), bfhi(g2.y)};
;                         const f32x4 o = gv * acc[ai][bj][m][n]; u32x2 w; w.x = cvt_pk_bf16(o[0], o[1]); w.y = cvt_pk_bf16(o[2], o[3]); *(u32x2*)(tmp + row * 1024 + col) = w; } }
	v_lshlrev_b32_e32 v184, 16, v174
	v_and_b32_e32 v185, 0xffff0000, v174
	v_lshlrev_b32_e32 v174, 16, v175
	v_and_b32_e32 v175, 0xffff0000, v175
	v_pk_mul_f32 v[126:127], v[126:127], v[174:175]
	v_pk_mul_f32 v[124:125], v[124:125], v[184:185]
	v_lshlrev_b32_e32 v174, 16, v177
	v_cvt_pk_bf16_f32 v124, v124, v125
	v_cvt_pk_bf16_f32 v125, v126, v127
	v_lshl_add_u64 v[126:127], s[4:5], 0, v[182:183]
	v_lshl_add_u64 v[126:127], v[126:127], 0, v[134:135]
	global_store_dwordx2 v[126:127], v[124:125], off
	v_lshlrev_b32_e32 v124, 16, v176
	v_and_b32_e32 v125, 0xffff0000, v176
	v_and_b32_e32 v175, 0xffff0000, v177
	v_pk_mul_f32 v[120:121], v[120:121], v[124:125]
	v_pk_mul_f32 v[122:123], v[122:123], v[174:175]
	v_cvt_pk_bf16_f32 v120, v120, v121
	s_nop 0
	v_cvt_pk_bf16_f32 v121, v122, v123
	global_store_dwordx2 v[126:127], v[120:121], off offset:32
	v_lshlrev_b32_e32 v120, 16, v178
	v_and_b32_e32 v121, 0xffff0000, v178
	v_lshlrev_b32_e32 v122, 16, v179
	v_and_b32_e32 v123, 0xffff0000, v179
	v_pk_mul_f32 v[116:117], v[116:117], v[120:121]
	v_pk_mul_f32 v[118:119], v[118:119], v[122:123]
	v_cvt_pk_bf16_f32 v116, v116, v117
	s_nop 0
	v_cvt_pk_bf16_f32 v117, v118, v119
	global_store_dwordx2 v[126:127], v[116:117], off offset:256
	v_lshlrev_b32_e32 v116, 16, v180
	v_and_b32_e32 v117, 0xffff0000, v180
	v_lshlrev_b32_e32 v118, 16, v181
	v_and_b32_e32 v119, 0xffff0000, v181
	v_pk_mul_f32 v[114:115], v[114:115], v[118:119]
	v_pk_mul_f32 v[112:113], v[112:113], v[116:117]
	v_lshlrev_b32_e32 v116, 16, v169
	v_cvt_pk_bf16_f32 v112, v112, v113
	v_cvt_pk_bf16_f32 v113, v114, v115
	v_lshlrev_b32_e32 v114, 16, v168
	v_and_b32_e32 v115, 0xffff0000, v168
	v_and_b32_e32 v117, 0xffff0000, v169
	global_store_dwordx2 v[126:127], v[112:113], off offset:288
	v_lshlrev_b64 v[112:113], 11, v[166:167]
	v_pk_mul_f32 v[110:111], v[110:111], v[116:117]
	v_pk_mul_f32 v[108:109], v[108:109], v[114:115]
	s_nop 0
	v_cvt_pk_bf16_f32 v108, v108, v109
	v_cvt_pk_bf16_f32 v109, v110, v111
	v_lshl_add_u64 v[110:111], s[4:5], 0, v[112:113]
	v_lshl_add_u64 v[110:111], v[110:111], 0, v[134:135]
	global_store_dwordx2 v[110:111], v[108:109], off
	v_lshlrev_b32_e32 v108, 16, v164
	v_and_b32_e32 v109, 0xffff0000, v164
	v_lshlrev_b32_e32 v112, 16, v165
	v_and_b32_e32 v113, 0xffff0000, v165
	v_pk_mul_f32 v[104:105], v[104:105], v[108:109]
	v_pk_mul_f32 v[106:107], v[106:107], v[112:113]
	v_cvt_pk_bf16_f32 v104, v104, v105
	s_nop 0
	v_cvt_pk_bf16_f32 v105, v106, v107
	global_store_dwordx2 v[110:111], v[104:105], off offset:32
	v_lshlrev_b32_e32 v104, 16, v162
	v_and_b32_e32 v105, 0xffff0000, v162
	v_lshlrev_b32_e32 v106, 16, v163
	v_and_b32_e32 v107, 0xffff0000, v163
	v_pk_mul_f32 v[100:101], v[100:101], v[104:105]
	v_pk_mul_f32 v[102:103], v[102:103], v[106:107]
	v_cvt_pk_bf16_f32 v100, v100, v101
	s_nop 0
	v_cvt_pk_bf16_f32 v101, v102, v103
	global_store_dwordx2 v[110:111], v[100:101], off offset:256
	v_lshlrev_b32_e32 v100, 16, v160
	v_and_b32_e32 v101, 0xffff0000, v160
	v_lshlrev_b32_e32 v102, 16, v161
	v_and_b32_e32 v103, 0xffff0000, v161
	v_pk_mul_f32 v[92:93], v[92:93], v[100:101]
	v_pk_mul_f32 v[94:95], v[94:95], v[102:103]
	v_cvt_pk_bf16_f32 v92, v92, v93
	v_lshlrev_b32_e32 v100, 16, v159
	v_cvt_pk_bf16_f32 v93, v94, v95
	global_store_dwordx2 v[110:111], v[92:93], off offset:288
	v_lshlrev_b64 v[92:93], 11, v[156:157]
	v_lshlrev_b32_e32 v94, 16, v158
	v_and_b32_e32 v95, 0xffff0000, v158
	v_and_b32_e32 v101, 0xffff0000, v159
	v_pk_mul_f32 v[94:95], v[96:97], v[94:95]
	v_lshl_add_u64 v[92:93], s[4:5], 0, v[92:93]
	v_pk_mul_f32 v[98:99], v[98:99], v[100:101]
	v_cvt_pk_bf16_f32 v94, v94, v95
	v_lshl_add_u64 v[92:93], v[92:93], 0, v[134:135]
	v_cvt_pk_bf16_f32 v95, v98, v99
	global_store_dwordx2 v[92:93], v[94:95], off
	v_lshlrev_b32_e32 v94, 16, v154
	v_and_b32_e32 v95, 0xffff0000, v154
	v_lshlrev_b32_e32 v96, 16, v155
	v_and_b32_e32 v97, 0xffff0000, v155
	v_pk_mul_f32 v[88:89], v[88:89], v[94:95]
	v_pk_mul_f32 v[90:91], v[90:91], v[96:97]
	v_cvt_pk_bf16_f32 v88, v88, v89
	v_add_u32_e32 v94, 0xa0, v136
	v_cvt_pk_bf16_f32 v89, v90, v91
	global_store_dwordx2 v[92:93], v[88:89], off offset:32
	v_lshlrev_b32_e32 v88, 16, v152
	v_and_b32_e32 v89, 0xffff0000, v152
	v_lshlrev_b32_e32 v90, 16, v153
	v_and_b32_e32 v91, 0xffff0000, v153
	v_pk_mul_f32 v[84:85], v[84:85], v[88:89]
	v_pk_mul_f32 v[86:87], v[86:87], v[90:91]
	v_cvt_pk_bf16_f32 v84, v84, v85
	v_ashrrev_i32_e32 v95, 31, v94
	v_cvt_pk_bf16_f32 v85, v86, v87
	global_store_dwordx2 v[92:93], v[84:85], off offset:256
	v_lshlrev_b32_e32 v84, 16, v146
	v_and_b32_e32 v85, 0xffff0000, v146
	v_lshlrev_b32_e32 v86, 16, v147
	v_and_b32_e32 v87, 0xffff0000, v147
	v_pk_mul_f32 v[76:77], v[76:77], v[84:85]
	v_pk_mul_f32 v[78:79], v[78:79], v[86:87]
	v_cvt_pk_bf16_f32 v76, v76, v77
	v_lshlrev_b32_e32 v84, 16, v151
	v_cvt_pk_bf16_f32 v77, v78, v79
	global_store_dwordx2 v[92:93], v[76:77], off offset:288
	v_lshlrev_b64 v[76:77], 11, v[148:149]
	v_lshlrev_b32_e32 v78, 16, v150
	v_and_b32_e32 v79, 0xffff0000, v150
	v_and_b32_e32 v85, 0xffff0000, v151
	v_pk_mul_f32 v[78:79], v[80:81], v[78:79]
	v_lshl_add_u64 v[76:77], s[4:5], 0, v[76:77]
	v_pk_mul_f32 v[82:83], v[82:83], v[84:85]
	v_cvt_pk_bf16_f32 v78, v78, v79
	v_lshl_add_u64 v[76:77], v[76:77], 0, v[134:135]
	v_cvt_pk_bf16_f32 v79, v82, v83
	global_store_dwordx2 v[76:77], v[78:79], off
	v_lshlrev_b32_e32 v78, 16, v144
	v_and_b32_e32 v79, 0xffff0000, v144
	v_lshlrev_b32_e32 v80, 16, v145
	v_and_b32_e32 v81, 0xffff0000, v145
	v_pk_mul_f32 v[72:73], v[72:73], v[78:79]
	v_pk_mul_f32 v[74:75], v[74:75], v[80:81]
	v_cvt_pk_bf16_f32 v72, v72, v73
	v_add_u32_e32 v84, 0x90, v136
	v_cvt_pk_bf16_f32 v73, v74, v75
; __device__ __forceinline__ unsigned cvt_pk_bf16(float lo, float hi) { unsigned r; asm volatile("s_nop 0\n\tv_cvt_pk_bf16_f32 %0, %1, %2\n\ts_nop 1" : "=v"(r) : "v"(lo), "v"(hi)); return r; }
; __device__ __forceinline__ float bflo(unsigned w) { return __uint_as_float(w << 16); }
; __device__ __forceinline__ float bfhi(unsigned w) { return __uint_as_float(w & 0xffff0000u); }
;     __device__ __forceinline__ void operator()(f32x4 (&acc)[2][2][4][2], const Unit& u, int wr, int wc, int fr, int fq) const {
;     ...
;         for (int ai = 0; ai < 2; ++ai) {
;             u32x2 gw[4][2][2];
; #pragma unroll
;             for (int m = 0; m < 4; ++m)
; #pragma unroll
;                 for (int bj = 0; bj < 2; ++bj)
; #pragma unroll
;                     for (int n = 0; n < 2; ++n) gw[m][bj][n] = *(const u32x2*)(gates + (size_t)(row0 + ai * 128 + m * 16) * 2048 + col0 + bj * 128 + n * 16);
; #pragma unroll
;             for (int m = 0; m < 4; ++m) { const size_t row = row0 + ai * 128 + m * 16;
; #pragma unroll
;                 for (int bj = 0; bj < 2; ++bj)
; #pragma unroll
;                     for (int n = 0; n < 2; ++n) { const int col = col0 + bj * 128 + n * 16; const u32x2 g2 = gw[m][bj][n];
;                         const f32x4 gv = (f32x4){bflo(g2.x), bfhi(g2.x), bflo(g2.y), bfhi(g2.y)};
;                         const f32x4 o = gv * acc[ai][bj][m][n]; u32x2 w; w.x = cvt_pk_bf16(o[0], o[1]); w.y = cvt_pk_bf16(o[2], o[3]); *(u32x2*)(tmp + row * 1024 + col) = w; } }
	global_store_dwordx2 v[76:77], v[72:73], off offset:32
	v_lshlrev_b32_e32 v72, 16, v142
	v_and_b32_e32 v73, 0xffff0000, v142
	v_lshlrev_b32_e32 v74, 16, v143
	v_and_b32_e32 v75, 0xffff0000, v143
	v_pk_mul_f32 v[68:69], v[68:69], v[72:73]
	v_pk_mul_f32 v[70:71], v[70:71], v[74:75]
	v_cvt_pk_bf16_f32 v68, v68, v69
	v_add_u32_e32 v74, 0x80, v136
	v_cvt_pk_bf16_f32 v69, v70, v71
	global_store_dwordx2 v[76:77], v[68:69], off offset:256
	v_lshlrev_b32_e32 v68, 16, v140
	v_and_b32_e32 v69, 0xffff0000, v140
	v_lshlrev_b32_e32 v70, 16, v141
	v_and_b32_e32 v71, 0xffff0000, v141
	v_pk_mul_f32 v[64:65], v[64:65], v[68:69]
	v_pk_mul_f32 v[66:67], v[66:67], v[70:71]
	v_cvt_pk_bf16_f32 v64, v64, v65
	v_ashrrev_i32_e32 v75, 31, v74
	v_cvt_pk_bf16_f32 v65, v66, v67
	global_store_dwordx2 v[76:77], v[64:65], off offset:288
	v_lshlrev_b64 v[64:65], 12, v[74:75]
	v_lshl_add_u64 v[64:65], v[138:139], 0, v[64:65]
	global_load_dwordx2 v[76:77], v[64:65], off
	global_load_dwordx2 v[78:79], v[64:65], off offset:32
	global_load_dwordx2 v[80:81], v[64:65], off offset:256
	global_load_dwordx2 v[82:83], v[64:65], off offset:288
	v_ashrrev_i32_e32 v85, 31, v84
	v_lshlrev_b64 v[64:65], 12, v[84:85]
	v_lshl_add_u64 v[64:65], v[138:139], 0, v[64:65]
	global_load_dwordx2 v[86:87], v[64:65], off
	global_load_dwordx2 v[88:89], v[64:65], off offset:32
	global_load_dwordx2 v[90:91], v[64:65], off offset:256
	global_load_dwordx2 v[92:93], v[64:65], off offset:288
	v_lshlrev_b64 v[64:65], 12, v[94:95]
	v_lshl_add_u64 v[64:65], v[138:139], 0, v[64:65]
	global_load_dwordx2 v[96:97], v[64:65], off
	global_load_dwordx2 v[98:99], v[64:65], off offset:32
	global_load_dwordx2 v[100:101], v[64:65], off offset:256
	global_load_dwordx2 v[102:103], v[64:65], off offset:288
	v_add_u32_e32 v70, 0xb0, v136
	v_ashrrev_i32_e32 v71, 31, v70
	v_lshlrev_b64 v[64:65], 12, v[70:71]
	v_lshl_add_u64 v[64:65], v[138:139], 0, v[64:65]
	global_load_dwordx2 v[72:73], v[64:65], off
	global_load_dwordx2 v[68:69], v[64:65], off offset:32
	global_load_dwordx2 v[66:67], v[64:65], off offset:256
	s_nop 0
	global_load_dwordx2 v[64:65], v[64:65], off offset:288
	v_lshlrev_b64 v[74:75], 11, v[74:75]
	s_waitcnt vmcnt(0)
; __device__ __forceinline__ unsigned cvt_pk_bf16(float lo, float hi) { unsigned r; asm volatile("s_nop 0\n\tv_cvt_pk_bf16_f32 %0, %1, %2\n\ts_nop 1" : "=v"(r) : "v"(lo), "v"(hi)); return r; }
; #define PG8_WAIT_V(n) asm volatile("s_waitcnt vmcnt(" #n ")" ::: "memory")
; #define PG8_BAR __builtin_amdgcn_s_barrier()
; __device__ __forceinline__ float bflo(unsigned w) { return __uint_as_float(w << 16); }
; __device__ __forceinline__ float bfhi(unsigned w) { return __uint_as_float(w & 0xffff0000u); }
; template <class Epi, class Sched>
; __device__ __forceinline__ void gemm_phase(PG8_LAS unsigned char* lds, const Gemm g, const Sched& S, const Epi& E, int tid_in) {
;     ...
;     PG8_WAIT_V(0);
;     if (wr == 0) PG8_BAR;
;     __device__ __forceinline__ void operator()(f32x4 (&acc)[2][2][4][2], const Unit& u, int wr, int wc, int fr, int fq) const {
;     ...
;             for (int m = 0; m < 4; ++m) { const size_t row = row0 + ai * 128 + m * 16;
; #pragma unroll
;                 for (int bj = 0; bj < 2; ++bj)
; #pragma unroll
;                     for (int n = 0; n < 2; ++n) { const int col = col0 + bj * 128 + n * 16; const u32x2 g2 = gw[m][bj][n];
;                         const f32x4 gv = (f32x4){bflo(g2.x), bfhi(g2.x), bflo(g2.y), bfhi(g2.y)};
;                         const f32x4 o = gv * acc[ai][bj][m][n]; u32x2 w; w.x = cvt_pk_bf16(o[0], o[1]); w.y = cvt_pk_bf16(o[2], o[3]); *(u32x2*)(tmp + row * 1024 + col) = w; } }
	v_lshlrev_b32_e32 v104, 16, v76
	v_and_b32_e32 v105, 0xffff0000, v76
	v_lshlrev_b32_e32 v76, 16, v77
	v_and_b32_e32 v77, 0xffff0000, v77
	v_pk_mul_f32 v[62:63], v[62:63], v[76:77]
	v_pk_mul_f32 v[60:61], v[60:61], v[104:105]
	s_nop 0
	v_cvt_pk_bf16_f32 v60, v60, v61
	v_cvt_pk_bf16_f32 v61, v62, v63
	v_lshl_add_u64 v[62:63], s[4:5], 0, v[74:75]
	v_lshl_add_u64 v[62:63], v[62:63], 0, v[134:135]
	global_store_dwordx2 v[62:63], v[60:61], off
	v_lshlrev_b32_e32 v60, 16, v78
	v_and_b32_e32 v61, 0xffff0000, v78
	v_lshlrev_b32_e32 v74, 16, v79
	v_and_b32_e32 v75, 0xffff0000, v79
	v_pk_mul_f32 v[56:57], v[56:57], v[60:61]
	v_pk_mul_f32 v[58:59], v[58:59], v[74:75]
	v_cvt_pk_bf16_f32 v56, v56, v57
	s_nop 0
	v_cvt_pk_bf16_f32 v57, v58, v59
	global_store_dwordx2 v[62:63], v[56:57], off offset:32
	v_lshlrev_b32_e32 v56, 16, v80
	v_and_b32_e32 v57, 0xffff0000, v80
	v_lshlrev_b32_e32 v58, 16, v81
	v_and_b32_e32 v59, 0xffff0000, v81
	v_pk_mul_f32 v[52:53], v[52:53], v[56:57]
	v_pk_mul_f32 v[54:55], v[54:55], v[58:59]
	v_cvt_pk_bf16_f32 v52, v52, v53
	s_nop 0
	v_cvt_pk_bf16_f32 v53, v54, v55
	global_store_dwordx2 v[62:63], v[52:53], off offset:256
	v_lshlrev_b32_e32 v52, 16, v82
	v_and_b32_e32 v53, 0xffff0000, v82
	v_lshlrev_b32_e32 v54, 16, v83
	v_and_b32_e32 v55, 0xffff0000, v83
	v_pk_mul_f32 v[44:45], v[44:45], v[52:53]
	v_pk_mul_f32 v[46:47], v[46:47], v[54:55]
	v_cvt_pk_bf16_f32 v44, v44, v45
	v_lshlrev_b32_e32 v52, 16, v87
	v_cvt_pk_bf16_f32 v45, v46, v47
	global_store_dwordx2 v[62:63], v[44:45], off offset:288
	v_lshlrev_b64 v[44:45], 11, v[84:85]
	v_lshlrev_b32_e32 v46, 16, v86
	v_and_b32_e32 v47, 0xffff0000, v86
	v_and_b32_e32 v53, 0xffff0000, v87
	v_pk_mul_f32 v[46:47], v[48:49], v[46:47]
	v_lshl_add_u64 v[44:45], s[4:5], 0, v[44:45]
	v_pk_mul_f32 v[50:51], v[50:51], v[52:53]
	v_cvt_pk_bf16_f32 v46, v46, v47
	v_lshl_add_u64 v[44:45], v[44:45], 0, v[134:135]
	v_cvt_pk_bf16_f32 v47, v50, v51
	global_store_dwordx2 v[44:45], v[46:47], off
	v_lshlrev_b32_e32 v46, 16, v88
	v_and_b32_e32 v47, 0xffff0000, v88
	v_lshlrev_b32_e32 v48, 16, v89
	v_and_b32_e32 v49, 0xffff0000, v89
	v_pk_mul_f32 v[40:41], v[40:41], v[46:47]
	v_pk_mul_f32 v[42:43], v[42:43], v[48:49]
	v_cvt_pk_bf16_f32 v40, v40, v41
	s_nop 0
	v_cvt_pk_bf16_f32 v41, v42, v43
	global_store_dwordx2 v[44:45], v[40:41], off offset:32
	v_lshlrev_b32_e32 v40, 16, v90
	v_and_b32_e32 v41, 0xffff0000, v90
	v_lshlrev_b32_e32 v42, 16, v91
	v_and_b32_e32 v43, 0xffff0000, v91
	v_pk_mul_f32 v[36:37], v[36:37], v[40:41]
	v_pk_mul_f32 v[38:39], v[38:39], v[42:43]
	v_cvt_pk_bf16_f32 v36, v36, v37
	s_nop 0
	v_cvt_pk_bf16_f32 v37, v38, v39
	global_store_dwordx2 v[44:45], v[36:37], off offset:256
	v_lshlrev_b32_e32 v36, 16, v92
	v_and_b32_e32 v37, 0xffff0000, v92
	v_lshlrev_b32_e32 v38, 16, v93
	v_and_b32_e32 v39, 0xffff0000, v93
	v_pk_mul_f32 v[28:29], v[28:29], v[36:37]
	v_pk_mul_f32 v[30:31], v[30:31], v[38:39]
	v_cvt_pk_bf16_f32 v28, v28, v29
	v_lshlrev_b32_e32 v36, 16, v97
	v_cvt_pk_bf16_f32 v29, v30, v31
	global_store_dwordx2 v[44:45], v[28:29], off offset:288
	v_lshlrev_b64 v[28:29], 11, v[94:95]
	v_lshlrev_b32_e32 v30, 16, v96
	v_and_b32_e32 v31, 0xffff0000, v96
	v_and_b32_e32 v37, 0xffff0000, v97
	v_pk_mul_f32 v[30:31], v[32:33], v[30:31]
	v_lshl_add_u64 v[28:29], s[4:5], 0, v[28:29]
	v_pk_mul_f32 v[34:35], v[34:35], v[36:37]
	v_cvt_pk_bf16_f32 v30, v30, v31
	v_lshl_add_u64 v[28:29], v[28:29], 0, v[134:135]
	v_cvt_pk_bf16_f32 v31, v34, v35
	global_store_dwordx2 v[28:29], v[30:31], off
	v_lshlrev_b32_e32 v30, 16, v98
	v_and_b32_e32 v31, 0xffff0000, v98
	v_lshlrev_b32_e32 v32, 16, v99
	v_and_b32_e32 v33, 0xffff0000, v99
	v_pk_mul_f32 v[24:25], v[24:25], v[30:31]
	v_pk_mul_f32 v[26:27], v[26:27], v[32:33]
	v_cvt_pk_bf16_f32 v24, v24, v25
	s_nop 0
	v_cvt_pk_bf16_f32 v25, v26, v27
	global_store_dwordx2 v[28:29], v[24:25], off offset:32
	v_lshlrev_b32_e32 v24, 16, v100
	v_and_b32_e32 v25, 0xffff0000, v100
	v_lshlrev_b32_e32 v26, 16, v101
	v_and_b32_e32 v27, 0xffff0000, v101
	v_pk_mul_f32 v[20:21], v[20:21], v[24:25]
	v_pk_mul_f32 v[22:23], v[22:23], v[26:27]
	v_cvt_pk_bf16_f32 v20, v20, v21
	s_nop 0
	v_cvt_pk_bf16_f32 v21, v22, v23
	global_store_dwordx2 v[28:29], v[20:21], off offset:256
	v_lshlrev_b32_e32 v20, 16, v102
	v_and_b32_e32 v21, 0xffff0000, v102
	v_lshlrev_b32_e32 v22, 16, v103
	v_and_b32_e32 v23, 0xffff0000, v103
	v_pk_mul_f32 v[12:13], v[12:13], v[20:21]
	v_pk_mul_f32 v[14:15], v[14:15], v[22:23]
	v_cvt_pk_bf16_f32 v12, v12, v13
	v_lshlrev_b32_e32 v20, 16, v73
	v_cvt_pk_bf16_f32 v13, v14, v15
	global_store_dwordx2 v[28:29], v[12:13], off offset:288
	v_lshlrev_b64 v[12:13], 11, v[70:71]
	v_lshlrev_b32_e32 v14, 16, v72
	v_and_b32_e32 v15, 0xffff0000, v72
	v_and_b32_e32 v21, 0xffff0000, v73
	v_pk_mul_f32 v[14:15], v[16:17], v[14:15]
	v_lshl_add_u64 v[12:13], s[4:5], 0, v[12:13]
	v_pk_mul_f32 v[18:19], v[18:19], v[20:21]
	v_cvt_pk_bf16_f32 v14, v14, v15
	v_lshl_add_u64 v[12:13], v[12:13], 0, v[134:135]
	v_cvt_pk_bf16_f32 v15, v18, v19
	global_store_dwordx2 v[12:13], v[14:15], off
	v_lshlrev_b32_e32 v14, 16, v68
	v_and_b32_e32 v15, 0xffff0000, v68
	v_lshlrev_b32_e32 v16, 16, v69
	v_and_b32_e32 v17, 0xffff0000, v69
	v_pk_mul_f32 v[8:9], v[8:9], v[14:15]
	v_pk_mul_f32 v[10:11], v[10:11], v[16:17]
	v_cvt_pk_bf16_f32 v8, v8, v9
	s_nop 0
	v_cvt_pk_bf16_f32 v9, v10, v11
	global_store_dwordx2 v[12:13], v[8:9], off offset:32
	v_lshlrev_b32_e32 v8, 16, v66
	v_and_b32_e32 v9, 0xffff0000, v66
	v_lshlrev_b32_e32 v10, 16, v67
	v_and_b32_e32 v11, 0xffff0000, v67
	v_pk_mul_f32 v[4:5], v[4:5], v[8:9]
	v_pk_mul_f32 v[6:7], v[6:7], v[10:11]
	v_cvt_pk_bf16_f32 v4, v4, v5
	s_nop 0
	v_cvt_pk_bf16_f32 v5, v6, v7
	global_store_dwordx2 v[12:13], v[4:5], off offset:256
	v_lshlrev_b32_e32 v4, 16, v64
	v_and_b32_e32 v5, 0xffff0000, v64
	v_lshlrev_b32_e32 v6, 16, v65
	v_and_b32_e32 v7, 0xffff0000, v65
	v_pk_mul_f32 v[0:1], v[0:1], v[4:5]
	v_pk_mul_f32 v[2:3], v[2:3], v[6:7]
	v_cvt_pk_bf16_f32 v0, v0, v1
	s_nop 0
	v_cvt_pk_bf16_f32 v1, v2, v3
	s_nop 1
	global_store_dwordx2 v[12:13], v[0:1], off offset:288
	s_cbranch_vccz .LBB0_343
	s_waitcnt vmcnt(0)
	s_cmpk_gt_u32 s24, 0xff
	s_cbranch_scc1 .LBB0_354
	s_barrier

; #define PG8_STAGE(bufoff, gbase, voff) do { _Pragma("unroll") for (int _i = 0; _i < 2; ++_i) \
;         __builtin_amdgcn_global_load_lds((const unsigned*)((const char*)(gbase) + (voff)[_i]), (PG8_LAS unsigned*)(lds + (bufoff) + ldsw + _i * 8192), 16, 0, 0); } while (0)
; #define PG8_LDA(dst, b, h) do { _Pragma("unroll") for (int m = 0; m < 4; ++m) _Pragma("unroll") for (int k = 0; k < 2; ++k) dst[m][k] = *(const PG8_LAS bf16x8*)(lds + PG8_SA(b, h) + aoff + m * 2048 + k * 1024); } while (0)
; #define PG8_LDB(dst, b, h) do { _Pragma("unroll") for (int n = 0; n < 2; ++n) _Pragma("unroll") for (int k = 0; k < 2; ++k) dst[n][k] = *(const PG8_LAS bf16x8*)(lds + PG8_SB(b, h) + boff + n * 2048 + k * 1024); } while (0)
; #define PG8_MMA(ai, bj, At, Bt) do { __builtin_amdgcn_s_setprio(1); _Pragma("unroll") for (int m = 0; m < 4; ++m) _Pragma("unroll") for (int n = 0; n < 2; ++n) _Pragma("unroll") for (int k = 0; k < 2; ++k) \
;         acc[ai][bj][m][n] = __builtin_amdgcn_mfma_f32_16x16x32_bf16(Bt[n][k], At[m][k], acc[ai][bj][m][n], 0, 0, 0); __builtin_amdgcn_s_setprio(0); } while (0)
; #define PG8_WAIT_L(n) asm volatile("s_waitcnt lgkmcnt(" #n ")" ::: "memory")
; #define PG8_BAR __builtin_amdgcn_s_barrier()
; #define PG8_SCHED __builtin_amdgcn_sched_barrier(0)
; template <class Epi, class Sched>
; __device__ __forceinline__ void gemm_phase(PG8_LAS unsigned char* lds, const Gemm g, const Sched& S, const Epi& E, int tid_in) {
;     ...
;             const bool last = (t == nt - 2);
;             const char* a1 = cA + (size_t)(t + 1) * kstep;
;             const char* a2 = last ? nA : cA + (size_t)(t + 2) * kstep; const char* b2 = last ? nB : cB + (size_t)(t + 2) * kstep;
;             const char* a3 = a2 + kstep; const char* b3 = b2 + kstep;
;             if (last && has_next) S.a_ready(nxt);
;             PG8_LDB(B0, 0, 0); PG8_SCHED; PG8_LDA(At, 0, 0); PG8_STAGE(PG8_SA(1, 1), a1 + hstep, voffA);
;             PG8_WAIT_L(8); PG8_BAR; PG8_WAIT_L(0); PG8_MMA(0, 0, At, B0); PG8_BAR; PG8_SCHED;
;             PG8_LDB(B1, 0, 1); PG8_STAGE(PG8_SB(0, 0), b2, voffB);
;             PG8_BAR; PG8_WAIT_L(0); PG8_MMA(0, 1, At, B1); PG8_BAR;
;             PG8_LDA(At, 0, 1); PG8_STAGE(PG8_SA(0, 0), a2, voffA);
;             PG8_BAR; PG8_WAIT_L(0); PG8_MMA(1, 0, At, B0); PG8_BAR; PG8_SCHED;
.LBB0_370:
	s_add_u32 s20, s18, 0xfffc0080
	s_addc_u32 s21, s19, -1
	s_add_i32 s46, 0, 0x10000
	v_add_u32_e32 v146, s46, v214
	ds_read_b128 v[134:137], v146
	ds_read_b128 v[138:141], v146 offset:1024
	ds_read_b128 v[142:145], v146 offset:2048
	ds_read_b128 v[146:149], v146 offset:3072
	s_cmp_eq_u32 s45, 12
	s_cselect_b32 s23, s11, s21
	s_cselect_b32 s22, s41, s20
	s_cselect_b32 s21, s9, s44
	s_cselect_b32 s20, s42, s43
	v_lshl_add_u64 v[182:183], s[18:19], 0, v[130:131]
	s_add_i32 m0, s17, 0xc000
	ds_read_b128 v[150:153], v216
	ds_read_b128 v[154:157], v216 offset:1024
	ds_read_b128 v[158:161], v216 offset:2048
	ds_read_b128 v[162:165], v216 offset:3072
	ds_read_b128 v[166:169], v216 offset:4096
	ds_read_b128 v[170:173], v216 offset:5120
	ds_read_b128 v[174:177], v216 offset:6144
	ds_read_b128 v[178:181], v216 offset:7168
	global_load_lds_dwordx4 v[182:183], off
	v_lshl_add_u64 v[182:183], s[18:19], 0, v[132:133]
	s_add_i32 m0, s17, 0xe000
	s_nop 0
	global_load_lds_dwordx4 v[182:183], off
	s_waitcnt lgkmcnt(8)
	s_barrier
	s_waitcnt lgkmcnt(0)
	s_waitcnt lgkmcnt(0)
	v_mfma_f32_16x16x32_bf16 v[124:127], v[134:137], v[150:153], v[124:127]
	v_mfma_f32_16x16x32_bf16 v[120:123], v[142:145], v[150:153], v[120:123]
	v_mfma_f32_16x16x32_bf16 v[108:111], v[134:137], v[158:161], v[108:111]
	v_mfma_f32_16x16x32_bf16 v[104:107], v[142:145], v[158:161], v[104:107]
	v_mfma_f32_16x16x32_bf16 v[92:95], v[134:137], v[166:169], v[92:95]
	v_mfma_f32_16x16x32_bf16 v[88:91], v[142:145], v[166:169], v[88:91]
	v_mfma_f32_16x16x32_bf16 v[76:79], v[134:137], v[174:177], v[76:79]
	v_mfma_f32_16x16x32_bf16 v[72:75], v[142:145], v[174:177], v[72:75]
	v_mfma_f32_16x16x32_bf16 v[124:127], v[138:141], v[154:157], v[124:127]
	v_mfma_f32_16x16x32_bf16 v[120:123], v[146:149], v[154:157], v[120:123]
	v_mfma_f32_16x16x32_bf16 v[108:111], v[138:141], v[162:165], v[108:111]
	v_mfma_f32_16x16x32_bf16 v[104:107], v[146:149], v[162:165], v[104:107]
	v_mfma_f32_16x16x32_bf16 v[92:95], v[138:141], v[170:173], v[92:95]
	v_mfma_f32_16x16x32_bf16 v[88:91], v[146:149], v[170:173], v[88:91]
	v_mfma_f32_16x16x32_bf16 v[76:79], v[138:141], v[178:181], v[76:79]
	v_mfma_f32_16x16x32_bf16 v[72:75], v[146:149], v[178:181], v[72:75]
	s_barrier
	s_add_i32 s50, 0, 0x14000
	v_add_u32_e32 v190, s50, v214
	s_add_i32 s46, s46, s30
	ds_read_b128 v[182:185], v190
	ds_read_b128 v[186:189], v190 offset:1024
	ds_read_b128 v[194:197], v190 offset:2048
	ds_read_b128 v[200:203], v190 offset:3072
	v_lshl_add_u64 v[190:191], s[20:21], 0, v[192:193]
	s_mov_b32 m0, s46
	v_lshl_add_u64 v[204:205], s[20:21], 0, v[128:129]
	global_load_lds_dwordx4 v[190:191], off
	s_add_i32 m0, s46, 0x2000
	s_nop 0
	global_load_lds_dwordx4 v[204:205], off
	s_barrier
	s_waitcnt lgkmcnt(0)
	s_waitcnt lgkmcnt(0)
	v_mfma_f32_16x16x32_bf16 v[116:119], v[182:185], v[150:153], v[116:119]
	v_mfma_f32_16x16x32_bf16 v[112:115], v[194:197], v[150:153], v[112:115]
	v_mfma_f32_16x16x32_bf16 v[100:103], v[182:185], v[158:161], v[100:103]
	v_mfma_f32_16x16x32_bf16 v[96:99], v[194:197], v[158:161], v[96:99]
	v_mfma_f32_16x16x32_bf16 v[84:87], v[182:185], v[166:169], v[84:87]
	v_mfma_f32_16x16x32_bf16 v[80:83], v[194:197], v[166:169], v[80:83]
	v_mfma_f32_16x16x32_bf16 v[68:71], v[182:185], v[174:177], v[68:71]
	v_mfma_f32_16x16x32_bf16 v[64:67], v[194:197], v[174:177], v[64:67]
	v_mfma_f32_16x16x32_bf16 v[116:119], v[186:189], v[154:157], v[116:119]
	v_mfma_f32_16x16x32_bf16 v[112:115], v[200:203], v[154:157], v[112:115]
	v_mfma_f32_16x16x32_bf16 v[100:103], v[186:189], v[162:165], v[100:103]
	v_mfma_f32_16x16x32_bf16 v[96:99], v[200:203], v[162:165], v[96:99]
	v_mfma_f32_16x16x32_bf16 v[84:87], v[186:189], v[170:173], v[84:87]
	v_mfma_f32_16x16x32_bf16 v[80:83], v[200:203], v[170:173], v[80:83]
	v_mfma_f32_16x16x32_bf16 v[68:71], v[186:189], v[178:181], v[68:71]
	v_mfma_f32_16x16x32_bf16 v[64:67], v[200:203], v[178:181], v[64:67]
	s_mov_b32 m0, s17
	v_lshl_add_u64 v[206:207], s[22:23], 0, v[192:193]
	s_barrier
	ds_read_b128 v[150:153], v216 offset:16384
	ds_read_b128 v[154:157], v216 offset:17408
	ds_read_b128 v[158:161], v216 offset:18432
	ds_read_b128 v[162:165], v216 offset:19456
	ds_read_b128 v[166:169], v216 offset:20480
	ds_read_b128 v[170:173], v216 offset:21504
	ds_read_b128 v[174:177], v216 offset:22528
	ds_read_b128 v[178:181], v216 offset:23552
	global_load_lds_dwordx4 v[206:207], off
	v_lshl_add_u64 v[208:209], s[22:23], 0, v[128:129]
	s_mov_b32 m0, s31
	s_nop 0
	global_load_lds_dwordx4 v[208:209], off
	s_barrier
	s_waitcnt lgkmcnt(0)
	s_waitcnt lgkmcnt(0)
	v_mfma_f32_16x16x32_bf16 v[60:63], v[134:137], v[150:153], v[60:63]
	v_mfma_f32_16x16x32_bf16 v[56:59], v[142:145], v[150:153], v[56:59]
	v_mfma_f32_16x16x32_bf16 v[44:47], v[134:137], v[158:161], v[44:47]
	v_mfma_f32_16x16x32_bf16 v[40:43], v[142:145], v[158:161], v[40:43]
	v_mfma_f32_16x16x32_bf16 v[28:31], v[134:137], v[166:169], v[28:31]
	v_mfma_f32_16x16x32_bf16 v[24:27], v[142:145], v[166:169], v[24:27]
	v_mfma_f32_16x16x32_bf16 v[12:15], v[134:137], v[174:177], v[12:15]
	v_mfma_f32_16x16x32_bf16 v[8:11], v[142:145], v[174:177], v[8:11]
	v_mfma_f32_16x16x32_bf16 v[60:63], v[138:141], v[154:157], v[60:63]
	v_mfma_f32_16x16x32_bf16 v[56:59], v[146:149], v[154:157], v[56:59]
	v_mfma_f32_16x16x32_bf16 v[44:47], v[138:141], v[162:165], v[44:47]
	v_mfma_f32_16x16x32_bf16 v[40:43], v[146:149], v[162:165], v[40:43]
	v_mfma_f32_16x16x32_bf16 v[28:31], v[138:141], v[170:173], v[28:31]
	v_mfma_f32_16x16x32_bf16 v[24:27], v[146:149], v[170:173], v[24:27]
	v_mfma_f32_16x16x32_bf16 v[12:15], v[138:141], v[178:181], v[12:15]
	v_mfma_f32_16x16x32_bf16 v[8:11], v[146:149], v[178:181], v[8:11]
	s_barrier
; #define PG8_STAGE(bufoff, gbase, voff) do { _Pragma("unroll") for (int _i = 0; _i < 2; ++_i) \
;         __builtin_amdgcn_global_load_lds((const unsigned*)((const char*)(gbase) + (voff)[_i]), (PG8_LAS unsigned*)(lds + (bufoff) + ldsw + _i * 8192), 16, 0, 0); } while (0)
; #define PG8_LDA(dst, b, h) do { _Pragma("unroll") for (int m = 0; m < 4; ++m) _Pragma("unroll") for (int k = 0; k < 2; ++k) dst[m][k] = *(const PG8_LAS bf16x8*)(lds + PG8_SA(b, h) + aoff + m * 2048 + k * 1024); } while (0)
; #define PG8_LDB(dst, b, h) do { _Pragma("unroll") for (int n = 0; n < 2; ++n) _Pragma("unroll") for (int k = 0; k < 2; ++k) dst[n][k] = *(const PG8_LAS bf16x8*)(lds + PG8_SB(b, h) + boff + n * 2048 + k * 1024); } while (0)
; #define PG8_MMA(ai, bj, At, Bt) do { __builtin_amdgcn_s_setprio(1); _Pragma("unroll") for (int m = 0; m < 4; ++m) _Pragma("unroll") for (int n = 0; n < 2; ++n) _Pragma("unroll") for (int k = 0; k < 2; ++k) \
;         acc[ai][bj][m][n] = __builtin_amdgcn_mfma_f32_16x16x32_bf16(Bt[n][k], At[m][k], acc[ai][bj][m][n], 0, 0, 0); __builtin_amdgcn_s_setprio(0); } while (0)
; #define PG8_WAIT_V(n) asm volatile("s_waitcnt vmcnt(" #n ")" ::: "memory")
; #define PG8_WAIT_L(n) asm volatile("s_waitcnt lgkmcnt(" #n ")" ::: "memory")
; #define PG8_BAR __builtin_amdgcn_s_barrier()
; #define PG8_SCHED __builtin_amdgcn_sched_barrier(0)
; template <class Epi, class Sched>
; __device__ __forceinline__ void gemm_phase(PG8_LAS unsigned char* lds, const Gemm g, const Sched& S, const Epi& E, int tid_in) {
;     ...
;             PG8_STAGE(PG8_SB(0, 1), b2 + hstep, voffB);
;             PG8_WAIT_V(6); PG8_BAR; PG8_MMA(1, 1, At, B1); PG8_BAR;
;             PG8_LDB(B0, 1, 0); PG8_SCHED; PG8_LDA(At, 1, 0); PG8_STAGE(PG8_SA(0, 1), a2 + hstep, voffA);
;             PG8_WAIT_L(8); PG8_BAR; PG8_WAIT_L(0); PG8_MMA(0, 0, At, B0); PG8_BAR; PG8_SCHED;
;             PG8_LDB(B1, 1, 1); PG8_STAGE(PG8_SB(1, 0), b3, voffB);
;             PG8_BAR; PG8_WAIT_L(0); PG8_MMA(0, 1, At, B1); PG8_BAR;
;             PG8_LDA(At, 1, 1); PG8_STAGE(PG8_SA(1, 0), a3, voffA);
;             PG8_BAR; PG8_WAIT_L(0); PG8_MMA(1, 0, At, B0); PG8_BAR; PG8_SCHED;
	s_add_u32 s48, s20, 0x40000
	s_addc_u32 s49, s21, 0
	s_add_i32 s46, s50, s30
	v_lshl_add_u64 v[134:135], s[48:49], 0, v[192:193]
	s_mov_b32 m0, s46
	s_nop 0
	global_load_lds_dwordx4 v[134:135], off
	v_lshl_add_u64 v[134:135], s[48:49], 0, v[128:129]
	s_add_i32 m0, s46, 0x2000
	s_nop 0
	global_load_lds_dwordx4 v[134:135], off
	s_waitcnt vmcnt(6)
	s_barrier
	v_mfma_f32_16x16x32_bf16 v[52:55], v[182:185], v[150:153], v[52:55]
	v_mfma_f32_16x16x32_bf16 v[48:51], v[194:197], v[150:153], v[48:51]
	v_mfma_f32_16x16x32_bf16 v[36:39], v[182:185], v[158:161], v[36:39]
	v_mfma_f32_16x16x32_bf16 v[32:35], v[194:197], v[158:161], v[32:35]
	v_mfma_f32_16x16x32_bf16 v[20:23], v[182:185], v[166:169], v[20:23]
	v_mfma_f32_16x16x32_bf16 v[16:19], v[194:197], v[166:169], v[16:19]
	v_mfma_f32_16x16x32_bf16 v[4:7], v[182:185], v[174:177], v[4:7]
	v_mfma_f32_16x16x32_bf16 v[0:3], v[194:197], v[174:177], v[0:3]
	v_mfma_f32_16x16x32_bf16 v[52:55], v[186:189], v[154:157], v[52:55]
	v_mfma_f32_16x16x32_bf16 v[48:51], v[200:203], v[154:157], v[48:51]
	v_mfma_f32_16x16x32_bf16 v[36:39], v[186:189], v[162:165], v[36:39]
	v_mfma_f32_16x16x32_bf16 v[32:35], v[200:203], v[162:165], v[32:35]
	v_mfma_f32_16x16x32_bf16 v[20:23], v[186:189], v[170:173], v[20:23]
	v_mfma_f32_16x16x32_bf16 v[16:19], v[200:203], v[170:173], v[16:19]
	v_mfma_f32_16x16x32_bf16 v[4:7], v[186:189], v[178:181], v[4:7]
	v_mfma_f32_16x16x32_bf16 v[0:3], v[200:203], v[178:181], v[0:3]
	s_add_i32 s46, 0, 0x18000
	v_add_u32_e32 v146, s46, v214
	s_barrier
	ds_read_b128 v[134:137], v146
	ds_read_b128 v[138:141], v146 offset:1024
	ds_read_b128 v[142:145], v146 offset:2048
	ds_read_b128 v[146:149], v146 offset:3072
	s_add_u32 s22, s22, 0x40000
	s_addc_u32 s23, s23, 0
	s_mov_b32 m0, s36
	v_lshl_add_u64 v[182:183], s[22:23], 0, v[192:193]
	ds_read_b128 v[150:153], v216 offset:32768
	ds_read_b128 v[154:157], v216 offset:33792
	ds_read_b128 v[158:161], v216 offset:34816
	ds_read_b128 v[162:165], v216 offset:35840
	ds_read_b128 v[166:169], v216 offset:36864
	ds_read_b128 v[170:173], v216 offset:37888
	ds_read_b128 v[174:177], v216 offset:38912
	ds_read_b128 v[178:181], v216 offset:39936
	global_load_lds_dwordx4 v[182:183], off
	v_lshl_add_u64 v[182:183], s[22:23], 0, v[128:129]
	s_mov_b32 m0, s37
	s_nop 0
	global_load_lds_dwordx4 v[182:183], off
	s_waitcnt lgkmcnt(8)
	s_barrier
	s_waitcnt lgkmcnt(0)
	s_waitcnt lgkmcnt(0)
	v_mfma_f32_16x16x32_bf16 v[124:127], v[134:137], v[150:153], v[124:127]
	v_mfma_f32_16x16x32_bf16 v[120:123], v[142:145], v[150:153], v[120:123]
	v_mfma_f32_16x16x32_bf16 v[108:111], v[134:137], v[158:161], v[108:111]
	v_mfma_f32_16x16x32_bf16 v[104:107], v[142:145], v[158:161], v[104:107]
	v_mfma_f32_16x16x32_bf16 v[92:95], v[134:137], v[166:169], v[92:95]
	v_mfma_f32_16x16x32_bf16 v[88:91], v[142:145], v[166:169], v[88:91]
	v_mfma_f32_16x16x32_bf16 v[76:79], v[134:137], v[174:177], v[76:79]
	v_mfma_f32_16x16x32_bf16 v[72:75], v[142:145], v[174:177], v[72:75]
	v_mfma_f32_16x16x32_bf16 v[124:127], v[138:141], v[154:157], v[124:127]
	v_mfma_f32_16x16x32_bf16 v[120:123], v[146:149], v[154:157], v[120:123]
	v_mfma_f32_16x16x32_bf16 v[108:111], v[138:141], v[162:165], v[108:111]
	v_mfma_f32_16x16x32_bf16 v[104:107], v[146:149], v[162:165], v[104:107]
	v_mfma_f32_16x16x32_bf16 v[92:95], v[138:141], v[170:173], v[92:95]
	v_mfma_f32_16x16x32_bf16 v[88:91], v[146:149], v[170:173], v[88:91]
	v_mfma_f32_16x16x32_bf16 v[76:79], v[138:141], v[178:181], v[76:79]
	v_mfma_f32_16x16x32_bf16 v[72:75], v[146:149], v[178:181], v[72:75]
	s_barrier
	s_add_i32 s22, 0, 0x1c000
	s_add_i32 s23, s46, s30
	v_add_u32_e32 v200, s22, v214
	v_lshl_add_u64 v[190:191], v[190:191], 0, s[74:75]
	s_mov_b32 m0, s23
	ds_read_b128 v[182:185], v200
	ds_read_b128 v[186:189], v200 offset:1024
	ds_read_b128 v[194:197], v200 offset:2048
	ds_read_b128 v[200:203], v200 offset:3072
	global_load_lds_dwordx4 v[190:191], off
	v_lshl_add_u64 v[190:191], v[204:205], 0, s[74:75]
	s_add_i32 m0, s23, 0x2000
	s_nop 0
	global_load_lds_dwordx4 v[190:191], off
	s_barrier
	s_waitcnt lgkmcnt(0)
	s_waitcnt lgkmcnt(0)
	v_mfma_f32_16x16x32_bf16 v[116:119], v[182:185], v[150:153], v[116:119]
	v_mfma_f32_16x16x32_bf16 v[112:115], v[194:197], v[150:153], v[112:115]
	v_mfma_f32_16x16x32_bf16 v[100:103], v[182:185], v[158:161], v[100:103]
	v_mfma_f32_16x16x32_bf16 v[96:99], v[194:197], v[158:161], v[96:99]
	v_mfma_f32_16x16x32_bf16 v[84:87], v[182:185], v[166:169], v[84:87]
	v_mfma_f32_16x16x32_bf16 v[80:83], v[194:197], v[166:169], v[80:83]
	v_mfma_f32_16x16x32_bf16 v[68:71], v[182:185], v[174:177], v[68:71]
	v_mfma_f32_16x16x32_bf16 v[64:67], v[194:197], v[174:177], v[64:67]
	v_mfma_f32_16x16x32_bf16 v[116:119], v[186:189], v[154:157], v[116:119]
	v_mfma_f32_16x16x32_bf16 v[112:115], v[200:203], v[154:157], v[112:115]
	v_mfma_f32_16x16x32_bf16 v[100:103], v[186:189], v[162:165], v[100:103]
	v_mfma_f32_16x16x32_bf16 v[96:99], v[200:203], v[162:165], v[96:99]
	v_mfma_f32_16x16x32_bf16 v[84:87], v[186:189], v[170:173], v[84:87]
	v_mfma_f32_16x16x32_bf16 v[80:83], v[200:203], v[170:173], v[80:83]
	v_mfma_f32_16x16x32_bf16 v[68:71], v[186:189], v[178:181], v[68:71]
	v_mfma_f32_16x16x32_bf16 v[64:67], v[200:203], v[178:181], v[64:67]
	s_mov_b32 m0, s38
	v_lshl_add_u64 v[190:191], v[206:207], 0, s[74:75]
	s_barrier
	ds_read_b128 v[150:153], v216 offset:49152
	ds_read_b128 v[154:157], v216 offset:50176
	ds_read_b128 v[158:161], v216 offset:51200
	ds_read_b128 v[162:165], v216 offset:52224
	ds_read_b128 v[166:169], v216 offset:53248
	ds_read_b128 v[170:173], v216 offset:54272
	ds_read_b128 v[174:177], v216 offset:55296
	ds_read_b128 v[178:181], v216 offset:56320
	global_load_lds_dwordx4 v[190:191], off
	v_lshl_add_u64 v[190:191], v[208:209], 0, s[74:75]
	s_mov_b32 m0, s39
	s_nop 0
	global_load_lds_dwordx4 v[190:191], off
	s_barrier
; #define PG8_STAGE(bufoff, gbase, voff) do { _Pragma("unroll") for (int _i = 0; _i < 2; ++_i) \
;         __builtin_amdgcn_global_load_lds((const unsigned*)((const char*)(gbase) + (voff)[_i]), (PG8_LAS unsigned*)(lds + (bufoff) + ldsw + _i * 8192), 16, 0, 0); } while (0)
; #define PG8_MMA(ai, bj, At, Bt) do { __builtin_amdgcn_s_setprio(1); _Pragma("unroll") for (int m = 0; m < 4; ++m) _Pragma("unroll") for (int n = 0; n < 2; ++n) _Pragma("unroll") for (int k = 0; k < 2; ++k) \
;         acc[ai][bj][m][n] = __builtin_amdgcn_mfma_f32_16x16x32_bf16(Bt[n][k], At[m][k], acc[ai][bj][m][n], 0, 0, 0); __builtin_amdgcn_s_setprio(0); } while (0)
; #define PG8_WAIT_V(n) asm volatile("s_waitcnt vmcnt(" #n ")" ::: "memory")
; #define PG8_WAIT_L(n) asm volatile("s_waitcnt lgkmcnt(" #n ")" ::: "memory")
; #define PG8_BAR __builtin_amdgcn_s_barrier()
; #define PG8_SCHED __builtin_amdgcn_sched_barrier(0)
; template <class Epi, class Sched>
; __device__ __forceinline__ void gemm_phase(PG8_LAS unsigned char* lds, const Gemm g, const Sched& S, const Epi& E, int tid_in) {
;     ...
;             PG8_BAR; PG8_WAIT_L(0); PG8_MMA(1, 0, At, B0); PG8_BAR; PG8_SCHED;
;             PG8_STAGE(PG8_SB(1, 1), b3 + hstep, voffB);
;             PG8_WAIT_V(6); PG8_BAR; PG8_MMA(1, 1, At, B1); PG8_BAR;
;     __device__ __forceinline__ void operator()(f32x4 (&acc)[2][2][4][2], const Unit& u, int wr, int wc, int fr, int fq) const {
;         const int row0 = u.pm * 256 + wr * 64 + fr, col0 = u.pn * 256 + wc * 32 + 4 * fq;
; #pragma unroll
;         for (int ai = 0; ai < 2; ++ai) {
;             u32x2 gw[4][2][2], tw[4][2][2];
; #pragma unroll
;             for (int m = 0; m < 4; ++m)
; #pragma unroll
;                 for (int bj = 0; bj < 2; ++bj)
; #pragma unroll
;                     for (int n = 0; n < 2; ++n) { const size_t row = row0 + ai * 128 + m * 16; const int col = col0 + bj * 128 + n * 16;
;                         gw[m][bj][n] = *(const u32x2*)(gates + row * 2048 + 1024 + col); tw[m][bj][n] = *(const u32x2*)(tmp + row * 1024 + col); }
	s_waitcnt lgkmcnt(0)
	s_waitcnt lgkmcnt(0)
	v_mfma_f32_16x16x32_bf16 v[60:63], v[134:137], v[150:153], v[60:63]
	v_mfma_f32_16x16x32_bf16 v[56:59], v[142:145], v[150:153], v[56:59]
	v_mfma_f32_16x16x32_bf16 v[44:47], v[134:137], v[158:161], v[44:47]
	v_mfma_f32_16x16x32_bf16 v[40:43], v[142:145], v[158:161], v[40:43]
	v_mfma_f32_16x16x32_bf16 v[28:31], v[134:137], v[166:169], v[28:31]
	v_mfma_f32_16x16x32_bf16 v[24:27], v[142:145], v[166:169], v[24:27]
	v_mfma_f32_16x16x32_bf16 v[12:15], v[134:137], v[174:177], v[12:15]
	v_mfma_f32_16x16x32_bf16 v[8:11], v[142:145], v[174:177], v[8:11]
	v_mfma_f32_16x16x32_bf16 v[60:63], v[138:141], v[154:157], v[60:63]
	v_mfma_f32_16x16x32_bf16 v[56:59], v[146:149], v[154:157], v[56:59]
	v_mfma_f32_16x16x32_bf16 v[44:47], v[138:141], v[162:165], v[44:47]
	v_mfma_f32_16x16x32_bf16 v[40:43], v[146:149], v[162:165], v[40:43]
	v_mfma_f32_16x16x32_bf16 v[28:31], v[138:141], v[170:173], v[28:31]
	v_mfma_f32_16x16x32_bf16 v[24:27], v[146:149], v[170:173], v[24:27]
	v_mfma_f32_16x16x32_bf16 v[12:15], v[138:141], v[178:181], v[12:15]
	v_mfma_f32_16x16x32_bf16 v[8:11], v[146:149], v[178:181], v[8:11]
	s_barrier
	s_add_u32 s20, s20, 0x40080
	s_addc_u32 s21, s21, 0
	s_add_i32 s22, s22, s30
	v_lshl_add_u64 v[134:135], s[20:21], 0, v[192:193]
	s_mov_b32 m0, s22
	s_nop 0
	global_load_lds_dwordx4 v[134:135], off
	v_lshl_add_u64 v[134:135], s[20:21], 0, v[128:129]
	s_add_i32 m0, s22, 0x2000
	s_nop 0
	global_load_lds_dwordx4 v[134:135], off
	s_waitcnt vmcnt(6)
	s_barrier
	v_mfma_f32_16x16x32_bf16 v[52:55], v[182:185], v[150:153], v[52:55]
	v_mfma_f32_16x16x32_bf16 v[48:51], v[194:197], v[150:153], v[48:51]
	v_mfma_f32_16x16x32_bf16 v[36:39], v[182:185], v[158:161], v[36:39]
	v_mfma_f32_16x16x32_bf16 v[32:35], v[194:197], v[158:161], v[32:35]
	v_mfma_f32_16x16x32_bf16 v[20:23], v[182:185], v[166:169], v[20:23]
	v_mfma_f32_16x16x32_bf16 v[16:19], v[194:197], v[166:169], v[16:19]
	v_mfma_f32_16x16x32_bf16 v[4:7], v[182:185], v[174:177], v[4:7]
	v_mfma_f32_16x16x32_bf16 v[0:3], v[194:197], v[174:177], v[0:3]
	v_mfma_f32_16x16x32_bf16 v[52:55], v[186:189], v[154:157], v[52:55]
	v_mfma_f32_16x16x32_bf16 v[48:51], v[200:203], v[154:157], v[48:51]
	v_mfma_f32_16x16x32_bf16 v[36:39], v[186:189], v[162:165], v[36:39]
	v_mfma_f32_16x16x32_bf16 v[32:35], v[200:203], v[162:165], v[32:35]
	v_mfma_f32_16x16x32_bf16 v[20:23], v[186:189], v[170:173], v[20:23]
	v_mfma_f32_16x16x32_bf16 v[16:19], v[200:203], v[170:173], v[16:19]
	v_mfma_f32_16x16x32_bf16 v[4:7], v[186:189], v[178:181], v[4:7]
	v_mfma_f32_16x16x32_bf16 v[0:3], v[200:203], v[178:181], v[0:3]
	s_add_i32 s45, s45, 2
	s_add_u32 s18, s18, 0x100
	s_addc_u32 s19, s19, 0
	s_add_u32 s43, s43, 0x100
	s_addc_u32 s44, s44, 0
	s_cmp_gt_u32 s45, 13
	s_barrier
	s_cbranch_scc0 .LBB0_370
	v_lshl_add_u32 v136, s16, 8, v199
	v_lshl_or_b32 v134, s33, 8, v215
	v_ashrrev_i32_e32 v137, 31, v136
	v_lshlrev_b64 v[138:139], 12, v[136:137]
	v_ashrrev_i32_e32 v135, 31, v134
	v_lshl_add_u64 v[138:139], s[0:1], 0, v[138:139]
	v_lshlrev_b64 v[134:135], 1, v[134:135]
	v_lshl_add_u64 v[138:139], v[138:139], 0, v[134:135]
	global_load_dwordx2 v[194:195], v[138:139], off offset:2048
	v_lshlrev_b64 v[212:213], 11, v[136:137]
	v_lshl_add_u64 v[140:141], s[4:5], 0, v[212:213]
	v_lshl_add_u64 v[140:141], v[140:141], 0, v[134:135]
	global_load_dwordx2 v[196:197], v[140:141], off
	global_load_dwordx2 v[210:211], v[138:139], off offset:2080
	global_load_dwordx2 v[208:209], v[140:141], off offset:32
	global_load_dwordx2 v[206:207], v[138:139], off offset:2304
	global_load_dwordx2 v[204:205], v[140:141], off offset:256
	global_load_dwordx2 v[202:203], v[138:139], off offset:2336
	global_load_dwordx2 v[200:201], v[140:141], off offset:288
	v_or_b32_e32 v138, 16, v136
	v_ashrrev_i32_e32 v139, 31, v138
	v_lshlrev_b64 v[140:141], 12, v[138:139]
	v_lshl_add_u64 v[140:141], s[0:1], 0, v[140:141]
	v_lshl_add_u64 v[140:141], v[140:141], 0, v[134:135]
	global_load_dwordx2 v[190:191], v[140:141], off offset:2048
	v_lshlrev_b64 v[184:185], 11, v[138:139]
	v_lshl_add_u64 v[138:139], s[4:5], 0, v[184:185]
	v_lshl_add_u64 v[138:139], v[138:139], 0, v[134:135]
	global_load_dwordx2 v[188:189], v[138:139], off
	global_load_dwordx2 v[186:187], v[140:141], off offset:2080
	global_load_dwordx2 v[182:183], v[138:139], off offset:32
	global_load_dwordx2 v[172:173], v[140:141], off offset:2304
	global_load_dwordx2 v[170:171], v[138:139], off offset:256
	global_load_dwordx2 v[156:157], v[140:141], off offset:2336
	global_load_dwordx2 v[154:155], v[138:139], off offset:288
	v_or_b32_e32 v138, 32, v136
	v_ashrrev_i32_e32 v139, 31, v138
	v_lshlrev_b64 v[140:141], 12, v[138:139]
	v_lshl_add_u64 v[140:141], s[0:1], 0, v[140:141]
	v_lshl_add_u64 v[140:141], v[140:141], 0, v[134:135]
	global_load_dwordx2 v[180:181], v[140:141], off offset:2048
	v_lshlrev_b64 v[166:167], 11, v[138:139]
	v_lshl_add_u64 v[138:139], s[4:5], 0, v[166:167]
	v_lshl_add_u64 v[138:139], v[138:139], 0, v[134:135]
	global_load_dwordx2 v[176:177], v[138:139], off
	global_load_dwordx2 v[168:169], v[140:141], off offset:2080
	global_load_dwordx2 v[160:161], v[138:139], off offset:32
	global_load_dwordx2 v[152:153], v[140:141], off offset:2304
	global_load_dwordx2 v[148:149], v[138:139], off offset:256
	global_load_dwordx2 v[144:145], v[140:141], off offset:2336
	s_nop 0
	global_load_dwordx2 v[140:141], v[138:139], off offset:288
	v_or_b32_e32 v138, 48, v136
	v_ashrrev_i32_e32 v139, 31, v138
	v_lshlrev_b64 v[142:143], 12, v[138:139]
	v_lshl_add_u64 v[142:143], s[0:1], 0, v[142:143]
	v_lshl_add_u64 v[142:143], v[142:143], 0, v[134:135]
	global_load_dwordx2 v[178:179], v[142:143], off offset:2048
	v_lshlrev_b64 v[162:163], 11, v[138:139]
	v_lshl_add_u64 v[138:139], s[4:5], 0, v[162:163]
	v_lshl_add_u64 v[138:139], v[138:139], 0, v[134:135]
	global_load_dwordx2 v[174:175], v[138:139], off
	global_load_dwordx2 v[164:165], v[142:143], off offset:2080
	global_load_dwordx2 v[158:159], v[138:139], off offset:32
	global_load_dwordx2 v[150:151], v[142:143], off offset:2304
	global_load_dwordx2 v[146:147], v[138:139], off offset:256
	s_nop 0
	global_load_dwordx2 v[142:143], v[142:143], off offset:2336
	s_nop 0
	global_load_dwordx2 v[138:139], v[138:139], off offset:288
	s_and_b64 vcc, exec, s[2:3]
	s_mov_b32 s33, s8
	s_mov_b32 s16, s10
	s_mov_b64 s[20:21], s[14:15]
	s_mov_b64 s[18:19], s[12:13]
	s_waitcnt vmcnt(0)
; __device__ __forceinline__ unsigned cvt_pk_bf16(float lo, float hi) { unsigned r; asm volatile("s_nop 0\n\tv_cvt_pk_bf16_f32 %0, %1, %2\n\ts_nop 1" : "=v"(r) : "v"(lo), "v"(hi)); return r; }
; __device__ __forceinline__ float bflo(unsigned w) { return __uint_as_float(w << 16); }
; __device__ __forceinline__ float bfhi(unsigned w) { return __uint_as_float(w & 0xffff0000u); }
;     __device__ __forceinline__ void operator()(f32x4 (&acc)[2][2][4][2], const Unit& u, int wr, int wc, int fr, int fq) const {
;     ...
;             for (int m = 0; m < 4; ++m) { const size_t row = row0 + ai * 128 + m * 16;
; #pragma unroll
;                 for (int bj = 0; bj < 2; ++bj)
; #pragma unroll
;                     for (int n = 0; n < 2; ++n) { const int col = col0 + bj * 128 + n * 16; const u32x2 g2 = gw[m][bj][n], t2 = tw[m][bj][n];
;                         const f32x4 gv = (f32x4){bflo(g2.x), bfhi(g2.x), bflo(g2.y), bfhi(g2.y)};
;                         const f32x4 o = (f32x4){bflo(t2.x), bfhi(t2.x), bflo(t2.y), bfhi(t2.y)} + gv * acc[ai][bj][m][n];
;                         u32x2 w; w.x = cvt_pk_bf16(o[0], o[1]); w.y = cvt_pk_bf16(o[2], o[3]); *(u32x2*)(merged + row * 1024 + col) = w; } }
	v_lshlrev_b32_e32 v220, 16, v196
	v_and_b32_e32 v221, 0xffff0000, v196
	v_lshlrev_b32_e32 v218, 16, v194
	v_and_b32_e32 v219, 0xffff0000, v194
	v_lshlrev_b32_e32 v194, 16, v195
	v_and_b32_e32 v195, 0xffff0000, v195
	v_lshlrev_b32_e32 v196, 16, v197
	v_and_b32_e32 v197, 0xffff0000, v197
	v_pk_fma_f32 v[124:125], v[124:125], v[218:219], v[220:221]
	v_pk_fma_f32 v[126:127], v[126:127], v[194:195], v[196:197]
	v_cvt_pk_bf16_f32 v194, v124, v125
	v_lshl_add_u64 v[124:125], s[6:7], 0, v[212:213]
	v_cvt_pk_bf16_f32 v195, v126, v127
	v_lshl_add_u64 v[124:125], v[124:125], 0, v[134:135]
	v_lshlrev_b32_e32 v126, 16, v210
	v_and_b32_e32 v127, 0xffff0000, v210
	v_lshlrev_b32_e32 v196, 16, v208
	v_and_b32_e32 v197, 0xffff0000, v208
	global_store_dwordx2 v[124:125], v[194:195], off
	v_lshlrev_b32_e32 v194, 16, v211
	v_and_b32_e32 v195, 0xffff0000, v211
	v_lshlrev_b32_e32 v208, 16, v209
	v_and_b32_e32 v209, 0xffff0000, v209
	v_pk_fma_f32 v[120:121], v[120:121], v[126:127], v[196:197]
	v_pk_fma_f32 v[122:123], v[122:123], v[194:195], v[208:209]
	v_cvt_pk_bf16_f32 v120, v120, v121
	v_lshlrev_b32_e32 v126, 16, v204
	v_cvt_pk_bf16_f32 v121, v122, v123
	global_store_dwordx2 v[124:125], v[120:121], off offset:32
	v_lshlrev_b32_e32 v120, 16, v206
	v_and_b32_e32 v121, 0xffff0000, v206
	v_and_b32_e32 v127, 0xffff0000, v204
	v_lshlrev_b32_e32 v122, 16, v207
	v_and_b32_e32 v123, 0xffff0000, v207
	v_lshlrev_b32_e32 v194, 16, v205
	v_and_b32_e32 v195, 0xffff0000, v205
	v_pk_fma_f32 v[116:117], v[116:117], v[120:121], v[126:127]
	v_pk_fma_f32 v[118:119], v[118:119], v[122:123], v[194:195]
	v_cvt_pk_bf16_f32 v116, v116, v117
	v_lshlrev_b32_e32 v120, 16, v200
	v_cvt_pk_bf16_f32 v117, v118, v119
	global_store_dwordx2 v[124:125], v[116:117], off offset:256
	v_lshlrev_b32_e32 v116, 16, v202
	v_and_b32_e32 v117, 0xffff0000, v202
	v_and_b32_e32 v121, 0xffff0000, v200
	v_lshlrev_b32_e32 v118, 16, v203
	v_and_b32_e32 v119, 0xffff0000, v203
	v_lshlrev_b32_e32 v122, 16, v201
	v_and_b32_e32 v123, 0xffff0000, v201
	v_pk_fma_f32 v[112:113], v[112:113], v[116:117], v[120:121]
	v_pk_fma_f32 v[114:115], v[114:115], v[118:119], v[122:123]
	v_cvt_pk_bf16_f32 v112, v112, v113
	v_lshlrev_b32_e32 v116, 16, v188
	v_cvt_pk_bf16_f32 v113, v114, v115
	global_store_dwordx2 v[124:125], v[112:113], off offset:288
	v_lshlrev_b32_e32 v112, 16, v190
	v_and_b32_e32 v113, 0xffff0000, v190
	v_lshlrev_b32_e32 v114, 16, v191
	v_and_b32_e32 v115, 0xffff0000, v191
	v_and_b32_e32 v117, 0xffff0000, v188
	v_lshlrev_b32_e32 v118, 16, v189
	v_and_b32_e32 v119, 0xffff0000, v189
	v_pk_fma_f32 v[110:111], v[110:111], v[114:115], v[118:119]
	v_pk_fma_f32 v[108:109], v[108:109], v[112:113], v[116:117]
	v_lshlrev_b32_e32 v114, 16, v182
	v_cvt_pk_bf16_f32 v108, v108, v109
	v_cvt_pk_bf16_f32 v109, v110, v111
	v_lshl_add_u64 v[110:111], s[6:7], 0, v[184:185]
	v_lshl_add_u64 v[110:111], v[110:111], 0, v[134:135]
	global_store_dwordx2 v[110:111], v[108:109], off
	v_lshlrev_b32_e32 v108, 16, v186
	v_and_b32_e32 v109, 0xffff0000, v186
	v_and_b32_e32 v115, 0xffff0000, v182
	v_lshlrev_b32_e32 v112, 16, v187
	v_and_b32_e32 v113, 0xffff0000, v187
	v_lshlrev_b32_e32 v116, 16, v183
	v_and_b32_e32 v117, 0xffff0000, v183
	v_pk_fma_f32 v[104:105], v[104:105], v[108:109], v[114:115]
	v_pk_fma_f32 v[106:107], v[106:107], v[112:113], v[116:117]
	v_cvt_pk_bf16_f32 v104, v104, v105
	v_lshlrev_b32_e32 v108, 16, v170
	v_cvt_pk_bf16_f32 v105, v106, v107
	global_store_dwordx2 v[110:111], v[104:105], off offset:32
	v_lshlrev_b32_e32 v104, 16, v172
	v_and_b32_e32 v105, 0xffff0000, v172
	v_and_b32_e32 v109, 0xffff0000, v170
	v_lshlrev_b32_e32 v106, 16, v173
	v_and_b32_e32 v107, 0xffff0000, v173
	v_lshlrev_b32_e32 v112, 16, v171
	v_and_b32_e32 v113, 0xffff0000, v171
	v_pk_fma_f32 v[100:101], v[100:101], v[104:105], v[108:109]
	v_pk_fma_f32 v[102:103], v[102:103], v[106:107], v[112:113]
	v_cvt_pk_bf16_f32 v100, v100, v101
	v_lshlrev_b32_e32 v104, 16, v154
	v_cvt_pk_bf16_f32 v101, v102, v103
	global_store_dwordx2 v[110:111], v[100:101], off offset:256
	v_lshlrev_b32_e32 v100, 16, v156
	v_and_b32_e32 v101, 0xffff0000, v156
	v_and_b32_e32 v105, 0xffff0000, v154
	v_lshlrev_b32_e32 v102, 16, v157
	v_and_b32_e32 v103, 0xffff0000, v157
	v_lshlrev_b32_e32 v106, 16, v155
	v_and_b32_e32 v107, 0xffff0000, v155
	v_pk_fma_f32 v[96:97], v[96:97], v[100:101], v[104:105]
	v_pk_fma_f32 v[98:99], v[98:99], v[102:103], v[106:107]
	v_cvt_pk_bf16_f32 v96, v96, v97
	v_lshlrev_b32_e32 v100, 16, v176
	v_cvt_pk_bf16_f32 v97, v98, v99
	global_store_dwordx2 v[110:111], v[96:97], off offset:288
	v_lshlrev_b32_e32 v96, 16, v180
	v_and_b32_e32 v97, 0xffff0000, v180
	v_lshlrev_b32_e32 v98, 16, v181
	v_and_b32_e32 v99, 0xffff0000, v181
	v_and_b32_e32 v101, 0xffff0000, v176
	v_lshlrev_b32_e32 v102, 16, v177
	v_and_b32_e32 v103, 0xffff0000, v177
	v_pk_fma_f32 v[94:95], v[94:95], v[98:99], v[102:103]
	v_pk_fma_f32 v[92:93], v[92:93], v[96:97], v[100:101]
	v_lshlrev_b32_e32 v98, 16, v160
	v_cvt_pk_bf16_f32 v92, v92, v93
	v_cvt_pk_bf16_f32 v93, v94, v95
	v_lshl_add_u64 v[94:95], s[6:7], 0, v[166:167]
	v_lshl_add_u64 v[94:95], v[94:95], 0, v[134:135]
	global_store_dwordx2 v[94:95], v[92:93], off
	v_lshlrev_b32_e32 v92, 16, v168
	v_and_b32_e32 v93, 0xffff0000, v168
	v_and_b32_e32 v99, 0xffff0000, v160
	v_lshlrev_b32_e32 v96, 16, v169
	v_and_b32_e32 v97, 0xffff0000, v169
	v_lshlrev_b32_e32 v100, 16, v161
	v_and_b32_e32 v101, 0xffff0000, v161
	v_pk_fma_f32 v[88:89], v[88:89], v[92:93], v[98:99]
	v_pk_fma_f32 v[90:91], v[90:91], v[96:97], v[100:101]
	v_cvt_pk_bf16_f32 v88, v88, v89
	v_lshlrev_b32_e32 v92, 16, v148
	v_cvt_pk_bf16_f32 v89, v90, v91
	global_store_dwordx2 v[94:95], v[88:89], off offset:32
; __device__ __forceinline__ unsigned cvt_pk_bf16(float lo, float hi) { unsigned r; asm volatile("s_nop 0\n\tv_cvt_pk_bf16_f32 %0, %1, %2\n\ts_nop 1" : "=v"(r) : "v"(lo), "v"(hi)); return r; }
; __device__ __forceinline__ float bflo(unsigned w) { return __uint_as_float(w << 16); }
; __device__ __forceinline__ float bfhi(unsigned w) { return __uint_as_float(w & 0xffff0000u); }
;     __device__ __forceinline__ void operator()(f32x4 (&acc)[2][2][4][2], const Unit& u, int wr, int wc, int fr, int fq) const {
;     ...
;         for (int ai = 0; ai < 2; ++ai) {
;             u32x2 gw[4][2][2], tw[4][2][2];
; #pragma unroll
;             for (int m = 0; m < 4; ++m)
; #pragma unroll
;                 for (int bj = 0; bj < 2; ++bj)
; #pragma unroll
;                     for (int n = 0; n < 2; ++n) { const size_t row = row0 + ai * 128 + m * 16; const int col = col0 + bj * 128 + n * 16;
;                         gw[m][bj][n] = *(const u32x2*)(gates + row * 2048 + 1024 + col); tw[m][bj][n] = *(const u32x2*)(tmp + row * 1024 + col); }
; #pragma unroll
;             for (int m = 0; m < 4; ++m) { const size_t row = row0 + ai * 128 + m * 16;
; #pragma unroll
;                 for (int bj = 0; bj < 2; ++bj)
; #pragma unroll
;                     for (int n = 0; n < 2; ++n) { const int col = col0 + bj * 128 + n * 16; const u32x2 g2 = gw[m][bj][n], t2 = tw[m][bj][n];
;                         const f32x4 gv = (f32x4){bflo(g2.x), bfhi(g2.x), bflo(g2.y), bfhi(g2.y)};
;                         const f32x4 o = (f32x4){bflo(t2.x), bfhi(t2.x), bflo(t2.y), bfhi(t2.y)} + gv * acc[ai][bj][m][n];
;                         u32x2 w; w.x = cvt_pk_bf16(o[0], o[1]); w.y = cvt_pk_bf16(o[2], o[3]); *(u32x2*)(merged + row * 1024 + col) = w; } }
	v_lshlrev_b32_e32 v88, 16, v152
	v_and_b32_e32 v89, 0xffff0000, v152
	v_and_b32_e32 v93, 0xffff0000, v148
	v_lshlrev_b32_e32 v90, 16, v153
	v_and_b32_e32 v91, 0xffff0000, v153
	v_lshlrev_b32_e32 v96, 16, v149
	v_and_b32_e32 v97, 0xffff0000, v149
	v_pk_fma_f32 v[84:85], v[84:85], v[88:89], v[92:93]
	v_pk_fma_f32 v[86:87], v[86:87], v[90:91], v[96:97]
	v_cvt_pk_bf16_f32 v84, v84, v85
	v_lshlrev_b32_e32 v88, 16, v140
	v_cvt_pk_bf16_f32 v85, v86, v87
	global_store_dwordx2 v[94:95], v[84:85], off offset:256
	v_lshlrev_b32_e32 v84, 16, v144
	v_and_b32_e32 v85, 0xffff0000, v144
	v_and_b32_e32 v89, 0xffff0000, v140
	v_lshlrev_b32_e32 v86, 16, v145
	v_and_b32_e32 v87, 0xffff0000, v145
	v_lshlrev_b32_e32 v90, 16, v141
	v_and_b32_e32 v91, 0xffff0000, v141
	v_pk_fma_f32 v[80:81], v[80:81], v[84:85], v[88:89]
	v_pk_fma_f32 v[82:83], v[82:83], v[86:87], v[90:91]
	v_cvt_pk_bf16_f32 v80, v80, v81
	v_lshlrev_b32_e32 v84, 16, v174
	v_cvt_pk_bf16_f32 v81, v82, v83
	global_store_dwordx2 v[94:95], v[80:81], off offset:288
	v_lshlrev_b32_e32 v80, 16, v178
	v_and_b32_e32 v81, 0xffff0000, v178
	v_lshlrev_b32_e32 v82, 16, v179
	v_and_b32_e32 v83, 0xffff0000, v179
	v_and_b32_e32 v85, 0xffff0000, v174
	v_lshlrev_b32_e32 v86, 16, v175
	v_and_b32_e32 v87, 0xffff0000, v175
	v_pk_fma_f32 v[78:79], v[78:79], v[82:83], v[86:87]
	v_pk_fma_f32 v[76:77], v[76:77], v[80:81], v[84:85]
	v_lshlrev_b32_e32 v82, 16, v158
	v_cvt_pk_bf16_f32 v76, v76, v77
	v_cvt_pk_bf16_f32 v77, v78, v79
	v_lshl_add_u64 v[78:79], s[6:7], 0, v[162:163]
	v_lshl_add_u64 v[78:79], v[78:79], 0, v[134:135]
	global_store_dwordx2 v[78:79], v[76:77], off
	v_lshlrev_b32_e32 v76, 16, v164
	v_and_b32_e32 v77, 0xffff0000, v164
	v_and_b32_e32 v83, 0xffff0000, v158
	v_lshlrev_b32_e32 v80, 16, v165
	v_and_b32_e32 v81, 0xffff0000, v165
	v_lshlrev_b32_e32 v84, 16, v159
	v_and_b32_e32 v85, 0xffff0000, v159
	v_pk_fma_f32 v[72:73], v[72:73], v[76:77], v[82:83]
	v_pk_fma_f32 v[74:75], v[74:75], v[80:81], v[84:85]
	v_cvt_pk_bf16_f32 v72, v72, v73
	v_lshlrev_b32_e32 v76, 16, v146
	v_cvt_pk_bf16_f32 v73, v74, v75
	global_store_dwordx2 v[78:79], v[72:73], off offset:32
	v_lshlrev_b32_e32 v72, 16, v150
	v_and_b32_e32 v73, 0xffff0000, v150
	v_and_b32_e32 v77, 0xffff0000, v146
	v_lshlrev_b32_e32 v74, 16, v151
	v_and_b32_e32 v75, 0xffff0000, v151
	v_lshlrev_b32_e32 v80, 16, v147
	v_and_b32_e32 v81, 0xffff0000, v147
	v_pk_fma_f32 v[68:69], v[68:69], v[72:73], v[76:77]
	v_pk_fma_f32 v[70:71], v[70:71], v[74:75], v[80:81]
	v_cvt_pk_bf16_f32 v68, v68, v69
	v_lshlrev_b32_e32 v72, 16, v138
	v_cvt_pk_bf16_f32 v69, v70, v71
	global_store_dwordx2 v[78:79], v[68:69], off offset:256
	v_lshlrev_b32_e32 v68, 16, v142
	v_and_b32_e32 v69, 0xffff0000, v142
	v_and_b32_e32 v73, 0xffff0000, v138
	v_pk_fma_f32 v[64:65], v[64:65], v[68:69], v[72:73]
	v_lshlrev_b32_e32 v70, 16, v143
	v_and_b32_e32 v71, 0xffff0000, v143
	v_lshlrev_b32_e32 v74, 16, v139
	v_and_b32_e32 v75, 0xffff0000, v139
	v_cvt_pk_bf16_f32 v64, v64, v65
	v_pk_fma_f32 v[66:67], v[66:67], v[70:71], v[74:75]
	s_nop 0
	v_cvt_pk_bf16_f32 v65, v66, v67
	global_store_dwordx2 v[78:79], v[64:65], off offset:288
	v_add_u32_e32 v64, 0x80, v136
	v_ashrrev_i32_e32 v65, 31, v64
	v_lshlrev_b64 v[66:67], 12, v[64:65]
	v_lshl_add_u64 v[66:67], s[0:1], 0, v[66:67]
	v_lshl_add_u64 v[66:67], v[66:67], 0, v[134:135]
	global_load_dwordx2 v[116:117], v[66:67], off offset:2048
	v_lshlrev_b64 v[114:115], 11, v[64:65]
	v_lshl_add_u64 v[64:65], s[4:5], 0, v[114:115]
	v_lshl_add_u64 v[64:65], v[64:65], 0, v[134:135]
	global_load_dwordx2 v[118:119], v[64:65], off
	global_load_dwordx2 v[120:121], v[66:67], off offset:2080
	global_load_dwordx2 v[122:123], v[64:65], off offset:32
	global_load_dwordx2 v[124:125], v[66:67], off offset:2304
	global_load_dwordx2 v[126:127], v[64:65], off offset:256
	global_load_dwordx2 v[138:139], v[66:67], off offset:2336
	global_load_dwordx2 v[140:141], v[64:65], off offset:288
	v_add_u32_e32 v64, 0x90, v136
	v_ashrrev_i32_e32 v65, 31, v64
	v_lshlrev_b64 v[66:67], 12, v[64:65]
	v_lshl_add_u64 v[66:67], s[0:1], 0, v[66:67]
	v_lshl_add_u64 v[66:67], v[66:67], 0, v[134:135]
	global_load_dwordx2 v[142:143], v[66:67], off offset:2048
	v_lshlrev_b64 v[108:109], 11, v[64:65]
	v_lshl_add_u64 v[64:65], s[4:5], 0, v[108:109]
	v_lshl_add_u64 v[64:65], v[64:65], 0, v[134:135]
	global_load_dwordx2 v[144:145], v[64:65], off
	global_load_dwordx2 v[112:113], v[66:67], off offset:2080
	global_load_dwordx2 v[110:111], v[64:65], off offset:32
	global_load_dwordx2 v[106:107], v[66:67], off offset:2304
	global_load_dwordx2 v[104:105], v[64:65], off offset:256
	global_load_dwordx2 v[100:101], v[66:67], off offset:2336
	global_load_dwordx2 v[102:103], v[64:65], off offset:288
	v_add_u32_e32 v64, 0xa0, v136
	v_ashrrev_i32_e32 v65, 31, v64
	v_lshlrev_b64 v[66:67], 12, v[64:65]
	v_lshl_add_u64 v[66:67], s[0:1], 0, v[66:67]
	v_lshl_add_u64 v[66:67], v[66:67], 0, v[134:135]
	global_load_dwordx2 v[96:97], v[66:67], off offset:2048
	v_lshlrev_b64 v[90:91], 11, v[64:65]
	v_lshl_add_u64 v[64:65], s[4:5], 0, v[90:91]
	v_lshl_add_u64 v[64:65], v[64:65], 0, v[134:135]
	global_load_dwordx2 v[98:99], v[64:65], off
	global_load_dwordx2 v[94:95], v[66:67], off offset:2080
	global_load_dwordx2 v[92:93], v[64:65], off offset:32
	global_load_dwordx2 v[88:89], v[66:67], off offset:2304
	global_load_dwordx2 v[86:87], v[64:65], off offset:256
	global_load_dwordx2 v[82:83], v[66:67], off offset:2336
	global_load_dwordx2 v[84:85], v[64:65], off offset:288
	v_add_u32_e32 v64, 0xb0, v136
	v_ashrrev_i32_e32 v65, 31, v64
	v_lshlrev_b64 v[66:67], 12, v[64:65]
	v_lshl_add_u64 v[66:67], s[0:1], 0, v[66:67]
	v_lshl_add_u64 v[66:67], v[66:67], 0, v[134:135]
	global_load_dwordx2 v[78:79], v[66:67], off offset:2048
	v_lshlrev_b64 v[72:73], 11, v[64:65]
	v_lshl_add_u64 v[64:65], s[4:5], 0, v[72:73]
	v_lshl_add_u64 v[136:137], v[64:65], 0, v[134:135]
	global_load_dwordx2 v[80:81], v[136:137], off
	global_load_dwordx2 v[76:77], v[66:67], off offset:2080
	global_load_dwordx2 v[74:75], v[136:137], off offset:32
	global_load_dwordx2 v[70:71], v[66:67], off offset:2304
	global_load_dwordx2 v[68:69], v[136:137], off offset:256
	global_load_dwordx2 v[64:65], v[66:67], off offset:2336
	s_nop 0
	global_load_dwordx2 v[66:67], v[136:137], off offset:288
	s_waitcnt vmcnt(0)
; __device__ __forceinline__ unsigned cvt_pk_bf16(float lo, float hi) { unsigned r; asm volatile("s_nop 0\n\tv_cvt_pk_bf16_f32 %0, %1, %2\n\ts_nop 1" : "=v"(r) : "v"(lo), "v"(hi)); return r; }
; __device__ __forceinline__ float bflo(unsigned w) { return __uint_as_float(w << 16); }
; __device__ __forceinline__ float bfhi(unsigned w) { return __uint_as_float(w & 0xffff0000u); }
;     __device__ __forceinline__ void operator()(f32x4 (&acc)[2][2][4][2], const Unit& u, int wr, int wc, int fr, int fq) const {
;     ...
;             for (int m = 0; m < 4; ++m) { const size_t row = row0 + ai * 128 + m * 16;
; #pragma unroll
;                 for (int bj = 0; bj < 2; ++bj)
; #pragma unroll
;                     for (int n = 0; n < 2; ++n) { const int col = col0 + bj * 128 + n * 16; const u32x2 g2 = gw[m][bj][n], t2 = tw[m][bj][n];
;                         const f32x4 gv = (f32x4){bflo(g2.x), bfhi(g2.x), bflo(g2.y), bfhi(g2.y)};
;                         const f32x4 o = (f32x4){bflo(t2.x), bfhi(t2.x), bflo(t2.y), bfhi(t2.y)} + gv * acc[ai][bj][m][n];
;                         u32x2 w; w.x = cvt_pk_bf16(o[0], o[1]); w.y = cvt_pk_bf16(o[2], o[3]); *(u32x2*)(merged + row * 1024 + col) = w; } }
	v_lshlrev_b32_e32 v146, 16, v118
	v_and_b32_e32 v147, 0xffff0000, v118
	v_lshlrev_b32_e32 v136, 16, v116
	v_and_b32_e32 v137, 0xffff0000, v116
	v_lshlrev_b32_e32 v116, 16, v117
	v_and_b32_e32 v117, 0xffff0000, v117
	v_lshlrev_b32_e32 v118, 16, v119
	v_and_b32_e32 v119, 0xffff0000, v119
	v_pk_fma_f32 v[62:63], v[62:63], v[116:117], v[118:119]
	v_pk_fma_f32 v[60:61], v[60:61], v[136:137], v[146:147]
	v_lshlrev_b32_e32 v116, 16, v122
	v_cvt_pk_bf16_f32 v60, v60, v61
	v_cvt_pk_bf16_f32 v61, v62, v63
	v_lshl_add_u64 v[62:63], s[6:7], 0, v[114:115]
	v_lshl_add_u64 v[62:63], v[62:63], 0, v[134:135]
	global_store_dwordx2 v[62:63], v[60:61], off
	v_lshlrev_b32_e32 v60, 16, v120
	v_and_b32_e32 v61, 0xffff0000, v120
	v_and_b32_e32 v117, 0xffff0000, v122
	v_lshlrev_b32_e32 v114, 16, v121
	v_and_b32_e32 v115, 0xffff0000, v121
	v_lshlrev_b32_e32 v118, 16, v123
	v_and_b32_e32 v119, 0xffff0000, v123
	v_pk_fma_f32 v[56:57], v[56:57], v[60:61], v[116:117]
	v_pk_fma_f32 v[58:59], v[58:59], v[114:115], v[118:119]
	v_cvt_pk_bf16_f32 v56, v56, v57
	v_lshlrev_b32_e32 v60, 16, v126
	v_cvt_pk_bf16_f32 v57, v58, v59
	global_store_dwordx2 v[62:63], v[56:57], off offset:32
	v_lshlrev_b32_e32 v56, 16, v124
	v_and_b32_e32 v57, 0xffff0000, v124
	v_and_b32_e32 v61, 0xffff0000, v126
	v_lshlrev_b32_e32 v58, 16, v125
	v_and_b32_e32 v59, 0xffff0000, v125
	v_lshlrev_b32_e32 v114, 16, v127
	v_and_b32_e32 v115, 0xffff0000, v127
	v_pk_fma_f32 v[52:53], v[52:53], v[56:57], v[60:61]
	v_pk_fma_f32 v[54:55], v[54:55], v[58:59], v[114:115]
	v_cvt_pk_bf16_f32 v52, v52, v53
	v_lshlrev_b32_e32 v56, 16, v140
	v_cvt_pk_bf16_f32 v53, v54, v55
	global_store_dwordx2 v[62:63], v[52:53], off offset:256
	v_lshlrev_b32_e32 v52, 16, v138
	v_and_b32_e32 v53, 0xffff0000, v138
	v_and_b32_e32 v57, 0xffff0000, v140
	v_lshlrev_b32_e32 v54, 16, v139
	v_and_b32_e32 v55, 0xffff0000, v139
	v_lshlrev_b32_e32 v58, 16, v141
	v_and_b32_e32 v59, 0xffff0000, v141
	v_pk_fma_f32 v[48:49], v[48:49], v[52:53], v[56:57]
	v_pk_fma_f32 v[50:51], v[50:51], v[54:55], v[58:59]
	v_cvt_pk_bf16_f32 v48, v48, v49
	v_lshlrev_b32_e32 v52, 16, v144
	v_cvt_pk_bf16_f32 v49, v50, v51
	global_store_dwordx2 v[62:63], v[48:49], off offset:288
	v_lshlrev_b32_e32 v48, 16, v142
	v_and_b32_e32 v49, 0xffff0000, v142
	v_lshlrev_b32_e32 v50, 16, v143
	v_and_b32_e32 v51, 0xffff0000, v143
	v_and_b32_e32 v53, 0xffff0000, v144
	v_lshlrev_b32_e32 v54, 16, v145
	v_and_b32_e32 v55, 0xffff0000, v145
	v_pk_fma_f32 v[46:47], v[46:47], v[50:51], v[54:55]
	v_pk_fma_f32 v[44:45], v[44:45], v[48:49], v[52:53]
	v_lshlrev_b32_e32 v50, 16, v110
	v_cvt_pk_bf16_f32 v44, v44, v45
	v_cvt_pk_bf16_f32 v45, v46, v47
	v_lshl_add_u64 v[46:47], s[6:7], 0, v[108:109]
	v_lshl_add_u64 v[46:47], v[46:47], 0, v[134:135]
	global_store_dwordx2 v[46:47], v[44:45], off
	v_lshlrev_b32_e32 v44, 16, v112
	v_and_b32_e32 v45, 0xffff0000, v112
	v_and_b32_e32 v51, 0xffff0000, v110
	v_lshlrev_b32_e32 v48, 16, v113
	v_and_b32_e32 v49, 0xffff0000, v113
	v_lshlrev_b32_e32 v52, 16, v111
	v_and_b32_e32 v53, 0xffff0000, v111
	v_pk_fma_f32 v[40:41], v[40:41], v[44:45], v[50:51]
	v_pk_fma_f32 v[42:43], v[42:43], v[48:49], v[52:53]
	v_cvt_pk_bf16_f32 v40, v40, v41
	v_lshlrev_b32_e32 v44, 16, v104
	v_cvt_pk_bf16_f32 v41, v42, v43
	global_store_dwordx2 v[46:47], v[40:41], off offset:32
	v_lshlrev_b32_e32 v40, 16, v106
	v_and_b32_e32 v41, 0xffff0000, v106
	v_and_b32_e32 v45, 0xffff0000, v104
	v_lshlrev_b32_e32 v42, 16, v107
	v_and_b32_e32 v43, 0xffff0000, v107
	v_lshlrev_b32_e32 v48, 16, v105
	v_and_b32_e32 v49, 0xffff0000, v105
	v_pk_fma_f32 v[36:37], v[36:37], v[40:41], v[44:45]
	v_pk_fma_f32 v[38:39], v[38:39], v[42:43], v[48:49]
	v_cvt_pk_bf16_f32 v36, v36, v37
	v_lshlrev_b32_e32 v40, 16, v102
	v_cvt_pk_bf16_f32 v37, v38, v39
	global_store_dwordx2 v[46:47], v[36:37], off offset:256
	v_lshlrev_b32_e32 v36, 16, v100
	v_and_b32_e32 v37, 0xffff0000, v100
	v_and_b32_e32 v41, 0xffff0000, v102
	v_lshlrev_b32_e32 v38, 16, v101
	v_and_b32_e32 v39, 0xffff0000, v101
	v_lshlrev_b32_e32 v42, 16, v103
	v_and_b32_e32 v43, 0xffff0000, v103
	v_pk_fma_f32 v[32:33], v[32:33], v[36:37], v[40:41]
	v_pk_fma_f32 v[34:35], v[34:35], v[38:39], v[42:43]
	v_cvt_pk_bf16_f32 v32, v32, v33
	v_lshlrev_b32_e32 v36, 16, v98
	v_cvt_pk_bf16_f32 v33, v34, v35
; __device__ __forceinline__ unsigned cvt_pk_bf16(float lo, float hi) { unsigned r; asm volatile("s_nop 0\n\tv_cvt_pk_bf16_f32 %0, %1, %2\n\ts_nop 1" : "=v"(r) : "v"(lo), "v"(hi)); return r; }
; #define PG8_WAIT_V(n) asm volatile("s_waitcnt vmcnt(" #n ")" ::: "memory")
; #define PG8_BAR __builtin_amdgcn_s_barrier()
; __device__ __forceinline__ float bflo(unsigned w) { return __uint_as_float(w << 16); }
; __device__ __forceinline__ float bfhi(unsigned w) { return __uint_as_float(w & 0xffff0000u); }
; template <class Epi, class Sched>
; __device__ __forceinline__ void gemm_phase(PG8_LAS unsigned char* lds, const Gemm g, const Sched& S, const Epi& E, int tid_in) {
;     ...
;     PG8_WAIT_V(0);
;     if (wr == 0) PG8_BAR;
;     __device__ __forceinline__ void operator()(f32x4 (&acc)[2][2][4][2], const Unit& u, int wr, int wc, int fr, int fq) const {
;     ...
;             for (int m = 0; m < 4; ++m) { const size_t row = row0 + ai * 128 + m * 16;
; #pragma unroll
;                 for (int bj = 0; bj < 2; ++bj)
; #pragma unroll
;                     for (int n = 0; n < 2; ++n) { const int col = col0 + bj * 128 + n * 16; const u32x2 g2 = gw[m][bj][n], t2 = tw[m][bj][n];
;                         const f32x4 gv = (f32x4){bflo(g2.x), bfhi(g2.x), bflo(g2.y), bfhi(g2.y)};
;                         const f32x4 o = (f32x4){bflo(t2.x), bfhi(t2.x), bflo(t2.y), bfhi(t2.y)} + gv * acc[ai][bj][m][n];
;                         u32x2 w; w.x = cvt_pk_bf16(o[0], o[1]); w.y = cvt_pk_bf16(o[2], o[3]); *(u32x2*)(merged + row * 1024 + col) = w; } }
	global_store_dwordx2 v[46:47], v[32:33], off offset:288
	v_lshlrev_b32_e32 v32, 16, v96
	v_and_b32_e32 v33, 0xffff0000, v96
	v_lshlrev_b32_e32 v34, 16, v97
	v_and_b32_e32 v35, 0xffff0000, v97
	v_and_b32_e32 v37, 0xffff0000, v98
	v_lshlrev_b32_e32 v38, 16, v99
	v_and_b32_e32 v39, 0xffff0000, v99
	v_pk_fma_f32 v[30:31], v[30:31], v[34:35], v[38:39]
	v_pk_fma_f32 v[28:29], v[28:29], v[32:33], v[36:37]
	v_lshlrev_b32_e32 v34, 16, v92
	v_cvt_pk_bf16_f32 v28, v28, v29
	v_cvt_pk_bf16_f32 v29, v30, v31
	v_lshl_add_u64 v[30:31], s[6:7], 0, v[90:91]
	v_lshl_add_u64 v[30:31], v[30:31], 0, v[134:135]
	global_store_dwordx2 v[30:31], v[28:29], off
	v_lshlrev_b32_e32 v28, 16, v94
	v_and_b32_e32 v29, 0xffff0000, v94
	v_and_b32_e32 v35, 0xffff0000, v92
	v_lshlrev_b32_e32 v32, 16, v95
	v_and_b32_e32 v33, 0xffff0000, v95
	v_lshlrev_b32_e32 v36, 16, v93
	v_and_b32_e32 v37, 0xffff0000, v93
	v_pk_fma_f32 v[24:25], v[24:25], v[28:29], v[34:35]
	v_pk_fma_f32 v[26:27], v[26:27], v[32:33], v[36:37]
	v_cvt_pk_bf16_f32 v24, v24, v25
	v_lshlrev_b32_e32 v28, 16, v86
	v_cvt_pk_bf16_f32 v25, v26, v27
	global_store_dwordx2 v[30:31], v[24:25], off offset:32
	v_lshlrev_b32_e32 v24, 16, v88
	v_and_b32_e32 v25, 0xffff0000, v88
	v_and_b32_e32 v29, 0xffff0000, v86
	v_lshlrev_b32_e32 v26, 16, v89
	v_and_b32_e32 v27, 0xffff0000, v89
	v_lshlrev_b32_e32 v32, 16, v87
	v_and_b32_e32 v33, 0xffff0000, v87
	v_pk_fma_f32 v[20:21], v[20:21], v[24:25], v[28:29]
	v_pk_fma_f32 v[22:23], v[22:23], v[26:27], v[32:33]
	v_cvt_pk_bf16_f32 v20, v20, v21
	v_lshlrev_b32_e32 v24, 16, v84
	v_cvt_pk_bf16_f32 v21, v22, v23
	global_store_dwordx2 v[30:31], v[20:21], off offset:256
	v_lshlrev_b32_e32 v20, 16, v82
	v_and_b32_e32 v21, 0xffff0000, v82
	v_and_b32_e32 v25, 0xffff0000, v84
	v_lshlrev_b32_e32 v22, 16, v83
	v_and_b32_e32 v23, 0xffff0000, v83
	v_lshlrev_b32_e32 v26, 16, v85
	v_and_b32_e32 v27, 0xffff0000, v85
	v_pk_fma_f32 v[16:17], v[16:17], v[20:21], v[24:25]
	v_pk_fma_f32 v[18:19], v[18:19], v[22:23], v[26:27]
	v_cvt_pk_bf16_f32 v16, v16, v17
	v_lshlrev_b32_e32 v20, 16, v80
	v_cvt_pk_bf16_f32 v17, v18, v19
	global_store_dwordx2 v[30:31], v[16:17], off offset:288
	v_lshlrev_b32_e32 v16, 16, v78
	v_and_b32_e32 v17, 0xffff0000, v78
	v_lshlrev_b32_e32 v18, 16, v79
	v_and_b32_e32 v19, 0xffff0000, v79
	v_and_b32_e32 v21, 0xffff0000, v80
	v_lshlrev_b32_e32 v22, 16, v81
	v_and_b32_e32 v23, 0xffff0000, v81
	v_pk_fma_f32 v[14:15], v[14:15], v[18:19], v[22:23]
	v_pk_fma_f32 v[12:13], v[12:13], v[16:17], v[20:21]
	v_lshlrev_b32_e32 v18, 16, v74
	v_cvt_pk_bf16_f32 v12, v12, v13
	v_cvt_pk_bf16_f32 v13, v14, v15
	v_lshl_add_u64 v[14:15], s[6:7], 0, v[72:73]
	v_lshl_add_u64 v[14:15], v[14:15], 0, v[134:135]
	global_store_dwordx2 v[14:15], v[12:13], off
	v_lshlrev_b32_e32 v12, 16, v76
	v_and_b32_e32 v13, 0xffff0000, v76
	v_and_b32_e32 v19, 0xffff0000, v74
	v_lshlrev_b32_e32 v16, 16, v77
	v_and_b32_e32 v17, 0xffff0000, v77
	v_lshlrev_b32_e32 v20, 16, v75
	v_and_b32_e32 v21, 0xffff0000, v75
	v_pk_fma_f32 v[8:9], v[8:9], v[12:13], v[18:19]
	v_pk_fma_f32 v[10:11], v[10:11], v[16:17], v[20:21]
	v_cvt_pk_bf16_f32 v8, v8, v9
	v_lshlrev_b32_e32 v12, 16, v68
	v_cvt_pk_bf16_f32 v9, v10, v11
	global_store_dwordx2 v[14:15], v[8:9], off offset:32
	v_lshlrev_b32_e32 v8, 16, v70
	v_and_b32_e32 v9, 0xffff0000, v70
	v_and_b32_e32 v13, 0xffff0000, v68
	v_lshlrev_b32_e32 v10, 16, v71
	v_and_b32_e32 v11, 0xffff0000, v71
	v_lshlrev_b32_e32 v16, 16, v69
	v_and_b32_e32 v17, 0xffff0000, v69
	v_pk_fma_f32 v[4:5], v[4:5], v[8:9], v[12:13]
	v_pk_fma_f32 v[6:7], v[6:7], v[10:11], v[16:17]
	v_cvt_pk_bf16_f32 v4, v4, v5
	v_lshlrev_b32_e32 v8, 16, v66
	v_cvt_pk_bf16_f32 v5, v6, v7
	global_store_dwordx2 v[14:15], v[4:5], off offset:256
	v_lshlrev_b32_e32 v4, 16, v64
	v_and_b32_e32 v5, 0xffff0000, v64
	v_and_b32_e32 v9, 0xffff0000, v66
	v_lshlrev_b32_e32 v6, 16, v65
	v_and_b32_e32 v7, 0xffff0000, v65
	v_lshlrev_b32_e32 v10, 16, v67
	v_and_b32_e32 v11, 0xffff0000, v67
	v_pk_fma_f32 v[0:1], v[0:1], v[4:5], v[8:9]
	v_pk_fma_f32 v[2:3], v[2:3], v[6:7], v[10:11]
	v_cvt_pk_bf16_f32 v0, v0, v1
	s_nop 0
	v_cvt_pk_bf16_f32 v1, v2, v3
	s_nop 1
	global_store_dwordx2 v[14:15], v[0:1], off offset:288
	s_cbranch_vccz .LBB0_363
	s_waitcnt vmcnt(0)
	s_cmpk_gt_u32 s24, 0xff
	s_cbranch_scc1 .LBB0_374
	s_barrier

; #define PG8_STAGE(bufoff, gbase, voff) do { _Pragma("unroll") for (int _i = 0; _i < 2; ++_i) \
;         __builtin_amdgcn_global_load_lds((const unsigned*)((const char*)(gbase) + (voff)[_i]), (PG8_LAS unsigned*)(lds + (bufoff) + ldsw + _i * 8192), 16, 0, 0); } while (0)
; #define PG8_LDA(dst, b, h) do { _Pragma("unroll") for (int m = 0; m < 4; ++m) _Pragma("unroll") for (int k = 0; k < 2; ++k) dst[m][k] = *(const PG8_LAS bf16x8*)(lds + PG8_SA(b, h) + aoff + m * 2048 + k * 1024); } while (0)
; #define PG8_LDB(dst, b, h) do { _Pragma("unroll") for (int n = 0; n < 2; ++n) _Pragma("unroll") for (int k = 0; k < 2; ++k) dst[n][k] = *(const PG8_LAS bf16x8*)(lds + PG8_SB(b, h) + boff + n * 2048 + k * 1024); } while (0)
; #define PG8_MMA(ai, bj, At, Bt) do { __builtin_amdgcn_s_setprio(1); _Pragma("unroll") for (int m = 0; m < 4; ++m) _Pragma("unroll") for (int n = 0; n < 2; ++n) _Pragma("unroll") for (int k = 0; k < 2; ++k) \
;         acc[ai][bj][m][n] = __builtin_amdgcn_mfma_f32_16x16x32_bf16(Bt[n][k], At[m][k], acc[ai][bj][m][n], 0, 0, 0); __builtin_amdgcn_s_setprio(0); } while (0)
; #define PG8_WAIT_L(n) asm volatile("s_waitcnt lgkmcnt(" #n ")" ::: "memory")
; #define PG8_BAR __builtin_amdgcn_s_barrier()
; #define PG8_SCHED __builtin_amdgcn_sched_barrier(0)
; template <class Epi, class Sched>
; __device__ __forceinline__ void gemm_phase(PG8_LAS unsigned char* lds, const Gemm g, const Sched& S, const Epi& E, int tid_in) {
;     ...
;             const bool last = (t == nt - 2);
;             const char* a1 = cA + (size_t)(t + 1) * kstep;
;             const char* a2 = last ? nA : cA + (size_t)(t + 2) * kstep; const char* b2 = last ? nB : cB + (size_t)(t + 2) * kstep;
;             const char* a3 = a2 + kstep; const char* b3 = b2 + kstep;
;             if (last && has_next) S.a_ready(nxt);
;             PG8_LDB(B0, 0, 0); PG8_SCHED; PG8_LDA(At, 0, 0); PG8_STAGE(PG8_SA(1, 1), a1 + hstep, voffA);
;             PG8_WAIT_L(8); PG8_BAR; PG8_WAIT_L(0); PG8_MMA(0, 0, At, B0); PG8_BAR; PG8_SCHED;
;             PG8_LDB(B1, 0, 1); PG8_STAGE(PG8_SB(0, 0), b2, voffB);
;             PG8_BAR; PG8_WAIT_L(0); PG8_MMA(0, 1, At, B1); PG8_BAR;
;             PG8_LDA(At, 0, 1); PG8_STAGE(PG8_SA(0, 0), a2, voffA);
;             PG8_BAR; PG8_WAIT_L(0); PG8_MMA(1, 0, At, B0); PG8_BAR; PG8_SCHED;
.LBB0_388:
	s_add_u32 s28, s26, 0xfffc0080
	s_addc_u32 s29, s27, -1
	s_add_i32 s38, 0, 0x10000
	v_add_u32_e32 v140, s38, v246
	ds_read_b128 v[128:131], v140
	ds_read_b128 v[132:135], v140 offset:1024
	ds_read_b128 v[136:139], v140 offset:2048
	ds_read_b128 v[140:143], v140 offset:3072
	s_cmp_eq_u32 s37, 12
	s_cselect_b32 s31, s1, s29
	s_cselect_b32 s30, s19, s28
	s_cselect_b32 s29, s17, s36
	s_cselect_b32 s28, s25, s33
	v_lshl_add_u64 v[176:177], s[26:27], 0, v[210:211]
	s_add_i32 m0, s73, 0xc000
	ds_read_b128 v[144:147], v251
	ds_read_b128 v[148:151], v251 offset:1024
	ds_read_b128 v[152:155], v251 offset:2048
	ds_read_b128 v[156:159], v251 offset:3072
	ds_read_b128 v[160:163], v251 offset:4096
	ds_read_b128 v[164:167], v251 offset:5120
	ds_read_b128 v[168:171], v251 offset:6144
	ds_read_b128 v[172:175], v251 offset:7168
	global_load_lds_dwordx4 v[176:177], off
	v_lshl_add_u64 v[176:177], s[26:27], 0, v[212:213]
	s_add_i32 m0, s73, 0xe000
	s_nop 0
	global_load_lds_dwordx4 v[176:177], off
	s_waitcnt lgkmcnt(8)
	s_barrier
	s_waitcnt lgkmcnt(0)
	s_waitcnt lgkmcnt(0)
	v_mfma_f32_16x16x32_bf16 v[124:127], v[128:131], v[144:147], v[124:127]
	v_mfma_f32_16x16x32_bf16 v[120:123], v[136:139], v[144:147], v[120:123]
	v_mfma_f32_16x16x32_bf16 v[108:111], v[128:131], v[152:155], v[108:111]
	v_mfma_f32_16x16x32_bf16 v[104:107], v[136:139], v[152:155], v[104:107]
	v_mfma_f32_16x16x32_bf16 v[92:95], v[128:131], v[160:163], v[92:95]
	v_mfma_f32_16x16x32_bf16 v[88:91], v[136:139], v[160:163], v[88:91]
	v_mfma_f32_16x16x32_bf16 v[76:79], v[128:131], v[168:171], v[76:79]
	v_mfma_f32_16x16x32_bf16 v[72:75], v[136:139], v[168:171], v[72:75]
	v_mfma_f32_16x16x32_bf16 v[124:127], v[132:135], v[148:151], v[124:127]
	v_mfma_f32_16x16x32_bf16 v[120:123], v[140:143], v[148:151], v[120:123]
	v_mfma_f32_16x16x32_bf16 v[108:111], v[132:135], v[156:159], v[108:111]
	v_mfma_f32_16x16x32_bf16 v[104:107], v[140:143], v[156:159], v[104:107]
	v_mfma_f32_16x16x32_bf16 v[92:95], v[132:135], v[164:167], v[92:95]
	v_mfma_f32_16x16x32_bf16 v[88:91], v[140:143], v[164:167], v[88:91]
	v_mfma_f32_16x16x32_bf16 v[76:79], v[132:135], v[172:175], v[76:79]
	v_mfma_f32_16x16x32_bf16 v[72:75], v[140:143], v[172:175], v[72:75]
	s_barrier
	s_add_i32 s40, 0, 0x14000
	s_add_i32 s38, s38, s72
	v_add_u32_e32 v188, s40, v246
	v_lshl_add_u64 v[194:195], s[28:29], 0, v[202:203]
	s_mov_b32 m0, s38
	ds_read_b128 v[176:179], v188
	ds_read_b128 v[180:183], v188 offset:1024
	ds_read_b128 v[184:187], v188 offset:2048
	ds_read_b128 v[188:191], v188 offset:3072
	global_load_lds_dwordx4 v[194:195], off
	v_lshl_add_u64 v[196:197], s[28:29], 0, v[206:207]
	s_add_i32 m0, s38, 0x2000
	s_nop 0
	global_load_lds_dwordx4 v[196:197], off
	s_barrier
	s_waitcnt lgkmcnt(0)
	s_waitcnt lgkmcnt(0)
	v_mfma_f32_16x16x32_bf16 v[116:119], v[176:179], v[144:147], v[116:119]
	v_mfma_f32_16x16x32_bf16 v[112:115], v[184:187], v[144:147], v[112:115]
	v_mfma_f32_16x16x32_bf16 v[100:103], v[176:179], v[152:155], v[100:103]
	v_mfma_f32_16x16x32_bf16 v[96:99], v[184:187], v[152:155], v[96:99]
	v_mfma_f32_16x16x32_bf16 v[84:87], v[176:179], v[160:163], v[84:87]
	v_mfma_f32_16x16x32_bf16 v[80:83], v[184:187], v[160:163], v[80:83]
	v_mfma_f32_16x16x32_bf16 v[68:71], v[176:179], v[168:171], v[68:71]
	v_mfma_f32_16x16x32_bf16 v[64:67], v[184:187], v[168:171], v[64:67]
	v_mfma_f32_16x16x32_bf16 v[116:119], v[180:183], v[148:151], v[116:119]
	v_mfma_f32_16x16x32_bf16 v[112:115], v[188:191], v[148:151], v[112:115]
	v_mfma_f32_16x16x32_bf16 v[100:103], v[180:183], v[156:159], v[100:103]
	v_mfma_f32_16x16x32_bf16 v[96:99], v[188:191], v[156:159], v[96:99]
	v_mfma_f32_16x16x32_bf16 v[84:87], v[180:183], v[164:167], v[84:87]
	v_mfma_f32_16x16x32_bf16 v[80:83], v[188:191], v[164:167], v[80:83]
	v_mfma_f32_16x16x32_bf16 v[68:71], v[180:183], v[172:175], v[68:71]
	v_mfma_f32_16x16x32_bf16 v[64:67], v[188:191], v[172:175], v[64:67]
	s_mov_b32 m0, s73
	v_lshl_add_u64 v[214:215], s[30:31], 0, v[200:201]
	s_barrier
	ds_read_b128 v[144:147], v251 offset:16384
	ds_read_b128 v[148:151], v251 offset:17408
	ds_read_b128 v[152:155], v251 offset:18432
	ds_read_b128 v[156:159], v251 offset:19456
	ds_read_b128 v[160:163], v251 offset:20480
	ds_read_b128 v[164:167], v251 offset:21504
	ds_read_b128 v[168:171], v251 offset:22528
	ds_read_b128 v[172:175], v251 offset:23552
	global_load_lds_dwordx4 v[214:215], off
	v_lshl_add_u64 v[216:217], s[30:31], 0, v[204:205]
	s_mov_b32 m0, s76
	s_nop 0
	global_load_lds_dwordx4 v[216:217], off
	s_barrier
	s_waitcnt lgkmcnt(0)
	s_waitcnt lgkmcnt(0)
	v_mfma_f32_16x16x32_bf16 v[60:63], v[128:131], v[144:147], v[60:63]
	v_mfma_f32_16x16x32_bf16 v[56:59], v[136:139], v[144:147], v[56:59]
	v_mfma_f32_16x16x32_bf16 v[44:47], v[128:131], v[152:155], v[44:47]
	v_mfma_f32_16x16x32_bf16 v[40:43], v[136:139], v[152:155], v[40:43]
	v_mfma_f32_16x16x32_bf16 v[28:31], v[128:131], v[160:163], v[28:31]
	v_mfma_f32_16x16x32_bf16 v[24:27], v[136:139], v[160:163], v[24:27]
	v_mfma_f32_16x16x32_bf16 v[12:15], v[128:131], v[168:171], v[12:15]
	v_mfma_f32_16x16x32_bf16 v[8:11], v[136:139], v[168:171], v[8:11]
	v_mfma_f32_16x16x32_bf16 v[60:63], v[132:135], v[148:151], v[60:63]
	v_mfma_f32_16x16x32_bf16 v[56:59], v[140:143], v[148:151], v[56:59]
	v_mfma_f32_16x16x32_bf16 v[44:47], v[132:135], v[156:159], v[44:47]
	v_mfma_f32_16x16x32_bf16 v[40:43], v[140:143], v[156:159], v[40:43]
	v_mfma_f32_16x16x32_bf16 v[28:31], v[132:135], v[164:167], v[28:31]
	v_mfma_f32_16x16x32_bf16 v[24:27], v[140:143], v[164:167], v[24:27]
	v_mfma_f32_16x16x32_bf16 v[12:15], v[132:135], v[172:175], v[12:15]
	v_mfma_f32_16x16x32_bf16 v[8:11], v[140:143], v[172:175], v[8:11]
	s_barrier
; #define PG8_STAGE(bufoff, gbase, voff) do { _Pragma("unroll") for (int _i = 0; _i < 2; ++_i) \
;         __builtin_amdgcn_global_load_lds((const unsigned*)((const char*)(gbase) + (voff)[_i]), (PG8_LAS unsigned*)(lds + (bufoff) + ldsw + _i * 8192), 16, 0, 0); } while (0)
; #define PG8_LDA(dst, b, h) do { _Pragma("unroll") for (int m = 0; m < 4; ++m) _Pragma("unroll") for (int k = 0; k < 2; ++k) dst[m][k] = *(const PG8_LAS bf16x8*)(lds + PG8_SA(b, h) + aoff + m * 2048 + k * 1024); } while (0)
; #define PG8_LDB(dst, b, h) do { _Pragma("unroll") for (int n = 0; n < 2; ++n) _Pragma("unroll") for (int k = 0; k < 2; ++k) dst[n][k] = *(const PG8_LAS bf16x8*)(lds + PG8_SB(b, h) + boff + n * 2048 + k * 1024); } while (0)
; #define PG8_MMA(ai, bj, At, Bt) do { __builtin_amdgcn_s_setprio(1); _Pragma("unroll") for (int m = 0; m < 4; ++m) _Pragma("unroll") for (int n = 0; n < 2; ++n) _Pragma("unroll") for (int k = 0; k < 2; ++k) \
;         acc[ai][bj][m][n] = __builtin_amdgcn_mfma_f32_16x16x32_bf16(Bt[n][k], At[m][k], acc[ai][bj][m][n], 0, 0, 0); __builtin_amdgcn_s_setprio(0); } while (0)
; #define PG8_WAIT_V(n) asm volatile("s_waitcnt vmcnt(" #n ")" ::: "memory")
; #define PG8_WAIT_L(n) asm volatile("s_waitcnt lgkmcnt(" #n ")" ::: "memory")
; #define PG8_BAR __builtin_amdgcn_s_barrier()
; #define PG8_SCHED __builtin_amdgcn_sched_barrier(0)
; template <class Epi, class Sched>
; __device__ __forceinline__ void gemm_phase(PG8_LAS unsigned char* lds, const Gemm g, const Sched& S, const Epi& E, int tid_in) {
;     ...
;             PG8_STAGE(PG8_SB(0, 1), b2 + hstep, voffB);
;             PG8_WAIT_V(6); PG8_BAR; PG8_MMA(1, 1, At, B1); PG8_BAR;
;             PG8_LDB(B0, 1, 0); PG8_SCHED; PG8_LDA(At, 1, 0); PG8_STAGE(PG8_SA(0, 1), a2 + hstep, voffA);
;             PG8_WAIT_L(8); PG8_BAR; PG8_WAIT_L(0); PG8_MMA(0, 0, At, B0); PG8_BAR; PG8_SCHED;
;             PG8_LDB(B1, 1, 1); PG8_STAGE(PG8_SB(1, 0), b3, voffB);
;             PG8_BAR; PG8_WAIT_L(0); PG8_MMA(0, 1, At, B1); PG8_BAR;
;             PG8_LDA(At, 1, 1); PG8_STAGE(PG8_SA(1, 0), a3, voffA);
	s_add_u32 s38, s28, 0x40000
	s_addc_u32 s39, s29, 0
	s_add_i32 s40, s40, s72
	v_lshl_add_u64 v[128:129], s[38:39], 0, v[202:203]
	s_mov_b32 m0, s40
	s_nop 0
	global_load_lds_dwordx4 v[128:129], off
	v_lshl_add_u64 v[128:129], s[38:39], 0, v[206:207]
	s_add_i32 m0, s40, 0x2000
	s_nop 0
	global_load_lds_dwordx4 v[128:129], off
	s_waitcnt vmcnt(6)
	s_barrier
	v_mfma_f32_16x16x32_bf16 v[52:55], v[176:179], v[144:147], v[52:55]
	v_mfma_f32_16x16x32_bf16 v[48:51], v[184:187], v[144:147], v[48:51]
	v_mfma_f32_16x16x32_bf16 v[36:39], v[176:179], v[152:155], v[36:39]
	v_mfma_f32_16x16x32_bf16 v[32:35], v[184:187], v[152:155], v[32:35]
	v_mfma_f32_16x16x32_bf16 v[20:23], v[176:179], v[160:163], v[20:23]
	v_mfma_f32_16x16x32_bf16 v[16:19], v[184:187], v[160:163], v[16:19]
	v_mfma_f32_16x16x32_bf16 v[4:7], v[176:179], v[168:171], v[4:7]
	v_mfma_f32_16x16x32_bf16 v[0:3], v[184:187], v[168:171], v[0:3]
	v_mfma_f32_16x16x32_bf16 v[52:55], v[180:183], v[148:151], v[52:55]
	v_mfma_f32_16x16x32_bf16 v[48:51], v[188:191], v[148:151], v[48:51]
	v_mfma_f32_16x16x32_bf16 v[36:39], v[180:183], v[156:159], v[36:39]
	v_mfma_f32_16x16x32_bf16 v[32:35], v[188:191], v[156:159], v[32:35]
	v_mfma_f32_16x16x32_bf16 v[20:23], v[180:183], v[164:167], v[20:23]
	v_mfma_f32_16x16x32_bf16 v[16:19], v[188:191], v[164:167], v[16:19]
	v_mfma_f32_16x16x32_bf16 v[4:7], v[180:183], v[172:175], v[4:7]
	v_mfma_f32_16x16x32_bf16 v[0:3], v[188:191], v[172:175], v[0:3]
	s_add_i32 s38, 0, 0x18000
	v_add_u32_e32 v140, s38, v246
	s_barrier
	ds_read_b128 v[128:131], v140
	ds_read_b128 v[132:135], v140 offset:1024
	ds_read_b128 v[136:139], v140 offset:2048
	ds_read_b128 v[140:143], v140 offset:3072
	s_add_u32 s30, s30, 0x40000
	s_addc_u32 s31, s31, 0
	s_mov_b32 m0, s77
	v_lshl_add_u64 v[176:177], s[30:31], 0, v[200:201]
	ds_read_b128 v[144:147], v251 offset:32768
	ds_read_b128 v[148:151], v251 offset:33792
	ds_read_b128 v[152:155], v251 offset:34816
	ds_read_b128 v[156:159], v251 offset:35840
	ds_read_b128 v[160:163], v251 offset:36864
	ds_read_b128 v[164:167], v251 offset:37888
	ds_read_b128 v[168:171], v251 offset:38912
	ds_read_b128 v[172:175], v251 offset:39936
	global_load_lds_dwordx4 v[176:177], off
	v_lshl_add_u64 v[176:177], s[30:31], 0, v[204:205]
	s_mov_b32 m0, s78
	s_nop 0
	global_load_lds_dwordx4 v[176:177], off
	s_waitcnt lgkmcnt(8)
	s_barrier
	s_waitcnt lgkmcnt(0)
	s_waitcnt lgkmcnt(0)
	v_mfma_f32_16x16x32_bf16 v[124:127], v[128:131], v[144:147], v[124:127]
	v_mfma_f32_16x16x32_bf16 v[120:123], v[136:139], v[144:147], v[120:123]
	v_mfma_f32_16x16x32_bf16 v[108:111], v[128:131], v[152:155], v[108:111]
	v_mfma_f32_16x16x32_bf16 v[104:107], v[136:139], v[152:155], v[104:107]
	v_mfma_f32_16x16x32_bf16 v[92:95], v[128:131], v[160:163], v[92:95]
	v_mfma_f32_16x16x32_bf16 v[88:91], v[136:139], v[160:163], v[88:91]
	v_mfma_f32_16x16x32_bf16 v[76:79], v[128:131], v[168:171], v[76:79]
	v_mfma_f32_16x16x32_bf16 v[72:75], v[136:139], v[168:171], v[72:75]
	v_mfma_f32_16x16x32_bf16 v[124:127], v[132:135], v[148:151], v[124:127]
	v_mfma_f32_16x16x32_bf16 v[120:123], v[140:143], v[148:151], v[120:123]
	v_mfma_f32_16x16x32_bf16 v[108:111], v[132:135], v[156:159], v[108:111]
	v_mfma_f32_16x16x32_bf16 v[104:107], v[140:143], v[156:159], v[104:107]
	v_mfma_f32_16x16x32_bf16 v[92:95], v[132:135], v[164:167], v[92:95]
	v_mfma_f32_16x16x32_bf16 v[88:91], v[140:143], v[164:167], v[88:91]
	v_mfma_f32_16x16x32_bf16 v[76:79], v[132:135], v[172:175], v[76:79]
	v_mfma_f32_16x16x32_bf16 v[72:75], v[140:143], v[172:175], v[72:75]
	s_barrier
	s_add_i32 s30, 0, 0x1c000
	s_add_i32 s31, s38, s72
	v_add_u32_e32 v188, s30, v246
	v_lshl_add_u64 v[194:195], v[194:195], 0, s[74:75]
	s_mov_b32 m0, s31
	ds_read_b128 v[176:179], v188
	ds_read_b128 v[180:183], v188 offset:1024
	ds_read_b128 v[184:187], v188 offset:2048
	ds_read_b128 v[188:191], v188 offset:3072
	global_load_lds_dwordx4 v[194:195], off
	v_lshl_add_u64 v[194:195], v[196:197], 0, s[74:75]
	s_add_i32 m0, s31, 0x2000
	s_nop 0
	global_load_lds_dwordx4 v[194:195], off
	s_barrier
	s_waitcnt lgkmcnt(0)
	s_waitcnt lgkmcnt(0)
	v_mfma_f32_16x16x32_bf16 v[116:119], v[176:179], v[144:147], v[116:119]
	v_mfma_f32_16x16x32_bf16 v[112:115], v[184:187], v[144:147], v[112:115]
	v_mfma_f32_16x16x32_bf16 v[100:103], v[176:179], v[152:155], v[100:103]
	v_mfma_f32_16x16x32_bf16 v[96:99], v[184:187], v[152:155], v[96:99]
	v_mfma_f32_16x16x32_bf16 v[84:87], v[176:179], v[160:163], v[84:87]
	v_mfma_f32_16x16x32_bf16 v[80:83], v[184:187], v[160:163], v[80:83]
	v_mfma_f32_16x16x32_bf16 v[68:71], v[176:179], v[168:171], v[68:71]
	v_mfma_f32_16x16x32_bf16 v[64:67], v[184:187], v[168:171], v[64:67]
	v_mfma_f32_16x16x32_bf16 v[116:119], v[180:183], v[148:151], v[116:119]
	v_mfma_f32_16x16x32_bf16 v[112:115], v[188:191], v[148:151], v[112:115]
	v_mfma_f32_16x16x32_bf16 v[100:103], v[180:183], v[156:159], v[100:103]
	v_mfma_f32_16x16x32_bf16 v[96:99], v[188:191], v[156:159], v[96:99]
	v_mfma_f32_16x16x32_bf16 v[84:87], v[180:183], v[164:167], v[84:87]
	v_mfma_f32_16x16x32_bf16 v[80:83], v[188:191], v[164:167], v[80:83]
	v_mfma_f32_16x16x32_bf16 v[68:71], v[180:183], v[172:175], v[68:71]
	v_mfma_f32_16x16x32_bf16 v[64:67], v[188:191], v[172:175], v[64:67]
	s_mov_b32 m0, s80
	v_lshl_add_u64 v[194:195], v[214:215], 0, s[74:75]
	s_barrier
	ds_read_b128 v[144:147], v251 offset:49152
	ds_read_b128 v[148:151], v251 offset:50176
	ds_read_b128 v[152:155], v251 offset:51200
	ds_read_b128 v[156:159], v251 offset:52224
	ds_read_b128 v[160:163], v251 offset:53248
	ds_read_b128 v[164:167], v251 offset:54272
	ds_read_b128 v[168:171], v251 offset:55296
	ds_read_b128 v[172:175], v251 offset:56320
	global_load_lds_dwordx4 v[194:195], off
	v_lshl_add_u64 v[194:195], v[216:217], 0, s[74:75]
	s_mov_b32 m0, s81
	s_nop 0
	global_load_lds_dwordx4 v[194:195], off
	s_barrier
; __device__ __forceinline__ unsigned cvt_pk_bf16(float lo, float hi) { unsigned r; asm volatile("s_nop 0\n\tv_cvt_pk_bf16_f32 %0, %1, %2\n\ts_nop 1" : "=v"(r) : "v"(lo), "v"(hi)); return r; }
; #define PG8_STAGE(bufoff, gbase, voff) do { _Pragma("unroll") for (int _i = 0; _i < 2; ++_i) \
;         __builtin_amdgcn_global_load_lds((const unsigned*)((const char*)(gbase) + (voff)[_i]), (PG8_LAS unsigned*)(lds + (bufoff) + ldsw + _i * 8192), 16, 0, 0); } while (0)
; #define PG8_MMA(ai, bj, At, Bt) do { __builtin_amdgcn_s_setprio(1); _Pragma("unroll") for (int m = 0; m < 4; ++m) _Pragma("unroll") for (int n = 0; n < 2; ++n) _Pragma("unroll") for (int k = 0; k < 2; ++k) \
;         acc[ai][bj][m][n] = __builtin_amdgcn_mfma_f32_16x16x32_bf16(Bt[n][k], At[m][k], acc[ai][bj][m][n], 0, 0, 0); __builtin_amdgcn_s_setprio(0); } while (0)
; #define PG8_WAIT_V(n) asm volatile("s_waitcnt vmcnt(" #n ")" ::: "memory")
; #define PG8_WAIT_L(n) asm volatile("s_waitcnt lgkmcnt(" #n ")" ::: "memory")
; #define PG8_BAR __builtin_amdgcn_s_barrier()
; template <class Epi, class Sched>
; __device__ __forceinline__ void gemm_phase(PG8_LAS unsigned char* lds, const Gemm g, const Sched& S, const Epi& E, int tid_in) {
;     ...
;             PG8_BAR; PG8_WAIT_L(0); PG8_MMA(1, 0, At, B0); PG8_BAR; PG8_SCHED;
;             PG8_STAGE(PG8_SB(1, 1), b3 + hstep, voffB);
;             PG8_WAIT_V(6); PG8_BAR; PG8_MMA(1, 1, At, B1); PG8_BAR;
;         }
;     __device__ __forceinline__ void operator()(f32x4 (&acc)[2][2][4][2], const Unit& u, int wr, int wc, int fr, int fq) const {
;     ...
;         } else {
; #pragma unroll
;             for (int bj = 0; bj < 2; ++bj) { const int col = (u.pn - 12) * 256 + bj * 128 + c8;
;                 const f32x4 b0 = *(const f32x4*)(b_gate + col), b1 = *(const f32x4*)(b_gate + col + 4);
; #pragma unroll
;                 for (int ai = 0; ai < 2; ++ai)
; #pragma unroll
;                     for (int m = 0; m < 4; ++m) { const f32x4 v0 = acc[ai][bj][m][0] + b0, v1 = acc[ai][bj][m][1] + b1;
;                         u32x4 w; w.x = cvt_pk_bf16(sigmoidf_(v0[0]), sigmoidf_(v0[1])); w.y = cvt_pk_bf16(sigmoidf_(v0[2]), sigmoidf_(v0[3]));
;                         w.z = cvt_pk_bf16(sigmoidf_(v1[0]), sigmoidf_(v1[1])); w.w = cvt_pk_bf16(sigmoidf_(v1[2]), sigmoidf_(v1[3]));
;                         *(u32x4*)(gates + (size_t)(row0 + ai * 128 + m * 16) * 2048 + col) = w; } }
	s_waitcnt lgkmcnt(0)
	s_waitcnt lgkmcnt(0)
	v_mfma_f32_16x16x32_bf16 v[60:63], v[128:131], v[144:147], v[60:63]
	v_mfma_f32_16x16x32_bf16 v[56:59], v[136:139], v[144:147], v[56:59]
	v_mfma_f32_16x16x32_bf16 v[44:47], v[128:131], v[152:155], v[44:47]
	v_mfma_f32_16x16x32_bf16 v[40:43], v[136:139], v[152:155], v[40:43]
	v_mfma_f32_16x16x32_bf16 v[28:31], v[128:131], v[160:163], v[28:31]
	v_mfma_f32_16x16x32_bf16 v[24:27], v[136:139], v[160:163], v[24:27]
	v_mfma_f32_16x16x32_bf16 v[12:15], v[128:131], v[168:171], v[12:15]
	v_mfma_f32_16x16x32_bf16 v[8:11], v[136:139], v[168:171], v[8:11]
	v_mfma_f32_16x16x32_bf16 v[60:63], v[132:135], v[148:151], v[60:63]
	v_mfma_f32_16x16x32_bf16 v[56:59], v[140:143], v[148:151], v[56:59]
	v_mfma_f32_16x16x32_bf16 v[44:47], v[132:135], v[156:159], v[44:47]
	v_mfma_f32_16x16x32_bf16 v[40:43], v[140:143], v[156:159], v[40:43]
	v_mfma_f32_16x16x32_bf16 v[28:31], v[132:135], v[164:167], v[28:31]
	v_mfma_f32_16x16x32_bf16 v[24:27], v[140:143], v[164:167], v[24:27]
	v_mfma_f32_16x16x32_bf16 v[12:15], v[132:135], v[172:175], v[12:15]
	v_mfma_f32_16x16x32_bf16 v[8:11], v[140:143], v[172:175], v[8:11]
	s_barrier
	s_add_u32 s28, s28, 0x40080
	s_addc_u32 s29, s29, 0
	s_add_i32 s30, s30, s72
	v_lshl_add_u64 v[128:129], s[28:29], 0, v[202:203]
	s_mov_b32 m0, s30
	s_nop 0
	global_load_lds_dwordx4 v[128:129], off
	v_lshl_add_u64 v[128:129], s[28:29], 0, v[206:207]
	s_add_i32 m0, s30, 0x2000
	s_nop 0
	global_load_lds_dwordx4 v[128:129], off
	s_waitcnt vmcnt(6)
	s_barrier
	v_mfma_f32_16x16x32_bf16 v[52:55], v[176:179], v[144:147], v[52:55]
	v_mfma_f32_16x16x32_bf16 v[48:51], v[184:187], v[144:147], v[48:51]
	v_mfma_f32_16x16x32_bf16 v[36:39], v[176:179], v[152:155], v[36:39]
	v_mfma_f32_16x16x32_bf16 v[32:35], v[184:187], v[152:155], v[32:35]
	v_mfma_f32_16x16x32_bf16 v[20:23], v[176:179], v[160:163], v[20:23]
	v_mfma_f32_16x16x32_bf16 v[16:19], v[184:187], v[160:163], v[16:19]
	v_mfma_f32_16x16x32_bf16 v[4:7], v[176:179], v[168:171], v[4:7]
	v_mfma_f32_16x16x32_bf16 v[0:3], v[184:187], v[168:171], v[0:3]
	v_mfma_f32_16x16x32_bf16 v[52:55], v[180:183], v[148:151], v[52:55]
	v_mfma_f32_16x16x32_bf16 v[48:51], v[188:191], v[148:151], v[48:51]
	v_mfma_f32_16x16x32_bf16 v[36:39], v[180:183], v[156:159], v[36:39]
	v_mfma_f32_16x16x32_bf16 v[32:35], v[188:191], v[156:159], v[32:35]
	v_mfma_f32_16x16x32_bf16 v[20:23], v[180:183], v[164:167], v[20:23]
	v_mfma_f32_16x16x32_bf16 v[16:19], v[188:191], v[164:167], v[16:19]
	v_mfma_f32_16x16x32_bf16 v[4:7], v[180:183], v[172:175], v[4:7]
	v_mfma_f32_16x16x32_bf16 v[0:3], v[188:191], v[172:175], v[0:3]
	s_add_i32 s37, s37, 2
	s_add_u32 s26, s26, 0x100
	s_addc_u32 s27, s27, 0
	s_add_u32 s33, s33, 0x100
	s_addc_u32 s36, s36, 0
	s_cmp_gt_u32 s37, 13
	s_barrier
	s_cbranch_scc0 .LBB0_388
	v_lshl_add_u32 v214, s0, 8, v209
	s_cmp_gt_i32 s24, 7
	s_mov_b64 s[0:1], -1
	s_cbranch_scc0 .LBB0_395
	s_lshl_b32 s17, s24, 8
	s_cmp_lt_u32 s24, 12
	s_cbranch_scc1 .LBB0_392
	v_or_b32_e32 v128, 0xfffff400, v208
	v_add_u32_e32 v140, s17, v128
	v_readlane_b32 s48, v255, 19
	v_ashrrev_i32_e32 v141, 31, v140
	v_readlane_b32 s49, v255, 20
	v_ashrrev_i32_e32 v215, 31, v214
	v_lshlrev_b64 v[146:147], 1, v[140:141]
	v_lshl_add_u64 v[132:133], v[140:141], 2, s[48:49]
	global_load_dwordx4 v[128:131], v[132:133], off offset:16
	s_nop 0
	global_load_dwordx4 v[132:135], v[132:133], off
	s_mov_b64 s[0:1], 0x80000
	v_or_b32_e32 v140, 0x80, v140
	v_readlane_b32 s50, v255, 21
	v_readlane_b32 s51, v255, 22
	v_readlane_b32 s52, v255, 23
	v_readlane_b32 s53, v255, 24
	v_readlane_b32 s54, v255, 25
	v_readlane_b32 s55, v255, 26
	s_waitcnt vmcnt(0)
	v_pk_add_f32 v[144:145], v[120:121], v[128:129]
	v_pk_add_f32 v[136:137], v[124:125], v[132:133]
	v_pk_add_f32 v[138:139], v[126:127], v[134:135]
	v_mul_f32_e32 v136, 0xbfb8aa3b, v136
	v_mul_f32_e32 v137, 0xbfb8aa3b, v137
	v_exp_f32_e32 v136, v136
	v_exp_f32_e32 v137, v137
	v_pk_add_f32 v[142:143], v[122:123], v[130:131]
	v_pk_add_f32 v[148:149], v[104:105], v[128:129]
	v_add_f32_e32 v136, 1.0, v136
	v_add_f32_e32 v137, 1.0, v137
	v_rcp_f32_e32 v136, v136
	v_rcp_f32_e32 v137, v137
	s_nop 0
	v_cvt_pk_bf16_f32 v136, v136, v137
	v_mul_f32_e32 v137, 0xbfb8aa3b, v138
	v_mul_f32_e32 v138, 0xbfb8aa3b, v139
	v_exp_f32_e32 v137, v137
	v_exp_f32_e32 v138, v138
	v_mul_f32_e32 v139, 0xbfb8aa3b, v145
	v_exp_f32_e32 v139, v139
	v_add_f32_e32 v137, 1.0, v137
	v_add_f32_e32 v138, 1.0, v138
	v_rcp_f32_e32 v137, v137
	v_rcp_f32_e32 v138, v138
	s_nop 0
	v_cvt_pk_bf16_f32 v137, v137, v138
	v_mul_f32_e32 v138, 0xbfb8aa3b, v144
	v_exp_f32_e32 v138, v138
	v_add_f32_e32 v139, 1.0, v139
	v_rcp_f32_e32 v139, v139
	v_pk_add_f32 v[150:151], v[88:89], v[128:129]
	v_add_f32_e32 v138, 1.0, v138
	v_rcp_f32_e32 v138, v138
	s_nop 0
	v_cvt_pk_bf16_f32 v138, v138, v139
	v_mul_f32_e32 v139, 0xbfb8aa3b, v142
	v_mul_f32_e32 v142, 0xbfb8aa3b, v143
	v_exp_f32_e32 v139, v139
	v_exp_f32_e32 v142, v142
	v_pk_add_f32 v[152:153], v[90:91], v[130:131]
	v_pk_add_f32 v[154:155], v[58:59], v[130:131]
	v_add_f32_e32 v139, 1.0, v139
	v_add_f32_e32 v142, 1.0, v142
	v_rcp_f32_e32 v139, v139
	v_rcp_f32_e32 v142, v142
	s_nop 0
	v_cvt_pk_bf16_f32 v139, v139, v142
	v_lshlrev_b64 v[142:143], 12, v[214:215]
	v_lshl_add_u64 v[142:143], s[14:15], 0, v[142:143]
	v_lshl_add_u64 v[144:145], v[142:143], 0, v[146:147]
	global_store_dwordx4 v[144:145], v[136:139], off
	v_pk_add_f32 v[144:145], v[106:107], v[130:131]
	v_pk_add_f32 v[156:157], v[42:43], v[130:131]
	v_pk_add_f32 v[136:137], v[108:109], v[132:133]
	v_pk_add_f32 v[138:139], v[110:111], v[134:135]
	v_mul_f32_e32 v136, 0xbfb8aa3b, v136
	v_mul_f32_e32 v137, 0xbfb8aa3b, v137
; __device__ __forceinline__ unsigned cvt_pk_bf16(float lo, float hi) { unsigned r; asm volatile("s_nop 0\n\tv_cvt_pk_bf16_f32 %0, %1, %2\n\ts_nop 1" : "=v"(r) : "v"(lo), "v"(hi)); return r; }
; __device__ __forceinline__ float sigmoidf_(float x) { return __builtin_amdgcn_rcpf(1.f + __expf(-x)); }
;     __device__ __forceinline__ void operator()(f32x4 (&acc)[2][2][4][2], const Unit& u, int wr, int wc, int fr, int fq) const {
;     ...
;             for (int bj = 0; bj < 2; ++bj) { const int col = (u.pn - 12) * 256 + bj * 128 + c8;
;                 const f32x4 b0 = *(const f32x4*)(b_gate + col), b1 = *(const f32x4*)(b_gate + col + 4);
; #pragma unroll
;                 for (int ai = 0; ai < 2; ++ai)
; #pragma unroll
;                     for (int m = 0; m < 4; ++m) { const f32x4 v0 = acc[ai][bj][m][0] + b0, v1 = acc[ai][bj][m][1] + b1;
;                         u32x4 w; w.x = cvt_pk_bf16(sigmoidf_(v0[0]), sigmoidf_(v0[1])); w.y = cvt_pk_bf16(sigmoidf_(v0[2]), sigmoidf_(v0[3]));
;                         w.z = cvt_pk_bf16(sigmoidf_(v1[0]), sigmoidf_(v1[1])); w.w = cvt_pk_bf16(sigmoidf_(v1[2]), sigmoidf_(v1[3]));
;                         *(u32x4*)(gates + (size_t)(row0 + ai * 128 + m * 16) * 2048 + col) = w; } }
	v_exp_f32_e32 v136, v136
	v_exp_f32_e32 v137, v137
	v_mul_f32_e32 v141, 0xbfb8aa3b, v145
	v_exp_f32_e32 v141, v141
	v_add_f32_e32 v136, 1.0, v136
	v_add_f32_e32 v137, 1.0, v137
	v_rcp_f32_e32 v136, v136
	v_rcp_f32_e32 v137, v137
	s_nop 0
	v_cvt_pk_bf16_f32 v136, v136, v137
	v_mul_f32_e32 v137, 0xbfb8aa3b, v138
	v_mul_f32_e32 v138, 0xbfb8aa3b, v139
	v_exp_f32_e32 v137, v137
	v_exp_f32_e32 v138, v138
	v_mul_f32_e32 v139, 0xbfb8aa3b, v149
	v_exp_f32_e32 v139, v139
	v_add_f32_e32 v137, 1.0, v137
	v_add_f32_e32 v138, 1.0, v138
	v_rcp_f32_e32 v137, v137
	v_rcp_f32_e32 v138, v138
	s_nop 0
	v_cvt_pk_bf16_f32 v137, v137, v138
	v_mul_f32_e32 v138, 0xbfb8aa3b, v148
	v_exp_f32_e32 v138, v138
	v_add_f32_e32 v139, 1.0, v139
	v_rcp_f32_e32 v139, v139
	v_add_f32_e32 v141, 1.0, v141
	v_add_f32_e32 v138, 1.0, v138
	v_rcp_f32_e32 v138, v138
	s_nop 0
	v_cvt_pk_bf16_f32 v138, v138, v139
	v_mul_f32_e32 v139, 0xbfb8aa3b, v144
	v_exp_f32_e32 v139, v139
	v_or_b32_e32 v144, 16, v214
	v_ashrrev_i32_e32 v145, 31, v144
	v_lshlrev_b64 v[144:145], 12, v[144:145]
	v_add_f32_e32 v139, 1.0, v139
	v_lshl_add_u64 v[144:145], s[14:15], 0, v[144:145]
	v_rcp_f32_e32 v139, v139
	v_lshl_add_u64 v[148:149], v[144:145], 0, v[146:147]
	v_rcp_f32_e32 v141, v141
	s_nop 0
	v_cvt_pk_bf16_f32 v139, v139, v141
	global_store_dwordx4 v[148:149], v[136:139], off
	v_pk_add_f32 v[158:159], v[26:27], v[130:131]
	s_nop 0
	v_pk_add_f32 v[136:137], v[94:95], v[134:135]
	v_pk_add_f32 v[138:139], v[92:93], v[132:133]
	v_mul_f32_e32 v136, 0xbfb8aa3b, v136
	v_mul_f32_e32 v138, 0xbfb8aa3b, v138
	v_mul_f32_e32 v139, 0xbfb8aa3b, v139
	v_exp_f32_e32 v136, v136
	v_mul_f32_e32 v137, 0xbfb8aa3b, v137
	v_exp_f32_e32 v138, v138
	v_exp_f32_e32 v139, v139
	v_exp_f32_e32 v137, v137
	v_add_f32_e32 v136, 1.0, v136
	v_add_f32_e32 v138, 1.0, v138
	v_add_f32_e32 v139, 1.0, v139
	v_rcp_f32_e32 v136, v136
	v_add_f32_e32 v137, 1.0, v137
	v_rcp_f32_e32 v138, v138
	v_rcp_f32_e32 v139, v139
	s_nop 0
	v_cvt_pk_bf16_f32 v148, v138, v139
	v_rcp_f32_e32 v137, v137
	s_nop 0
	v_cvt_pk_bf16_f32 v149, v136, v137
	v_mul_f32_e32 v136, 0xbfb8aa3b, v150
	v_exp_f32_e32 v136, v136
	v_mul_f32_e32 v137, 0xbfb8aa3b, v151
	v_exp_f32_e32 v137, v137
	v_add_f32_e32 v136, 1.0, v136
	v_rcp_f32_e32 v136, v136
	v_add_f32_e32 v137, 1.0, v137
	v_rcp_f32_e32 v137, v137
	s_nop 0
	v_cvt_pk_bf16_f32 v150, v136, v137
	v_mul_f32_e32 v136, 0xbfb8aa3b, v152
	v_exp_f32_e32 v136, v136
	v_mul_f32_e32 v137, 0xbfb8aa3b, v153
	v_exp_f32_e32 v137, v137
	v_pk_add_f32 v[152:153], v[74:75], v[130:131]
	v_add_f32_e32 v136, 1.0, v136
	v_rcp_f32_e32 v136, v136
	v_add_f32_e32 v137, 1.0, v137
	v_rcp_f32_e32 v137, v137
	s_nop 0
	v_cvt_pk_bf16_f32 v151, v136, v137
	v_or_b32_e32 v136, 32, v214
	v_ashrrev_i32_e32 v137, 31, v136
	v_lshlrev_b64 v[136:137], 12, v[136:137]
	v_lshl_add_u64 v[136:137], s[14:15], 0, v[136:137]
	v_lshl_add_u64 v[138:139], v[136:137], 0, v[146:147]
	global_store_dwordx4 v[138:139], v[148:151], off
	v_pk_add_f32 v[138:139], v[78:79], v[134:135]
	s_nop 0
	v_pk_add_f32 v[148:149], v[76:77], v[132:133]
	v_mul_f32_e32 v138, 0xbfb8aa3b, v138
	v_mul_f32_e32 v141, 0xbfb8aa3b, v148
	v_mul_f32_e32 v148, 0xbfb8aa3b, v149
	v_exp_f32_e32 v148, v148
	v_exp_f32_e32 v138, v138
	v_mul_f32_e32 v139, 0xbfb8aa3b, v139
	v_exp_f32_e32 v141, v141
	v_exp_f32_e32 v139, v139
	v_add_f32_e32 v148, 1.0, v148
	v_add_f32_e32 v138, 1.0, v138
	v_pk_add_f32 v[150:151], v[72:73], v[128:129]
	v_add_f32_e32 v141, 1.0, v141
	v_rcp_f32_e32 v148, v148
	v_rcp_f32_e32 v138, v138
	v_add_f32_e32 v139, 1.0, v139
	v_rcp_f32_e32 v141, v141
	s_nop 0
	v_cvt_pk_bf16_f32 v148, v141, v148
	v_rcp_f32_e32 v139, v139
	s_nop 0
	v_cvt_pk_bf16_f32 v149, v138, v139
	v_mul_f32_e32 v138, 0xbfb8aa3b, v150
	v_exp_f32_e32 v138, v138
	v_mul_f32_e32 v139, 0xbfb8aa3b, v151
	v_exp_f32_e32 v139, v139
	v_add_f32_e32 v138, 1.0, v138
	v_rcp_f32_e32 v138, v138
	v_add_f32_e32 v139, 1.0, v139
	v_rcp_f32_e32 v139, v139
	s_nop 0
	v_cvt_pk_bf16_f32 v150, v138, v139
	v_mul_f32_e32 v138, 0xbfb8aa3b, v152
	v_exp_f32_e32 v138, v138
	v_mul_f32_e32 v139, 0xbfb8aa3b, v153
	v_exp_f32_e32 v139, v139
	v_add_f32_e32 v138, 1.0, v138
	v_rcp_f32_e32 v138, v138
	v_add_f32_e32 v139, 1.0, v139
	v_rcp_f32_e32 v139, v139
	s_nop 0
	v_cvt_pk_bf16_f32 v151, v138, v139
	v_or_b32_e32 v138, 48, v214
	v_ashrrev_i32_e32 v139, 31, v138
	v_lshlrev_b64 v[138:139], 12, v[138:139]
	v_lshl_add_u64 v[138:139], s[14:15], 0, v[138:139]
	v_lshl_add_u64 v[152:153], v[138:139], 0, v[146:147]
	global_store_dwordx4 v[152:153], v[148:151], off
	v_pk_add_f32 v[152:153], v[56:57], v[128:129]
	s_nop 0
	v_pk_add_f32 v[150:151], v[60:61], v[132:133]
	v_pk_add_f32 v[148:149], v[62:63], v[134:135]
	v_mul_f32_e32 v141, 0xbfb8aa3b, v150
	v_mul_f32_e32 v150, 0xbfb8aa3b, v151
	v_exp_f32_e32 v141, v141
	v_exp_f32_e32 v150, v150
	v_add_f32_e32 v141, 1.0, v141
	v_add_f32_e32 v150, 1.0, v150
	v_rcp_f32_e32 v141, v141
	v_rcp_f32_e32 v150, v150
	s_nop 0
	v_cvt_pk_bf16_f32 v150, v141, v150
	v_mul_f32_e32 v141, 0xbfb8aa3b, v148
	v_mul_f32_e32 v148, 0xbfb8aa3b, v149
	v_exp_f32_e32 v148, v148
	v_exp_f32_e32 v141, v141
	v_add_f32_e32 v148, 1.0, v148
	v_add_f32_e32 v141, 1.0, v141
	v_rcp_f32_e32 v148, v148
	v_rcp_f32_e32 v141, v141
	s_nop 0
	v_cvt_pk_bf16_f32 v151, v141, v148
	v_mul_f32_e32 v148, 0xbfb8aa3b, v153
	v_mul_f32_e32 v141, 0xbfb8aa3b, v152
	v_exp_f32_e32 v148, v148
	v_exp_f32_e32 v141, v141
	v_add_f32_e32 v148, 1.0, v148
	v_add_f32_e32 v141, 1.0, v141
	v_rcp_f32_e32 v148, v148
	v_rcp_f32_e32 v141, v141
	s_nop 0
	v_cvt_pk_bf16_f32 v152, v141, v148
	v_mul_f32_e32 v148, 0xbfb8aa3b, v155
	v_mul_f32_e32 v141, 0xbfb8aa3b, v154
	v_exp_f32_e32 v148, v148
	v_exp_f32_e32 v141, v141
; __device__ __forceinline__ unsigned cvt_pk_bf16(float lo, float hi) { unsigned r; asm volatile("s_nop 0\n\tv_cvt_pk_bf16_f32 %0, %1, %2\n\ts_nop 1" : "=v"(r) : "v"(lo), "v"(hi)); return r; }
; __device__ __forceinline__ float sigmoidf_(float x) { return __builtin_amdgcn_rcpf(1.f + __expf(-x)); }
;     __device__ __forceinline__ void operator()(f32x4 (&acc)[2][2][4][2], const Unit& u, int wr, int wc, int fr, int fq) const {
;     ...
;             for (int bj = 0; bj < 2; ++bj) { const int col = (u.pn - 12) * 256 + bj * 128 + c8;
;                 const f32x4 b0 = *(const f32x4*)(b_gate + col), b1 = *(const f32x4*)(b_gate + col + 4);
; #pragma unroll
;                 for (int ai = 0; ai < 2; ++ai)
; #pragma unroll
;                     for (int m = 0; m < 4; ++m) { const f32x4 v0 = acc[ai][bj][m][0] + b0, v1 = acc[ai][bj][m][1] + b1;
;                         u32x4 w; w.x = cvt_pk_bf16(sigmoidf_(v0[0]), sigmoidf_(v0[1])); w.y = cvt_pk_bf16(sigmoidf_(v0[2]), sigmoidf_(v0[3]));
;                         w.z = cvt_pk_bf16(sigmoidf_(v1[0]), sigmoidf_(v1[1])); w.w = cvt_pk_bf16(sigmoidf_(v1[2]), sigmoidf_(v1[3]));
;                         *(u32x4*)(gates + (size_t)(row0 + ai * 128 + m * 16) * 2048 + col) = w; } }
	v_add_f32_e32 v148, 1.0, v148
	v_add_f32_e32 v141, 1.0, v141
	v_rcp_f32_e32 v148, v148
	v_rcp_f32_e32 v141, v141
	s_nop 0
	v_cvt_pk_bf16_f32 v153, v141, v148
	v_lshl_add_u64 v[148:149], v[142:143], 0, s[0:1]
	v_lshl_add_u64 v[154:155], v[148:149], 0, v[146:147]
	global_store_dwordx4 v[154:155], v[150:153], off
	v_pk_add_f32 v[154:155], v[40:41], v[128:129]
	s_mov_b64 s[0:1], 0x90000
	v_pk_add_f32 v[152:153], v[44:45], v[132:133]
	v_pk_add_f32 v[150:151], v[46:47], v[134:135]
	v_mul_f32_e32 v141, 0xbfb8aa3b, v152
	v_mul_f32_e32 v152, 0xbfb8aa3b, v153
	v_exp_f32_e32 v141, v141
	v_exp_f32_e32 v152, v152
	v_add_f32_e32 v141, 1.0, v141
	v_add_f32_e32 v152, 1.0, v152
	v_rcp_f32_e32 v141, v141
	v_rcp_f32_e32 v152, v152
	s_nop 0
	v_cvt_pk_bf16_f32 v152, v141, v152
	v_mul_f32_e32 v141, 0xbfb8aa3b, v150
	v_mul_f32_e32 v150, 0xbfb8aa3b, v151
	v_exp_f32_e32 v150, v150
	v_exp_f32_e32 v141, v141
	v_add_f32_e32 v150, 1.0, v150
	v_add_f32_e32 v141, 1.0, v141
	v_rcp_f32_e32 v150, v150
	v_rcp_f32_e32 v141, v141
	s_nop 0
	v_cvt_pk_bf16_f32 v153, v141, v150
	v_mul_f32_e32 v150, 0xbfb8aa3b, v155
	v_mul_f32_e32 v141, 0xbfb8aa3b, v154
	v_exp_f32_e32 v150, v150
	v_exp_f32_e32 v141, v141
	v_add_f32_e32 v150, 1.0, v150
	v_add_f32_e32 v141, 1.0, v141
	v_rcp_f32_e32 v150, v150
	v_rcp_f32_e32 v141, v141
	s_nop 0
	v_cvt_pk_bf16_f32 v154, v141, v150
	v_mul_f32_e32 v150, 0xbfb8aa3b, v157
	v_mul_f32_e32 v141, 0xbfb8aa3b, v156
	v_exp_f32_e32 v150, v150
	v_exp_f32_e32 v141, v141
	v_add_f32_e32 v150, 1.0, v150
	v_add_f32_e32 v141, 1.0, v141
	v_rcp_f32_e32 v150, v150
	v_rcp_f32_e32 v141, v141
	s_nop 0
	v_cvt_pk_bf16_f32 v155, v141, v150
	v_lshl_add_u64 v[150:151], v[142:143], 0, s[0:1]
	v_lshl_add_u64 v[156:157], v[150:151], 0, v[146:147]
	global_store_dwordx4 v[156:157], v[152:155], off
	v_pk_add_f32 v[156:157], v[24:25], v[128:129]
	s_mov_b64 s[0:1], 0xa0000
	v_pk_add_f32 v[154:155], v[28:29], v[132:133]
	v_pk_add_f32 v[152:153], v[30:31], v[134:135]
	v_mul_f32_e32 v141, 0xbfb8aa3b, v154
	v_mul_f32_e32 v154, 0xbfb8aa3b, v155
	v_exp_f32_e32 v141, v141
	v_exp_f32_e32 v154, v154
	v_pk_add_f32 v[132:133], v[12:13], v[132:133]
	v_pk_add_f32 v[134:135], v[14:15], v[134:135]
	v_add_f32_e32 v141, 1.0, v141
	v_add_f32_e32 v154, 1.0, v154
	v_rcp_f32_e32 v141, v141
	v_rcp_f32_e32 v154, v154
	s_nop 0
	v_cvt_pk_bf16_f32 v154, v141, v154
	v_mul_f32_e32 v141, 0xbfb8aa3b, v152
	v_mul_f32_e32 v152, 0xbfb8aa3b, v153
	v_exp_f32_e32 v152, v152
	v_exp_f32_e32 v141, v141
	v_add_f32_e32 v152, 1.0, v152
	v_add_f32_e32 v141, 1.0, v141
	v_rcp_f32_e32 v152, v152
	v_rcp_f32_e32 v141, v141
	s_nop 0
	v_cvt_pk_bf16_f32 v155, v141, v152
	v_mul_f32_e32 v152, 0xbfb8aa3b, v157
	v_mul_f32_e32 v141, 0xbfb8aa3b, v156
	v_exp_f32_e32 v152, v152
	v_exp_f32_e32 v141, v141
	v_add_f32_e32 v152, 1.0, v152
	v_add_f32_e32 v141, 1.0, v141
	v_rcp_f32_e32 v152, v152
	v_rcp_f32_e32 v141, v141
	s_nop 0
	v_cvt_pk_bf16_f32 v156, v141, v152
	v_mul_f32_e32 v152, 0xbfb8aa3b, v159
	v_mul_f32_e32 v141, 0xbfb8aa3b, v158
	v_exp_f32_e32 v152, v152
	v_exp_f32_e32 v141, v141
	v_add_f32_e32 v152, 1.0, v152
	v_add_f32_e32 v141, 1.0, v141
	v_rcp_f32_e32 v152, v152
	v_rcp_f32_e32 v141, v141
	s_nop 0
	v_cvt_pk_bf16_f32 v157, v141, v152
	v_lshl_add_u64 v[152:153], v[142:143], 0, s[0:1]
	v_lshl_add_u64 v[158:159], v[152:153], 0, v[146:147]
	global_store_dwordx4 v[158:159], v[154:157], off
	s_mov_b64 s[0:1], 0xb0000
	v_ashrrev_i32_e32 v141, 31, v140
	v_pk_add_f32 v[154:155], v[10:11], v[130:131]
	v_pk_add_f32 v[130:131], v[8:9], v[128:129]
	v_mul_f32_e32 v128, 0xbfb8aa3b, v132
	v_mul_f32_e32 v129, 0xbfb8aa3b, v133
	v_exp_f32_e32 v128, v128
	v_exp_f32_e32 v129, v129
	v_mul_f32_e32 v132, 0xbfb8aa3b, v135
	v_mul_f32_e32 v130, 0xbfb8aa3b, v130
	v_add_f32_e32 v128, 1.0, v128
	v_add_f32_e32 v129, 1.0, v129
	v_rcp_f32_e32 v128, v128
	v_rcp_f32_e32 v129, v129
	s_nop 0
	v_cvt_pk_bf16_f32 v128, v128, v129
	v_mul_f32_e32 v129, 0xbfb8aa3b, v134
	v_mul_f32_e32 v131, 0xbfb8aa3b, v131
	v_exp_f32_e32 v129, v129
	v_exp_f32_e32 v132, v132
	v_exp_f32_e32 v130, v130
	v_exp_f32_e32 v131, v131
	v_add_f32_e32 v129, 1.0, v129
	v_add_f32_e32 v132, 1.0, v132
	v_add_f32_e32 v130, 1.0, v130
	v_add_f32_e32 v131, 1.0, v131
	v_rcp_f32_e32 v129, v129
	v_rcp_f32_e32 v132, v132
	v_rcp_f32_e32 v130, v130
	v_rcp_f32_e32 v131, v131
	s_nop 0
	v_cvt_pk_bf16_f32 v129, v129, v132
	v_cvt_pk_bf16_f32 v130, v130, v131
	v_mul_f32_e32 v131, 0xbfb8aa3b, v154
	v_mul_f32_e32 v132, 0xbfb8aa3b, v155
	v_exp_f32_e32 v131, v131
	v_exp_f32_e32 v132, v132
	v_lshl_add_u64 v[154:155], v[142:143], 0, s[0:1]
	s_mov_b64 s[0:1], 0
	v_add_f32_e32 v131, 1.0, v131
	v_add_f32_e32 v132, 1.0, v132
	v_rcp_f32_e32 v131, v131
	v_rcp_f32_e32 v132, v132
	s_nop 0
	v_cvt_pk_bf16_f32 v131, v131, v132
	v_lshl_add_u64 v[132:133], v[154:155], 0, v[146:147]
	global_store_dwordx4 v[132:133], v[128:131], off
	v_lshl_add_u64 v[132:133], v[140:141], 2, s[48:49]
	global_load_dwordx4 v[128:131], v[132:133], off offset:16
	s_nop 0
	global_load_dwordx4 v[132:135], v[132:133], off
	v_lshlrev_b64 v[140:141], 1, v[140:141]
	v_lshl_add_u64 v[142:143], v[142:143], 0, v[140:141]
	v_lshl_add_u64 v[136:137], v[136:137], 0, v[140:141]
	s_waitcnt vmcnt(0)
; __device__ __forceinline__ unsigned cvt_pk_bf16(float lo, float hi) { unsigned r; asm volatile("s_nop 0\n\tv_cvt_pk_bf16_f32 %0, %1, %2\n\ts_nop 1" : "=v"(r) : "v"(lo), "v"(hi)); return r; }
; __device__ __forceinline__ float sigmoidf_(float x) { return __builtin_amdgcn_rcpf(1.f + __expf(-x)); }
;     __device__ __forceinline__ void operator()(f32x4 (&acc)[2][2][4][2], const Unit& u, int wr, int wc, int fr, int fq) const {
;     ...
;             for (int bj = 0; bj < 2; ++bj) { const int col = (u.pn - 12) * 256 + bj * 128 + c8;
;                 const f32x4 b0 = *(const f32x4*)(b_gate + col), b1 = *(const f32x4*)(b_gate + col + 4);
; #pragma unroll
;                 for (int ai = 0; ai < 2; ++ai)
; #pragma unroll
;                     for (int m = 0; m < 4; ++m) { const f32x4 v0 = acc[ai][bj][m][0] + b0, v1 = acc[ai][bj][m][1] + b1;
;                         u32x4 w; w.x = cvt_pk_bf16(sigmoidf_(v0[0]), sigmoidf_(v0[1])); w.y = cvt_pk_bf16(sigmoidf_(v0[2]), sigmoidf_(v0[3]));
;                         w.z = cvt_pk_bf16(sigmoidf_(v1[0]), sigmoidf_(v1[1])); w.w = cvt_pk_bf16(sigmoidf_(v1[2]), sigmoidf_(v1[3]));
;                         *(u32x4*)(gates + (size_t)(row0 + ai * 128 + m * 16) * 2048 + col) = w; } }
	v_pk_add_f32 v[158:159], v[112:113], v[128:129]
	v_pk_add_f32 v[146:147], v[118:119], v[134:135]
	v_pk_add_f32 v[156:157], v[116:117], v[132:133]
	v_mul_f32_e32 v146, 0xbfb8aa3b, v146
	v_mul_f32_e32 v156, 0xbfb8aa3b, v156
	v_mul_f32_e32 v157, 0xbfb8aa3b, v157
	v_mul_f32_e32 v147, 0xbfb8aa3b, v147
	v_exp_f32_e32 v156, v156
	v_exp_f32_e32 v157, v157
	v_exp_f32_e32 v146, v146
	v_exp_f32_e32 v147, v147
	v_add_f32_e32 v156, 1.0, v156
	v_add_f32_e32 v157, 1.0, v157
	v_add_f32_e32 v146, 1.0, v146
	v_add_f32_e32 v147, 1.0, v147
	v_rcp_f32_e32 v156, v156
	v_rcp_f32_e32 v157, v157
	v_rcp_f32_e32 v146, v146
	v_rcp_f32_e32 v147, v147
	s_nop 0
	v_cvt_pk_bf16_f32 v156, v156, v157
	v_cvt_pk_bf16_f32 v157, v146, v147
	v_mul_f32_e32 v146, 0xbfb8aa3b, v158
	v_mul_f32_e32 v147, 0xbfb8aa3b, v159
	v_exp_f32_e32 v146, v146
	v_exp_f32_e32 v147, v147
	v_pk_add_f32 v[160:161], v[114:115], v[130:131]
	v_add_f32_e32 v146, 1.0, v146
	v_add_f32_e32 v147, 1.0, v147
	v_rcp_f32_e32 v146, v146
	v_rcp_f32_e32 v147, v147
	s_nop 0
	v_cvt_pk_bf16_f32 v158, v146, v147
	v_mul_f32_e32 v146, 0xbfb8aa3b, v160
	v_mul_f32_e32 v147, 0xbfb8aa3b, v161
	v_exp_f32_e32 v146, v146
	v_exp_f32_e32 v147, v147
	v_pk_add_f32 v[160:161], v[98:99], v[130:131]
	v_add_f32_e32 v146, 1.0, v146
	v_add_f32_e32 v147, 1.0, v147
	v_rcp_f32_e32 v146, v146
	v_rcp_f32_e32 v147, v147
	s_nop 0
	v_cvt_pk_bf16_f32 v159, v146, v147
	global_store_dwordx4 v[142:143], v[156:159], off
	v_pk_add_f32 v[142:143], v[102:103], v[134:135]
	v_pk_add_f32 v[146:147], v[100:101], v[132:133]
	v_mul_f32_e32 v142, 0xbfb8aa3b, v142
	v_mul_f32_e32 v143, 0xbfb8aa3b, v143
	v_mul_f32_e32 v146, 0xbfb8aa3b, v146
	v_mul_f32_e32 v147, 0xbfb8aa3b, v147
	v_exp_f32_e32 v142, v142
	v_exp_f32_e32 v143, v143
	v_exp_f32_e32 v146, v146
	v_exp_f32_e32 v147, v147
	v_add_f32_e32 v142, 1.0, v142
	v_add_f32_e32 v143, 1.0, v143
	v_pk_add_f32 v[158:159], v[96:97], v[128:129]
	v_add_f32_e32 v146, 1.0, v146
	v_add_f32_e32 v147, 1.0, v147
	v_rcp_f32_e32 v142, v142
	v_rcp_f32_e32 v143, v143
	v_rcp_f32_e32 v146, v146
	v_rcp_f32_e32 v147, v147
	s_nop 0
	v_cvt_pk_bf16_f32 v156, v146, v147
	v_cvt_pk_bf16_f32 v157, v142, v143
	v_mul_f32_e32 v142, 0xbfb8aa3b, v158
	v_mul_f32_e32 v143, 0xbfb8aa3b, v159
	v_exp_f32_e32 v142, v142
	v_exp_f32_e32 v143, v143
	v_pk_add_f32 v[146:147], v[82:83], v[130:131]
	v_add_f32_e32 v142, 1.0, v142
	v_add_f32_e32 v143, 1.0, v143
	v_rcp_f32_e32 v142, v142
	v_rcp_f32_e32 v143, v143
	s_nop 0
	v_cvt_pk_bf16_f32 v158, v142, v143
	v_mul_f32_e32 v142, 0xbfb8aa3b, v160
	v_mul_f32_e32 v143, 0xbfb8aa3b, v161
	v_exp_f32_e32 v142, v142
	v_exp_f32_e32 v143, v143
	v_add_f32_e32 v142, 1.0, v142
	v_add_f32_e32 v143, 1.0, v143
	v_rcp_f32_e32 v142, v142
	v_rcp_f32_e32 v143, v143
	s_nop 0
	v_cvt_pk_bf16_f32 v159, v142, v143
	v_lshl_add_u64 v[142:143], v[144:145], 0, v[140:141]
	global_store_dwordx4 v[142:143], v[156:159], off
	v_pk_add_f32 v[142:143], v[84:85], v[132:133]
	v_pk_add_f32 v[144:145], v[86:87], v[134:135]
	v_mul_f32_e32 v142, 0xbfb8aa3b, v142
	v_mul_f32_e32 v143, 0xbfb8aa3b, v143
	v_exp_f32_e32 v142, v142
	v_exp_f32_e32 v143, v143
	v_pk_add_f32 v[156:157], v[80:81], v[128:129]
	v_add_f32_e32 v142, 1.0, v142
	v_add_f32_e32 v143, 1.0, v143
	v_rcp_f32_e32 v142, v142
	v_rcp_f32_e32 v143, v143
	s_nop 0
	v_cvt_pk_bf16_f32 v142, v142, v143
	v_mul_f32_e32 v143, 0xbfb8aa3b, v144
	v_mul_f32_e32 v144, 0xbfb8aa3b, v145
	v_exp_f32_e32 v143, v143
	v_exp_f32_e32 v144, v144
	v_mul_f32_e32 v145, 0xbfb8aa3b, v157
	v_exp_f32_e32 v145, v145
	v_add_f32_e32 v143, 1.0, v143
	v_add_f32_e32 v144, 1.0, v144
	v_rcp_f32_e32 v143, v143
	v_rcp_f32_e32 v144, v144
	s_nop 0
	v_cvt_pk_bf16_f32 v143, v143, v144
	v_mul_f32_e32 v144, 0xbfb8aa3b, v156
	v_exp_f32_e32 v144, v144
	v_add_f32_e32 v145, 1.0, v145
	v_rcp_f32_e32 v145, v145
	v_add_f32_e32 v144, 1.0, v144
	v_rcp_f32_e32 v144, v144
	s_nop 0
	v_cvt_pk_bf16_f32 v144, v144, v145
	v_mul_f32_e32 v145, 0xbfb8aa3b, v146
	v_exp_f32_e32 v145, v145
	v_mul_f32_e32 v146, 0xbfb8aa3b, v147
	v_exp_f32_e32 v146, v146
	v_add_f32_e32 v145, 1.0, v145
	v_rcp_f32_e32 v145, v145
	v_add_f32_e32 v146, 1.0, v146
	v_rcp_f32_e32 v146, v146
	s_nop 0
	v_cvt_pk_bf16_f32 v145, v145, v146
	global_store_dwordx4 v[136:137], v[142:145], off
	v_pk_add_f32 v[136:137], v[70:71], v[134:135]
	v_pk_add_f32 v[146:147], v[66:67], v[130:131]
	v_pk_add_f32 v[142:143], v[68:69], v[132:133]
	v_mul_f32_e32 v136, 0xbfb8aa3b, v136
	v_mul_f32_e32 v142, 0xbfb8aa3b, v142
	v_mul_f32_e32 v143, 0xbfb8aa3b, v143
	v_mul_f32_e32 v137, 0xbfb8aa3b, v137
	v_exp_f32_e32 v142, v142
	v_exp_f32_e32 v143, v143
	v_exp_f32_e32 v136, v136
	v_exp_f32_e32 v137, v137
	v_add_f32_e32 v142, 1.0, v142
	v_add_f32_e32 v143, 1.0, v143
	v_add_f32_e32 v136, 1.0, v136
	v_add_f32_e32 v137, 1.0, v137
	v_pk_add_f32 v[144:145], v[64:65], v[128:129]
	v_rcp_f32_e32 v142, v142
	v_rcp_f32_e32 v143, v143
	v_rcp_f32_e32 v136, v136
	v_rcp_f32_e32 v137, v137
	s_nop 0
	v_cvt_pk_bf16_f32 v142, v142, v143
	v_cvt_pk_bf16_f32 v143, v136, v137
	v_mul_f32_e32 v136, 0xbfb8aa3b, v144
	v_mul_f32_e32 v137, 0xbfb8aa3b, v145
	v_exp_f32_e32 v136, v136
	v_exp_f32_e32 v137, v137
	v_add_f32_e32 v136, 1.0, v136
	v_add_f32_e32 v137, 1.0, v137
	v_rcp_f32_e32 v136, v136
	v_rcp_f32_e32 v137, v137
	s_nop 0
	v_cvt_pk_bf16_f32 v144, v136, v137
	v_mul_f32_e32 v136, 0xbfb8aa3b, v146
	v_mul_f32_e32 v137, 0xbfb8aa3b, v147
	v_exp_f32_e32 v136, v136
	v_exp_f32_e32 v137, v137
	v_add_f32_e32 v136, 1.0, v136
	v_add_f32_e32 v137, 1.0, v137
	v_rcp_f32_e32 v136, v136
	v_rcp_f32_e32 v137, v137
	s_nop 0
	v_cvt_pk_bf16_f32 v145, v136, v137
	v_lshl_add_u64 v[136:137], v[138:139], 0, v[140:141]
	global_store_dwordx4 v[136:137], v[142:145], off
; __device__ __forceinline__ unsigned cvt_pk_bf16(float lo, float hi) { unsigned r; asm volatile("s_nop 0\n\tv_cvt_pk_bf16_f32 %0, %1, %2\n\ts_nop 1" : "=v"(r) : "v"(lo), "v"(hi)); return r; }
; __device__ __forceinline__ float sigmoidf_(float x) { return __builtin_amdgcn_rcpf(1.f + __expf(-x)); }
;     __device__ __forceinline__ void operator()(f32x4 (&acc)[2][2][4][2], const Unit& u, int wr, int wc, int fr, int fq) const {
;     ...
;             for (int bj = 0; bj < 2; ++bj) { const int col = (u.pn - 12) * 256 + bj * 128 + c8;
;                 const f32x4 b0 = *(const f32x4*)(b_gate + col), b1 = *(const f32x4*)(b_gate + col + 4);
; #pragma unroll
;                 for (int ai = 0; ai < 2; ++ai)
; #pragma unroll
;                     for (int m = 0; m < 4; ++m) { const f32x4 v0 = acc[ai][bj][m][0] + b0, v1 = acc[ai][bj][m][1] + b1;
;                         u32x4 w; w.x = cvt_pk_bf16(sigmoidf_(v0[0]), sigmoidf_(v0[1])); w.y = cvt_pk_bf16(sigmoidf_(v0[2]), sigmoidf_(v0[3]));
;                         w.z = cvt_pk_bf16(sigmoidf_(v1[0]), sigmoidf_(v1[1])); w.w = cvt_pk_bf16(sigmoidf_(v1[2]), sigmoidf_(v1[3]));
;                         *(u32x4*)(gates + (size_t)(row0 + ai * 128 + m * 16) * 2048 + col) = w; } }
	v_pk_add_f32 v[136:137], v[52:53], v[132:133]
	v_pk_add_f32 v[138:139], v[54:55], v[134:135]
	v_mul_f32_e32 v136, 0xbfb8aa3b, v136
	v_mul_f32_e32 v137, 0xbfb8aa3b, v137
	v_exp_f32_e32 v136, v136
	v_exp_f32_e32 v137, v137
	v_pk_add_f32 v[144:145], v[48:49], v[128:129]
	v_pk_add_f32 v[142:143], v[50:51], v[130:131]
	v_add_f32_e32 v136, 1.0, v136
	v_add_f32_e32 v137, 1.0, v137
	v_rcp_f32_e32 v136, v136
	v_rcp_f32_e32 v137, v137
	s_nop 0
	v_cvt_pk_bf16_f32 v136, v136, v137
	v_mul_f32_e32 v137, 0xbfb8aa3b, v138
	v_mul_f32_e32 v138, 0xbfb8aa3b, v139
	v_exp_f32_e32 v137, v137
	v_exp_f32_e32 v138, v138
	v_mul_f32_e32 v139, 0xbfb8aa3b, v145
	v_exp_f32_e32 v139, v139
	v_add_f32_e32 v137, 1.0, v137
	v_add_f32_e32 v138, 1.0, v138
	v_rcp_f32_e32 v137, v137
	v_rcp_f32_e32 v138, v138
	s_nop 0
	v_cvt_pk_bf16_f32 v137, v137, v138
	v_mul_f32_e32 v138, 0xbfb8aa3b, v144
	v_exp_f32_e32 v138, v138
	v_add_f32_e32 v139, 1.0, v139
	v_rcp_f32_e32 v139, v139
	v_pk_add_f32 v[144:145], v[32:33], v[128:129]
	v_add_f32_e32 v138, 1.0, v138
	v_rcp_f32_e32 v138, v138
	s_nop 0
	v_cvt_pk_bf16_f32 v138, v138, v139
	v_mul_f32_e32 v139, 0xbfb8aa3b, v142
	v_mul_f32_e32 v142, 0xbfb8aa3b, v143
	v_exp_f32_e32 v139, v139
	v_exp_f32_e32 v142, v142
	v_add_f32_e32 v139, 1.0, v139
	v_add_f32_e32 v142, 1.0, v142
	v_rcp_f32_e32 v139, v139
	v_rcp_f32_e32 v142, v142
	s_nop 0
	v_cvt_pk_bf16_f32 v139, v139, v142
	v_lshl_add_u64 v[142:143], v[148:149], 0, v[140:141]
	global_store_dwordx4 v[142:143], v[136:139], off
	v_pk_add_f32 v[142:143], v[34:35], v[130:131]
	s_nop 0
	v_pk_add_f32 v[136:137], v[36:37], v[132:133]
	v_pk_add_f32 v[138:139], v[38:39], v[134:135]
	v_mul_f32_e32 v136, 0xbfb8aa3b, v136
	v_mul_f32_e32 v137, 0xbfb8aa3b, v137
	v_exp_f32_e32 v136, v136
	v_exp_f32_e32 v137, v137
	v_add_f32_e32 v136, 1.0, v136
	v_add_f32_e32 v137, 1.0, v137
	v_rcp_f32_e32 v136, v136
	v_rcp_f32_e32 v137, v137
	s_nop 0
	v_cvt_pk_bf16_f32 v136, v136, v137
	v_mul_f32_e32 v137, 0xbfb8aa3b, v138
	v_mul_f32_e32 v138, 0xbfb8aa3b, v139
	v_exp_f32_e32 v137, v137
	v_exp_f32_e32 v138, v138
	v_mul_f32_e32 v139, 0xbfb8aa3b, v145
	v_exp_f32_e32 v139, v139
	v_add_f32_e32 v137, 1.0, v137
	v_add_f32_e32 v138, 1.0, v138
	v_rcp_f32_e32 v137, v137
	v_rcp_f32_e32 v138, v138
	s_nop 0
	v_cvt_pk_bf16_f32 v137, v137, v138
	v_mul_f32_e32 v138, 0xbfb8aa3b, v144
	v_exp_f32_e32 v138, v138
	v_add_f32_e32 v139, 1.0, v139
	v_rcp_f32_e32 v139, v139
	v_pk_add_f32 v[144:145], v[16:17], v[128:129]
	v_add_f32_e32 v138, 1.0, v138
	v_rcp_f32_e32 v138, v138
	s_nop 0
	v_cvt_pk_bf16_f32 v138, v138, v139
	v_mul_f32_e32 v139, 0xbfb8aa3b, v142
	v_mul_f32_e32 v142, 0xbfb8aa3b, v143
	v_exp_f32_e32 v139, v139
	v_exp_f32_e32 v142, v142
	v_add_f32_e32 v139, 1.0, v139
	v_add_f32_e32 v142, 1.0, v142
	v_rcp_f32_e32 v139, v139
	v_rcp_f32_e32 v142, v142
	s_nop 0
	v_cvt_pk_bf16_f32 v139, v139, v142
	v_lshl_add_u64 v[142:143], v[150:151], 0, v[140:141]
	global_store_dwordx4 v[142:143], v[136:139], off
	v_pk_add_f32 v[142:143], v[18:19], v[130:131]
	s_nop 0
	v_pk_add_f32 v[136:137], v[20:21], v[132:133]
	v_pk_add_f32 v[138:139], v[22:23], v[134:135]
	v_mul_f32_e32 v136, 0xbfb8aa3b, v136
	v_mul_f32_e32 v137, 0xbfb8aa3b, v137
	v_exp_f32_e32 v136, v136
	v_exp_f32_e32 v137, v137
	v_pk_add_f32 v[132:133], v[4:5], v[132:133]
	v_pk_add_f32 v[134:135], v[6:7], v[134:135]
	v_add_f32_e32 v136, 1.0, v136
	v_add_f32_e32 v137, 1.0, v137
	v_rcp_f32_e32 v136, v136
	v_rcp_f32_e32 v137, v137
	s_nop 0
	v_cvt_pk_bf16_f32 v136, v136, v137
	v_mul_f32_e32 v137, 0xbfb8aa3b, v138
	v_mul_f32_e32 v138, 0xbfb8aa3b, v139
	v_exp_f32_e32 v137, v137
	v_exp_f32_e32 v138, v138
	v_mul_f32_e32 v139, 0xbfb8aa3b, v145
	v_exp_f32_e32 v139, v139
	v_add_f32_e32 v137, 1.0, v137
	v_add_f32_e32 v138, 1.0, v138
	v_rcp_f32_e32 v137, v137
	v_rcp_f32_e32 v138, v138
	s_nop 0
	v_cvt_pk_bf16_f32 v137, v137, v138
	v_mul_f32_e32 v138, 0xbfb8aa3b, v144
	v_exp_f32_e32 v138, v138
	v_add_f32_e32 v139, 1.0, v139
	v_rcp_f32_e32 v139, v139
	v_add_f32_e32 v138, 1.0, v138
	v_rcp_f32_e32 v138, v138
	s_nop 0
	v_cvt_pk_bf16_f32 v138, v138, v139
	v_mul_f32_e32 v139, 0xbfb8aa3b, v142
	v_mul_f32_e32 v142, 0xbfb8aa3b, v143
	v_exp_f32_e32 v139, v139
	v_exp_f32_e32 v142, v142
	v_add_f32_e32 v139, 1.0, v139
	v_add_f32_e32 v142, 1.0, v142
	v_rcp_f32_e32 v139, v139
	v_rcp_f32_e32 v142, v142
	s_nop 0
	v_cvt_pk_bf16_f32 v139, v139, v142
	v_lshl_add_u64 v[142:143], v[152:153], 0, v[140:141]
	global_store_dwordx4 v[142:143], v[136:139], off
	s_nop 1
	v_pk_add_f32 v[136:137], v[2:3], v[130:131]
	v_pk_add_f32 v[130:131], v[0:1], v[128:129]
	v_mul_f32_e32 v128, 0xbfb8aa3b, v132
	v_mul_f32_e32 v129, 0xbfb8aa3b, v133
	v_exp_f32_e32 v128, v128
	v_exp_f32_e32 v129, v129
	v_mul_f32_e32 v132, 0xbfb8aa3b, v135
	v_mul_f32_e32 v130, 0xbfb8aa3b, v130
	v_add_f32_e32 v128, 1.0, v128
	v_add_f32_e32 v129, 1.0, v129
	v_rcp_f32_e32 v128, v128
	v_rcp_f32_e32 v129, v129
	s_nop 0
	v_cvt_pk_bf16_f32 v128, v128, v129
	v_mul_f32_e32 v129, 0xbfb8aa3b, v134
	v_mul_f32_e32 v131, 0xbfb8aa3b, v131
	v_exp_f32_e32 v129, v129
	v_exp_f32_e32 v132, v132
	v_exp_f32_e32 v130, v130
	v_exp_f32_e32 v131, v131
	v_add_f32_e32 v129, 1.0, v129
	v_add_f32_e32 v132, 1.0, v132
	v_add_f32_e32 v130, 1.0, v130
	v_add_f32_e32 v131, 1.0, v131
	v_rcp_f32_e32 v129, v129
	v_rcp_f32_e32 v132, v132
	v_rcp_f32_e32 v130, v130
	v_rcp_f32_e32 v131, v131
	s_nop 0
	v_cvt_pk_bf16_f32 v129, v129, v132
	v_cvt_pk_bf16_f32 v130, v130, v131
	v_mul_f32_e32 v131, 0xbfb8aa3b, v136
	v_mul_f32_e32 v132, 0xbfb8aa3b, v137
	v_exp_f32_e32 v131, v131
	v_exp_f32_e32 v132, v132
	v_add_f32_e32 v131, 1.0, v131
	v_add_f32_e32 v132, 1.0, v132
	v_rcp_f32_e32 v131, v131
	v_rcp_f32_e32 v132, v132
	s_nop 0
	v_cvt_pk_bf16_f32 v131, v131, v132
	v_lshl_add_u64 v[132:133], v[154:155], 0, v[140:141]
	global_store_dwordx4 v[132:133], v[128:131], off

; #define PG8_STAGE(bufoff, gbase, voff) do { _Pragma("unroll") for (int _i = 0; _i < 2; ++_i) \
;         __builtin_amdgcn_global_load_lds((const unsigned*)((const char*)(gbase) + (voff)[_i]), (PG8_LAS unsigned*)(lds + (bufoff) + ldsw + _i * 8192), 16, 0, 0); } while (0)
; #define PG8_LDA(dst, b, h) do { _Pragma("unroll") for (int m = 0; m < 4; ++m) _Pragma("unroll") for (int k = 0; k < 2; ++k) dst[m][k] = *(const PG8_LAS bf16x8*)(lds + PG8_SA(b, h) + aoff + m * 2048 + k * 1024); } while (0)
; #define PG8_LDB(dst, b, h) do { _Pragma("unroll") for (int n = 0; n < 2; ++n) _Pragma("unroll") for (int k = 0; k < 2; ++k) dst[n][k] = *(const PG8_LAS bf16x8*)(lds + PG8_SB(b, h) + boff + n * 2048 + k * 1024); } while (0)
; #define PG8_MMA(ai, bj, At, Bt) do { __builtin_amdgcn_s_setprio(1); _Pragma("unroll") for (int m = 0; m < 4; ++m) _Pragma("unroll") for (int n = 0; n < 2; ++n) _Pragma("unroll") for (int k = 0; k < 2; ++k) \
;         acc[ai][bj][m][n] = __builtin_amdgcn_mfma_f32_16x16x32_bf16(Bt[n][k], At[m][k], acc[ai][bj][m][n], 0, 0, 0); __builtin_amdgcn_s_setprio(0); } while (0)
; #define PG8_WAIT_L(n) asm volatile("s_waitcnt lgkmcnt(" #n ")" ::: "memory")
; #define PG8_BAR __builtin_amdgcn_s_barrier()
; #define PG8_SCHED __builtin_amdgcn_sched_barrier(0)
; template <class Epi, class Sched>
; __device__ __forceinline__ void gemm_phase(PG8_LAS unsigned char* lds, const Gemm g, const Sched& S, const Epi& E, int tid_in) {
;     ...
;         for (int t = 0; t < nt; t += 2) {
;             const bool last = (t == nt - 2);
;             const char* a1 = cA + (size_t)(t + 1) * kstep;
;             const char* a2 = last ? nA : cA + (size_t)(t + 2) * kstep; const char* b2 = last ? nB : cB + (size_t)(t + 2) * kstep;
;             const char* a3 = a2 + kstep; const char* b3 = b2 + kstep;
;             if (last && has_next) S.a_ready(nxt);
;             PG8_LDB(B0, 0, 0); PG8_SCHED; PG8_LDA(At, 0, 0); PG8_STAGE(PG8_SA(1, 1), a1 + hstep, voffA);
;             PG8_WAIT_L(8); PG8_BAR; PG8_WAIT_L(0); PG8_MMA(0, 0, At, B0); PG8_BAR; PG8_SCHED;
;             PG8_LDB(B1, 0, 1); PG8_STAGE(PG8_SB(0, 0), b2, voffB);
;             PG8_BAR; PG8_WAIT_L(0); PG8_MMA(0, 1, At, B1); PG8_BAR;
;             PG8_LDA(At, 0, 1); PG8_STAGE(PG8_SA(0, 0), a2, voffA);
;             PG8_BAR; PG8_WAIT_L(0); PG8_MMA(1, 0, At, B0); PG8_BAR; PG8_SCHED;
.LBB0_696:
	s_add_u32 s18, s16, 0xfffc0080
	s_addc_u32 s19, s17, -1
	s_add_i32 s43, 0, 0x10000
	v_add_u32_e32 v154, s43, v143
	ds_read_b128 v[138:141], v154
	ds_read_b128 v[146:149], v154 offset:1024
	ds_read_b128 v[150:153], v154 offset:2048
	ds_read_b128 v[154:157], v154 offset:3072
	s_cmp_eq_u32 s42, 12
	s_cselect_b32 s21, s5, s19
	s_cselect_b32 s20, s7, s18
	s_cselect_b32 s19, s9, s41
	s_cselect_b32 s18, s11, s40
	v_lshl_add_u64 v[190:191], s[16:17], 0, v[134:135]
	s_add_i32 m0, s28, 0xc000
	ds_read_b128 v[158:161], v145
	ds_read_b128 v[162:165], v145 offset:1024
	ds_read_b128 v[166:169], v145 offset:2048
	ds_read_b128 v[170:173], v145 offset:3072
	ds_read_b128 v[174:177], v145 offset:4096
	ds_read_b128 v[178:181], v145 offset:5120
	ds_read_b128 v[182:185], v145 offset:6144
	ds_read_b128 v[186:189], v145 offset:7168
	global_load_lds_dwordx4 v[190:191], off
	v_lshl_add_u64 v[190:191], s[16:17], 0, v[136:137]
	s_add_i32 m0, s28, 0xe000
	s_nop 0
	global_load_lds_dwordx4 v[190:191], off
	s_waitcnt lgkmcnt(8)
	s_barrier
	s_waitcnt lgkmcnt(0)
	s_waitcnt lgkmcnt(0)
	v_mfma_f32_16x16x32_bf16 v[124:127], v[138:141], v[158:161], v[124:127]
	v_mfma_f32_16x16x32_bf16 v[120:123], v[150:153], v[158:161], v[120:123]
	v_mfma_f32_16x16x32_bf16 v[112:115], v[138:141], v[166:169], v[112:115]
	v_mfma_f32_16x16x32_bf16 v[104:107], v[150:153], v[166:169], v[104:107]
	v_mfma_f32_16x16x32_bf16 v[96:99], v[138:141], v[174:177], v[96:99]
	v_mfma_f32_16x16x32_bf16 v[88:91], v[150:153], v[174:177], v[88:91]
	v_mfma_f32_16x16x32_bf16 v[80:83], v[138:141], v[182:185], v[80:83]
	v_mfma_f32_16x16x32_bf16 v[72:75], v[150:153], v[182:185], v[72:75]
	v_mfma_f32_16x16x32_bf16 v[124:127], v[146:149], v[162:165], v[124:127]
	v_mfma_f32_16x16x32_bf16 v[120:123], v[154:157], v[162:165], v[120:123]
	v_mfma_f32_16x16x32_bf16 v[112:115], v[146:149], v[170:173], v[112:115]
	v_mfma_f32_16x16x32_bf16 v[104:107], v[154:157], v[170:173], v[104:107]
	v_mfma_f32_16x16x32_bf16 v[96:99], v[146:149], v[178:181], v[96:99]
	v_mfma_f32_16x16x32_bf16 v[88:91], v[154:157], v[178:181], v[88:91]
	v_mfma_f32_16x16x32_bf16 v[80:83], v[146:149], v[186:189], v[80:83]
	v_mfma_f32_16x16x32_bf16 v[72:75], v[154:157], v[186:189], v[72:75]
	s_barrier
	s_add_i32 s46, 0, 0x14000
	v_add_u32_e32 v190, s46, v143
	s_add_i32 s43, s43, s27
	ds_read_b128 v[200:203], v190
	ds_read_b128 v[204:207], v190 offset:1024
	ds_read_b128 v[208:211], v190 offset:2048
	ds_read_b128 v[212:215], v190 offset:3072
	v_lshl_add_u64 v[190:191], s[18:19], 0, v[192:193]
	s_mov_b32 m0, s43
	v_lshl_add_u64 v[194:195], s[18:19], 0, v[132:133]
	global_load_lds_dwordx4 v[190:191], off
	s_add_i32 m0, s43, 0x2000
	s_nop 0
	global_load_lds_dwordx4 v[194:195], off
	s_barrier
	s_waitcnt lgkmcnt(0)
	s_waitcnt lgkmcnt(0)
	v_mfma_f32_16x16x32_bf16 v[116:119], v[200:203], v[158:161], v[116:119]
	v_mfma_f32_16x16x32_bf16 v[108:111], v[208:211], v[158:161], v[108:111]
	v_mfma_f32_16x16x32_bf16 v[100:103], v[200:203], v[166:169], v[100:103]
	v_mfma_f32_16x16x32_bf16 v[92:95], v[208:211], v[166:169], v[92:95]
	v_mfma_f32_16x16x32_bf16 v[84:87], v[200:203], v[174:177], v[84:87]
	v_mfma_f32_16x16x32_bf16 v[76:79], v[208:211], v[174:177], v[76:79]
	v_mfma_f32_16x16x32_bf16 v[68:71], v[200:203], v[182:185], v[68:71]
	v_mfma_f32_16x16x32_bf16 v[64:67], v[208:211], v[182:185], v[64:67]
	v_mfma_f32_16x16x32_bf16 v[116:119], v[204:207], v[162:165], v[116:119]
	v_mfma_f32_16x16x32_bf16 v[108:111], v[212:215], v[162:165], v[108:111]
	v_mfma_f32_16x16x32_bf16 v[100:103], v[204:207], v[170:173], v[100:103]
	v_mfma_f32_16x16x32_bf16 v[92:95], v[212:215], v[170:173], v[92:95]
	v_mfma_f32_16x16x32_bf16 v[84:87], v[204:207], v[178:181], v[84:87]
	v_mfma_f32_16x16x32_bf16 v[76:79], v[212:215], v[178:181], v[76:79]
	v_mfma_f32_16x16x32_bf16 v[68:71], v[204:207], v[186:189], v[68:71]
	v_mfma_f32_16x16x32_bf16 v[64:67], v[212:215], v[186:189], v[64:67]
	s_mov_b32 m0, s28
	v_lshl_add_u64 v[196:197], s[20:21], 0, v[128:129]
	s_barrier
	ds_read_b128 v[158:161], v145 offset:16384
	ds_read_b128 v[162:165], v145 offset:17408
	ds_read_b128 v[166:169], v145 offset:18432
	ds_read_b128 v[170:173], v145 offset:19456
	ds_read_b128 v[174:177], v145 offset:20480
	ds_read_b128 v[178:181], v145 offset:21504
	ds_read_b128 v[182:185], v145 offset:22528
	ds_read_b128 v[186:189], v145 offset:23552
	global_load_lds_dwordx4 v[196:197], off
	v_lshl_add_u64 v[216:217], s[20:21], 0, v[130:131]
	s_mov_b32 m0, s29
	s_nop 0
	global_load_lds_dwordx4 v[216:217], off
	s_barrier
	s_waitcnt lgkmcnt(0)
	s_waitcnt lgkmcnt(0)
	v_mfma_f32_16x16x32_bf16 v[60:63], v[138:141], v[158:161], v[60:63]
	v_mfma_f32_16x16x32_bf16 v[56:59], v[150:153], v[158:161], v[56:59]
	v_mfma_f32_16x16x32_bf16 v[48:51], v[138:141], v[166:169], v[48:51]
	v_mfma_f32_16x16x32_bf16 v[40:43], v[150:153], v[166:169], v[40:43]
	v_mfma_f32_16x16x32_bf16 v[32:35], v[138:141], v[174:177], v[32:35]
	v_mfma_f32_16x16x32_bf16 v[24:27], v[150:153], v[174:177], v[24:27]
	v_mfma_f32_16x16x32_bf16 v[16:19], v[138:141], v[182:185], v[16:19]
	v_mfma_f32_16x16x32_bf16 v[8:11], v[150:153], v[182:185], v[8:11]
	v_mfma_f32_16x16x32_bf16 v[60:63], v[146:149], v[162:165], v[60:63]
	v_mfma_f32_16x16x32_bf16 v[56:59], v[154:157], v[162:165], v[56:59]
	v_mfma_f32_16x16x32_bf16 v[48:51], v[146:149], v[170:173], v[48:51]
	v_mfma_f32_16x16x32_bf16 v[40:43], v[154:157], v[170:173], v[40:43]
	v_mfma_f32_16x16x32_bf16 v[32:35], v[146:149], v[178:181], v[32:35]
	v_mfma_f32_16x16x32_bf16 v[24:27], v[154:157], v[178:181], v[24:27]
	v_mfma_f32_16x16x32_bf16 v[16:19], v[146:149], v[186:189], v[16:19]
	v_mfma_f32_16x16x32_bf16 v[8:11], v[154:157], v[186:189], v[8:11]
	s_barrier
; #define PG8_STAGE(bufoff, gbase, voff) do { _Pragma("unroll") for (int _i = 0; _i < 2; ++_i) \
;         __builtin_amdgcn_global_load_lds((const unsigned*)((const char*)(gbase) + (voff)[_i]), (PG8_LAS unsigned*)(lds + (bufoff) + ldsw + _i * 8192), 16, 0, 0); } while (0)
; #define PG8_LDA(dst, b, h) do { _Pragma("unroll") for (int m = 0; m < 4; ++m) _Pragma("unroll") for (int k = 0; k < 2; ++k) dst[m][k] = *(const PG8_LAS bf16x8*)(lds + PG8_SA(b, h) + aoff + m * 2048 + k * 1024); } while (0)
; #define PG8_LDB(dst, b, h) do { _Pragma("unroll") for (int n = 0; n < 2; ++n) _Pragma("unroll") for (int k = 0; k < 2; ++k) dst[n][k] = *(const PG8_LAS bf16x8*)(lds + PG8_SB(b, h) + boff + n * 2048 + k * 1024); } while (0)
; #define PG8_MMA(ai, bj, At, Bt) do { __builtin_amdgcn_s_setprio(1); _Pragma("unroll") for (int m = 0; m < 4; ++m) _Pragma("unroll") for (int n = 0; n < 2; ++n) _Pragma("unroll") for (int k = 0; k < 2; ++k) \
;         acc[ai][bj][m][n] = __builtin_amdgcn_mfma_f32_16x16x32_bf16(Bt[n][k], At[m][k], acc[ai][bj][m][n], 0, 0, 0); __builtin_amdgcn_s_setprio(0); } while (0)
; #define PG8_WAIT_V(n) asm volatile("s_waitcnt vmcnt(" #n ")" ::: "memory")
; #define PG8_WAIT_L(n) asm volatile("s_waitcnt lgkmcnt(" #n ")" ::: "memory")
; #define PG8_BAR __builtin_amdgcn_s_barrier()
; #define PG8_SCHED __builtin_amdgcn_sched_barrier(0)
; template <class Epi, class Sched>
; __device__ __forceinline__ void gemm_phase(PG8_LAS unsigned char* lds, const Gemm g, const Sched& S, const Epi& E, int tid_in) {
;     ...
;             PG8_STAGE(PG8_SB(0, 1), b2 + hstep, voffB);
;             PG8_WAIT_V(6); PG8_BAR; PG8_MMA(1, 1, At, B1); PG8_BAR;
;             PG8_LDB(B0, 1, 0); PG8_SCHED; PG8_LDA(At, 1, 0); PG8_STAGE(PG8_SA(0, 1), a2 + hstep, voffA);
;             PG8_WAIT_L(8); PG8_BAR; PG8_WAIT_L(0); PG8_MMA(0, 0, At, B0); PG8_BAR; PG8_SCHED;
;             PG8_LDB(B1, 1, 1); PG8_STAGE(PG8_SB(1, 0), b3, voffB);
	s_add_u32 s44, s18, 0x40000
	s_addc_u32 s45, s19, 0
	s_add_i32 s43, s46, s27
	v_lshl_add_u64 v[138:139], s[44:45], 0, v[192:193]
	s_mov_b32 m0, s43
	s_nop 0
	global_load_lds_dwordx4 v[138:139], off
	v_lshl_add_u64 v[138:139], s[44:45], 0, v[132:133]
	s_add_i32 m0, s43, 0x2000
	s_nop 0
	global_load_lds_dwordx4 v[138:139], off
	s_waitcnt vmcnt(6)
	s_barrier
	v_mfma_f32_16x16x32_bf16 v[52:55], v[200:203], v[158:161], v[52:55]
	v_mfma_f32_16x16x32_bf16 v[44:47], v[208:211], v[158:161], v[44:47]
	v_mfma_f32_16x16x32_bf16 v[36:39], v[200:203], v[166:169], v[36:39]
	v_mfma_f32_16x16x32_bf16 v[28:31], v[208:211], v[166:169], v[28:31]
	v_mfma_f32_16x16x32_bf16 v[20:23], v[200:203], v[174:177], v[20:23]
	v_mfma_f32_16x16x32_bf16 v[12:15], v[208:211], v[174:177], v[12:15]
	v_mfma_f32_16x16x32_bf16 v[4:7], v[200:203], v[182:185], v[4:7]
	v_mfma_f32_16x16x32_bf16 v[0:3], v[208:211], v[182:185], v[0:3]
	v_mfma_f32_16x16x32_bf16 v[52:55], v[204:207], v[162:165], v[52:55]
	v_mfma_f32_16x16x32_bf16 v[44:47], v[212:215], v[162:165], v[44:47]
	v_mfma_f32_16x16x32_bf16 v[36:39], v[204:207], v[170:173], v[36:39]
	v_mfma_f32_16x16x32_bf16 v[28:31], v[212:215], v[170:173], v[28:31]
	v_mfma_f32_16x16x32_bf16 v[20:23], v[204:207], v[178:181], v[20:23]
	v_mfma_f32_16x16x32_bf16 v[12:15], v[212:215], v[178:181], v[12:15]
	v_mfma_f32_16x16x32_bf16 v[4:7], v[204:207], v[186:189], v[4:7]
	v_mfma_f32_16x16x32_bf16 v[0:3], v[212:215], v[186:189], v[0:3]
	s_add_i32 s43, 0, 0x18000
	v_add_u32_e32 v154, s43, v143
	s_barrier
	ds_read_b128 v[138:141], v154
	ds_read_b128 v[146:149], v154 offset:1024
	ds_read_b128 v[150:153], v154 offset:2048
	ds_read_b128 v[154:157], v154 offset:3072
	s_add_u32 s20, s20, 0x40000
	s_addc_u32 s21, s21, 0
	s_mov_b32 m0, s30
	v_lshl_add_u64 v[200:201], s[20:21], 0, v[128:129]
	ds_read_b128 v[158:161], v145 offset:32768
	ds_read_b128 v[162:165], v145 offset:33792
	ds_read_b128 v[166:169], v145 offset:34816
	ds_read_b128 v[170:173], v145 offset:35840
	ds_read_b128 v[174:177], v145 offset:36864
	ds_read_b128 v[178:181], v145 offset:37888
	ds_read_b128 v[182:185], v145 offset:38912
	ds_read_b128 v[186:189], v145 offset:39936
	global_load_lds_dwordx4 v[200:201], off
	v_lshl_add_u64 v[200:201], s[20:21], 0, v[130:131]
	s_mov_b32 m0, s31
	s_nop 0
	global_load_lds_dwordx4 v[200:201], off
	s_waitcnt lgkmcnt(8)
	s_barrier
	s_waitcnt lgkmcnt(0)
	s_waitcnt lgkmcnt(0)
	v_mfma_f32_16x16x32_bf16 v[124:127], v[138:141], v[158:161], v[124:127]
	v_mfma_f32_16x16x32_bf16 v[120:123], v[150:153], v[158:161], v[120:123]
	v_mfma_f32_16x16x32_bf16 v[112:115], v[138:141], v[166:169], v[112:115]
	v_mfma_f32_16x16x32_bf16 v[104:107], v[150:153], v[166:169], v[104:107]
	v_mfma_f32_16x16x32_bf16 v[96:99], v[138:141], v[174:177], v[96:99]
	v_mfma_f32_16x16x32_bf16 v[88:91], v[150:153], v[174:177], v[88:91]
	v_mfma_f32_16x16x32_bf16 v[80:83], v[138:141], v[182:185], v[80:83]
	v_mfma_f32_16x16x32_bf16 v[72:75], v[150:153], v[182:185], v[72:75]
	v_mfma_f32_16x16x32_bf16 v[124:127], v[146:149], v[162:165], v[124:127]
	v_mfma_f32_16x16x32_bf16 v[120:123], v[154:157], v[162:165], v[120:123]
	v_mfma_f32_16x16x32_bf16 v[112:115], v[146:149], v[170:173], v[112:115]
	v_mfma_f32_16x16x32_bf16 v[104:107], v[154:157], v[170:173], v[104:107]
	v_mfma_f32_16x16x32_bf16 v[96:99], v[146:149], v[178:181], v[96:99]
	v_mfma_f32_16x16x32_bf16 v[88:91], v[154:157], v[178:181], v[88:91]
	v_mfma_f32_16x16x32_bf16 v[80:83], v[146:149], v[186:189], v[80:83]
	v_mfma_f32_16x16x32_bf16 v[72:75], v[154:157], v[186:189], v[72:75]
	s_barrier
	s_add_i32 s20, 0, 0x1c000
	s_add_i32 s21, s43, s27
	v_add_u32_e32 v199, s20, v143
	v_lshl_add_u64 v[190:191], v[190:191], 0, s[74:75]
	s_mov_b32 m0, s21
	ds_read_b128 v[200:203], v199
	ds_read_b128 v[204:207], v199 offset:1024
	ds_read_b128 v[208:211], v199 offset:2048
	ds_read_b128 v[212:215], v199 offset:3072
	global_load_lds_dwordx4 v[190:191], off
	v_lshl_add_u64 v[190:191], v[194:195], 0, s[74:75]
	s_add_i32 m0, s21, 0x2000
	s_nop 0
	global_load_lds_dwordx4 v[190:191], off
	s_barrier
; __device__ __forceinline__ unsigned cvt_pk_bf16(float lo, float hi) { unsigned r; asm volatile("s_nop 0\n\tv_cvt_pk_bf16_f32 %0, %1, %2\n\ts_nop 1" : "=v"(r) : "v"(lo), "v"(hi)); return r; }
; #define PG8_STAGE(bufoff, gbase, voff) do { _Pragma("unroll") for (int _i = 0; _i < 2; ++_i) \
;         __builtin_amdgcn_global_load_lds((const unsigned*)((const char*)(gbase) + (voff)[_i]), (PG8_LAS unsigned*)(lds + (bufoff) + ldsw + _i * 8192), 16, 0, 0); } while (0)
; #define PG8_LDA(dst, b, h) do { _Pragma("unroll") for (int m = 0; m < 4; ++m) _Pragma("unroll") for (int k = 0; k < 2; ++k) dst[m][k] = *(const PG8_LAS bf16x8*)(lds + PG8_SA(b, h) + aoff + m * 2048 + k * 1024); } while (0)
; #define PG8_WAIT_V(n) asm volatile("s_waitcnt vmcnt(" #n ")" ::: "memory")
; #define PG8_WAIT_L(n) asm volatile("s_waitcnt lgkmcnt(" #n ")" ::: "memory")
; #define PG8_BAR __builtin_amdgcn_s_barrier()
; #define PG8_SCHED __builtin_amdgcn_sched_barrier(0)
; template <class Epi, class Sched>
; __device__ __forceinline__ void gemm_phase(PG8_LAS unsigned char* lds, const Gemm g, const Sched& S, const Epi& E, int tid_in) {
;     ...
;             PG8_BAR; PG8_WAIT_L(0); PG8_MMA(0, 1, At, B1); PG8_BAR;
;             PG8_LDA(At, 1, 1); PG8_STAGE(PG8_SA(1, 0), a3, voffA);
;             PG8_BAR; PG8_WAIT_L(0); PG8_MMA(1, 0, At, B0); PG8_BAR; PG8_SCHED;
;             PG8_STAGE(PG8_SB(1, 1), b3 + hstep, voffB);
;             PG8_WAIT_V(6); PG8_BAR; PG8_MMA(1, 1, At, B1); PG8_BAR;
;         }
;     __device__ __forceinline__ void operator()(f32x4 (&acc)[2][2][4][2], const Unit& u, int wr, int wc, int fr, int fq) const {
;         const int row0 = u.pm * 256 + wr * 64 + fr, col0 = u.pn * 256 + wc * 32 + 8 * fq;
; #pragma unroll
;         for (int ai = 0; ai < 2; ++ai)
; #pragma unroll
;             for (int m = 0; m < 4; ++m) { bf16_t* rowp = O + (size_t)(row0 + ai * 128 + m * 16) * ldc + col0;
; #pragma unroll
;                 for (int bj = 0; bj < 2; ++bj) { if (u.pn * 256 + bj * 128 + wc * 32 >= 5184) continue;
;                     const f32x4 v0 = acc[ai][bj][m][0], v1 = acc[ai][bj][m][1];
;                     u32x4 w; w.x = cvt_pk_bf16(v0[0], v0[1]); w.y = cvt_pk_bf16(v0[2], v0[3]); w.z = cvt_pk_bf16(v1[0], v1[1]); w.w = cvt_pk_bf16(v1[2], v1[3]);
;                     *(u32x4*)(rowp + bj * 128) = w; } }
	s_waitcnt lgkmcnt(0)
	s_waitcnt lgkmcnt(0)
	v_mfma_f32_16x16x32_bf16 v[116:119], v[200:203], v[158:161], v[116:119]
	v_mfma_f32_16x16x32_bf16 v[108:111], v[208:211], v[158:161], v[108:111]
	v_mfma_f32_16x16x32_bf16 v[100:103], v[200:203], v[166:169], v[100:103]
	v_mfma_f32_16x16x32_bf16 v[92:95], v[208:211], v[166:169], v[92:95]
	v_mfma_f32_16x16x32_bf16 v[84:87], v[200:203], v[174:177], v[84:87]
	v_mfma_f32_16x16x32_bf16 v[76:79], v[208:211], v[174:177], v[76:79]
	v_mfma_f32_16x16x32_bf16 v[68:71], v[200:203], v[182:185], v[68:71]
	v_mfma_f32_16x16x32_bf16 v[64:67], v[208:211], v[182:185], v[64:67]
	v_mfma_f32_16x16x32_bf16 v[116:119], v[204:207], v[162:165], v[116:119]
	v_mfma_f32_16x16x32_bf16 v[108:111], v[212:215], v[162:165], v[108:111]
	v_mfma_f32_16x16x32_bf16 v[100:103], v[204:207], v[170:173], v[100:103]
	v_mfma_f32_16x16x32_bf16 v[92:95], v[212:215], v[170:173], v[92:95]
	v_mfma_f32_16x16x32_bf16 v[84:87], v[204:207], v[178:181], v[84:87]
	v_mfma_f32_16x16x32_bf16 v[76:79], v[212:215], v[178:181], v[76:79]
	v_mfma_f32_16x16x32_bf16 v[68:71], v[204:207], v[186:189], v[68:71]
	v_mfma_f32_16x16x32_bf16 v[64:67], v[212:215], v[186:189], v[64:67]
	s_mov_b32 m0, s36
	v_lshl_add_u64 v[190:191], v[196:197], 0, s[74:75]
	s_barrier
	ds_read_b128 v[158:161], v145 offset:49152
	ds_read_b128 v[162:165], v145 offset:50176
	ds_read_b128 v[166:169], v145 offset:51200
	ds_read_b128 v[170:173], v145 offset:52224
	ds_read_b128 v[174:177], v145 offset:53248
	ds_read_b128 v[178:181], v145 offset:54272
	ds_read_b128 v[182:185], v145 offset:55296
	ds_read_b128 v[186:189], v145 offset:56320
	global_load_lds_dwordx4 v[190:191], off
	v_lshl_add_u64 v[190:191], v[216:217], 0, s[74:75]
	s_mov_b32 m0, s37
	s_nop 0
	global_load_lds_dwordx4 v[190:191], off
	s_barrier
	s_waitcnt lgkmcnt(0)
	s_waitcnt lgkmcnt(0)
	v_mfma_f32_16x16x32_bf16 v[60:63], v[138:141], v[158:161], v[60:63]
	v_mfma_f32_16x16x32_bf16 v[56:59], v[150:153], v[158:161], v[56:59]
	v_mfma_f32_16x16x32_bf16 v[48:51], v[138:141], v[166:169], v[48:51]
	v_mfma_f32_16x16x32_bf16 v[40:43], v[150:153], v[166:169], v[40:43]
	v_mfma_f32_16x16x32_bf16 v[32:35], v[138:141], v[174:177], v[32:35]
	v_mfma_f32_16x16x32_bf16 v[24:27], v[150:153], v[174:177], v[24:27]
	v_mfma_f32_16x16x32_bf16 v[16:19], v[138:141], v[182:185], v[16:19]
	v_mfma_f32_16x16x32_bf16 v[8:11], v[150:153], v[182:185], v[8:11]
	v_mfma_f32_16x16x32_bf16 v[60:63], v[146:149], v[162:165], v[60:63]
	v_mfma_f32_16x16x32_bf16 v[56:59], v[154:157], v[162:165], v[56:59]
	v_mfma_f32_16x16x32_bf16 v[48:51], v[146:149], v[170:173], v[48:51]
	v_mfma_f32_16x16x32_bf16 v[40:43], v[154:157], v[170:173], v[40:43]
	v_mfma_f32_16x16x32_bf16 v[32:35], v[146:149], v[178:181], v[32:35]
	v_mfma_f32_16x16x32_bf16 v[24:27], v[154:157], v[178:181], v[24:27]
	v_mfma_f32_16x16x32_bf16 v[16:19], v[146:149], v[186:189], v[16:19]
	v_mfma_f32_16x16x32_bf16 v[8:11], v[154:157], v[186:189], v[8:11]
	s_barrier
	s_add_u32 s18, s18, 0x40080
	s_addc_u32 s19, s19, 0
	s_add_i32 s20, s20, s27
	v_lshl_add_u64 v[138:139], s[18:19], 0, v[192:193]
	s_mov_b32 m0, s20
	s_nop 0
	global_load_lds_dwordx4 v[138:139], off
	v_lshl_add_u64 v[138:139], s[18:19], 0, v[132:133]
	s_add_i32 m0, s20, 0x2000
	s_nop 0
	global_load_lds_dwordx4 v[138:139], off
	s_waitcnt vmcnt(6)
	s_barrier
	v_mfma_f32_16x16x32_bf16 v[52:55], v[200:203], v[158:161], v[52:55]
	v_mfma_f32_16x16x32_bf16 v[44:47], v[208:211], v[158:161], v[44:47]
	v_mfma_f32_16x16x32_bf16 v[36:39], v[200:203], v[166:169], v[36:39]
	v_mfma_f32_16x16x32_bf16 v[28:31], v[208:211], v[166:169], v[28:31]
	v_mfma_f32_16x16x32_bf16 v[20:23], v[200:203], v[174:177], v[20:23]
	v_mfma_f32_16x16x32_bf16 v[12:15], v[208:211], v[174:177], v[12:15]
	v_mfma_f32_16x16x32_bf16 v[4:7], v[200:203], v[182:185], v[4:7]
	v_mfma_f32_16x16x32_bf16 v[0:3], v[208:211], v[182:185], v[0:3]
	v_mfma_f32_16x16x32_bf16 v[52:55], v[204:207], v[162:165], v[52:55]
	v_mfma_f32_16x16x32_bf16 v[44:47], v[212:215], v[162:165], v[44:47]
	v_mfma_f32_16x16x32_bf16 v[36:39], v[204:207], v[170:173], v[36:39]
	v_mfma_f32_16x16x32_bf16 v[28:31], v[212:215], v[170:173], v[28:31]
	v_mfma_f32_16x16x32_bf16 v[20:23], v[204:207], v[178:181], v[20:23]
	v_mfma_f32_16x16x32_bf16 v[12:15], v[212:215], v[178:181], v[12:15]
	v_mfma_f32_16x16x32_bf16 v[4:7], v[204:207], v[186:189], v[4:7]
	v_mfma_f32_16x16x32_bf16 v[0:3], v[212:215], v[186:189], v[0:3]
	s_add_i32 s42, s42, 2
	s_add_u32 s16, s16, 0x100
	s_addc_u32 s17, s17, 0
	s_add_u32 s40, s40, 0x100
	s_addc_u32 s41, s41, 0
	s_cmp_gt_u32 s42, 13
	s_barrier
	s_cbranch_scc0 .LBB0_696
	s_lshl_b32 s4, s4, 8
	v_lshl_add_u32 v146, s6, 8, v142
	v_or_b32_e32 v138, s4, v144
	s_or_b32 s4, s4, s33
	v_mov_b64_e32 v[140:141], s[0:1]
	v_ashrrev_i32_e32 v139, 31, v138
	v_mad_i64_i32 v[140:141], s[6:7], v146, s78, v[140:141]
	s_cmpk_lt_i32 s4, 0x1440
	s_cselect_b64 s[6:7], -1, 0
	s_cmpk_gt_i32 s4, 0x143f
	v_lshl_add_u64 v[140:141], v[138:139], 1, v[140:141]
	s_cbranch_scc1 .LBB0_699
	v_cvt_pk_bf16_f32 v124, v124, v125
	v_cvt_pk_bf16_f32 v125, v126, v127
	v_cvt_pk_bf16_f32 v126, v120, v121
	v_cvt_pk_bf16_f32 v127, v122, v123
	s_nop 1
	global_store_dwordx4 v[140:141], v[124:127], off
